# hybrid load-segment order: DMA loads first only in the segments that issue two of them; the six-load segments issue their 8 fragment reads first
# speedup vs baseline: 1.0033x; 1.0033x over previous
; #define PG8_STAGE(bufoff, gbase, voff) do { _Pragma("unroll") for (int _i = 0; _i < 2; ++_i) \
;         __builtin_amdgcn_global_load_lds((const unsigned*)((const char*)(gbase) + (voff)[_i]), (LAS unsigned*)(lds + (bufoff) + ldsw + _i * 8192), 16, 0, 0); } while (0)
; #define PG8_LDA(dst, b, h) do { _Pragma("unroll") for (int m = 0; m < 4; ++m) _Pragma("unroll") for (int k = 0; k < 2; ++k) dst[m][k] = *(const LAS bf16x8*)(lds + PG8_SA(b, h) + aoff + m * 2048 + k * 1024); } while (0)
; #define PG8_LDB(dst, b, h) do { _Pragma("unroll") for (int n = 0; n < 2; ++n) _Pragma("unroll") for (int k = 0; k < 2; ++k) dst[n][k] = *(const LAS bf16x8*)(lds + PG8_SB(b, h) + boff + n * 2048 + k * 1024); } while (0)
; #define PG8_MMA(ai, bj, At, Bt) do { __builtin_amdgcn_s_setprio(1); _Pragma("unroll") for (int m = 0; m < 4; ++m) _Pragma("unroll") for (int n = 0; n < 2; ++n) _Pragma("unroll") for (int k = 0; k < 2; ++k) \
;         acc[ai][bj][m][n] = __builtin_amdgcn_mfma_f32_16x16x32_bf16(Bt[n][k], At[m][k], acc[ai][bj][m][n], 0, 0, 0); __builtin_amdgcn_s_setprio(0); } while (0)
; template <class Epi, class Sched>
; __device__ __forceinline__ void gemm_phase(LAS unsigned char* lds, const Gemm g, const Sched& S, const Epi& E) {
;     ...
;         const bool has_next = S.next(ui + 1, nxt);
;         const char* nA = has_next ? (const char*)g.A + (size_t)nxt.pm * tstepA + (size_t)nxt.pn * g.a_pn_off * 2 : cA; const char* nB = has_next ? (const char*)g.Bt + (size_t)nxt.pn * tstepB : cB;
;         for (int t = 0; t < nt; t += 2) {
;             const bool last = (t == nt - 2);
;             const char* a1 = cA + (size_t)(t + 1) * kstep;
;             const char* a2 = last ? nA : cA + (size_t)(t + 2) * kstep; const char* b2 = last ? nB : cB + (size_t)(t + 2) * kstep;
;             const char* a3 = a2 + kstep; const char* b3 = b2 + kstep;
;             PG8_LDB(B0, 0, 0); PG8_LDB(B1, 0, 1); PG8_SCHED; PG8_LDA(At, 0, 0); PG8_STAGE(PG8_SA(1, 1), a1 + hstepA, voffA);
;             PG8_WAIT_V(8); PG8_WAIT_L(0); PG8_BAR; PG8_MMA(0, 0, At, B0); PG8_MMA(0, 1, At, B1); PG8_BAR; PG8_SCHED;
;             PG8_LDA(At, 0, 1); PG8_STAGE(PG8_SB(0, 0), b2, voffB); PG8_STAGE(PG8_SB(0, 1), b2 + hstepB, voffB); PG8_STAGE(PG8_SA(0, 0), a2, voffA);
;             PG8_WAIT_V(8); PG8_WAIT_L(0); PG8_BAR; PG8_MMA(1, 0, At, B0); PG8_MMA(1, 1, At, B1); PG8_BAR; PG8_SCHED;
.LBB0_231:
	s_ashr_i32 s83, s82, 31
	s_lshl_b64 s[36:37], s[82:83], 19
	s_add_u32 s84, s4, s36
	s_addc_u32 s85, s5, s37
	s_and_b64 s[36:37], s[70:71], exec
	s_cselect_b32 s43, s85, s19
	s_cselect_b32 s48, s84, s18
	s_ashr_i32 s81, s80, 31
	s_lshl_b64 s[36:37], s[80:81], 19
	v_readlane_b32 s12, v248, 5
	s_add_u32 s36, s12, s36
	v_readlane_b32 s12, v248, 6
	s_addc_u32 s37, s12, s37
	s_and_b64 s[86:87], s[70:71], exec
	s_cselect_b32 s49, s37, s21
	s_cselect_b32 s53, s36, s20
	s_add_u32 s18, s18, 0x40080
	s_addc_u32 s19, s19, 0
	s_add_u32 s54, s20, 0x100
	s_addc_u32 s81, s21, 0
	s_mov_b32 s83, -2
	s_add_u32 s20, s18, 0xfffc0080
	s_addc_u32 s21, s19, -1
	s_add_i32 s88, 0, 0x10000
	s_cmp_eq_u32 s83, 12
	s_cselect_b32 s21, s43, s21
	s_cselect_b32 s20, s48, s20
	s_cselect_b32 s87, s49, s81
	s_cselect_b32 s86, s53, s54
	s_add_i32 s90, 0, 0x14000
	s_add_u32 s100, s20, 0x80
	s_addc_u32 s101, s21, 0
	s_add_i32 m0, s9, 0xc000
	s_nop 0
	global_load_lds_dwordx4 v170, s[18:19]
	s_add_i32 m0, s9, 0xe000
	s_nop 0
	global_load_lds_dwordx4 v190, s[18:19]
	ds_read_b128 v[130:133], v246
	ds_read_b128 v[134:137], v246 offset:1024
	ds_read_b128 v[138:141], v246 offset:2048
	ds_read_b128 v[142:145], v246 offset:3072
	ds_read_b128 v[146:149], v246 offset:16384
	ds_read_b128 v[150:153], v246 offset:17408
	ds_read_b128 v[154:157], v246 offset:18432
	ds_read_b128 v[158:161], v246 offset:19456
	ds_read_b128 v[162:165], v222
	ds_read_b128 v[166:169], v222 offset:1024
	ds_read_b128 v[194:197], v222 offset:2048
	ds_read_b128 v[198:201], v222 offset:3072
	ds_read_b128 v[202:205], v222 offset:4096
	ds_read_b128 v[224:227], v222 offset:5120
	ds_read_b128 v[228:231], v222 offset:6144
	ds_read_b128 v[232:235], v222 offset:7168
	s_waitcnt vmcnt(8)
	s_waitcnt lgkmcnt(0)
	s_barrier
	s_waitcnt lgkmcnt(0)
	v_mfma_f32_16x16x32_bf16 v[126:129], v[130:133], v[162:165], 0
	v_mfma_f32_16x16x32_bf16 v[118:121], v[138:141], v[162:165], 0
	v_mfma_f32_16x16x32_bf16 v[110:113], v[130:133], v[194:197], 0
	v_mfma_f32_16x16x32_bf16 v[102:105], v[138:141], v[194:197], 0
	v_mfma_f32_16x16x32_bf16 v[94:97], v[130:133], v[202:205], 0
	v_mfma_f32_16x16x32_bf16 v[86:89], v[138:141], v[202:205], 0
	v_mfma_f32_16x16x32_bf16 v[78:81], v[130:133], v[228:231], 0
	v_mfma_f32_16x16x32_bf16 v[70:73], v[138:141], v[228:231], 0
	v_mfma_f32_16x16x32_bf16 v[126:129], v[134:137], v[166:169], v[126:129]
	v_mfma_f32_16x16x32_bf16 v[118:121], v[142:145], v[166:169], v[118:121]
	v_mfma_f32_16x16x32_bf16 v[110:113], v[134:137], v[198:201], v[110:113]
	v_mfma_f32_16x16x32_bf16 v[102:105], v[142:145], v[198:201], v[102:105]
	v_mfma_f32_16x16x32_bf16 v[94:97], v[134:137], v[224:227], v[94:97]
	v_mfma_f32_16x16x32_bf16 v[86:89], v[142:145], v[224:227], v[86:89]
	v_mfma_f32_16x16x32_bf16 v[78:81], v[134:137], v[232:235], v[78:81]
	v_mfma_f32_16x16x32_bf16 v[70:73], v[142:145], v[232:235], v[70:73]
	v_mfma_f32_16x16x32_bf16 v[122:125], v[146:149], v[162:165], 0
	v_mfma_f32_16x16x32_bf16 v[114:117], v[154:157], v[162:165], 0
	v_mfma_f32_16x16x32_bf16 v[106:109], v[146:149], v[194:197], 0
	v_mfma_f32_16x16x32_bf16 v[98:101], v[154:157], v[194:197], 0
	v_mfma_f32_16x16x32_bf16 v[90:93], v[146:149], v[202:205], 0
	v_mfma_f32_16x16x32_bf16 v[82:85], v[154:157], v[202:205], 0
	v_mfma_f32_16x16x32_bf16 v[74:77], v[146:149], v[228:231], 0
	v_mfma_f32_16x16x32_bf16 v[66:69], v[154:157], v[228:231], 0
	v_mfma_f32_16x16x32_bf16 v[122:125], v[150:153], v[166:169], v[122:125]
	v_mfma_f32_16x16x32_bf16 v[114:117], v[158:161], v[166:169], v[114:117]
	v_mfma_f32_16x16x32_bf16 v[106:109], v[150:153], v[198:201], v[106:109]
	v_mfma_f32_16x16x32_bf16 v[98:101], v[158:161], v[198:201], v[98:101]
	v_mfma_f32_16x16x32_bf16 v[90:93], v[150:153], v[224:227], v[90:93]
	v_mfma_f32_16x16x32_bf16 v[82:85], v[158:161], v[224:227], v[82:85]
	v_mfma_f32_16x16x32_bf16 v[74:77], v[150:153], v[232:235], v[74:77]
	v_mfma_f32_16x16x32_bf16 v[66:69], v[158:161], v[232:235], v[66:69]
	s_barrier
	s_add_i32 s88, s88, s8
	s_mov_b32 m0, s88
	ds_read_b128 v[162:165], v222 offset:16384
	ds_read_b128 v[166:169], v222 offset:17408
	ds_read_b128 v[194:197], v222 offset:18432
	ds_read_b128 v[198:201], v222 offset:19456
	ds_read_b128 v[202:205], v222 offset:20480
	ds_read_b128 v[224:227], v222 offset:21504
	ds_read_b128 v[228:231], v222 offset:22528
	ds_read_b128 v[232:235], v222 offset:23552
	global_load_lds_dwordx4 v172, s[86:87]
	s_add_i32 m0, s88, 0x2000
	s_add_u32 s88, s86, 0x40000
	s_addc_u32 s89, s87, 0
	s_add_i32 s90, s90, s8
	global_load_lds_dwordx4 v192, s[86:87]
	s_mov_b32 m0, s90
	s_nop 0
	global_load_lds_dwordx4 v172, s[88:89]
	s_add_i32 m0, s90, 0x2000
	s_nop 0
	global_load_lds_dwordx4 v192, s[88:89]
	s_mov_b32 m0, s9
	s_nop 0
	global_load_lds_dwordx4 v170, s[20:21]
	s_mov_b32 m0, s28
	s_nop 0
	global_load_lds_dwordx4 v190, s[20:21]
	s_waitcnt vmcnt(8)
	s_waitcnt lgkmcnt(0)
	s_barrier
; #define PG8_STAGE(bufoff, gbase, voff) do { _Pragma("unroll") for (int _i = 0; _i < 2; ++_i) \
;         __builtin_amdgcn_global_load_lds((const unsigned*)((const char*)(gbase) + (voff)[_i]), (LAS unsigned*)(lds + (bufoff) + ldsw + _i * 8192), 16, 0, 0); } while (0)
; #define PG8_LDA(dst, b, h) do { _Pragma("unroll") for (int m = 0; m < 4; ++m) _Pragma("unroll") for (int k = 0; k < 2; ++k) dst[m][k] = *(const LAS bf16x8*)(lds + PG8_SA(b, h) + aoff + m * 2048 + k * 1024); } while (0)
; #define PG8_LDB(dst, b, h) do { _Pragma("unroll") for (int n = 0; n < 2; ++n) _Pragma("unroll") for (int k = 0; k < 2; ++k) dst[n][k] = *(const LAS bf16x8*)(lds + PG8_SB(b, h) + boff + n * 2048 + k * 1024); } while (0)
; #define PG8_MMA(ai, bj, At, Bt) do { __builtin_amdgcn_s_setprio(1); _Pragma("unroll") for (int m = 0; m < 4; ++m) _Pragma("unroll") for (int n = 0; n < 2; ++n) _Pragma("unroll") for (int k = 0; k < 2; ++k) \
;         acc[ai][bj][m][n] = __builtin_amdgcn_mfma_f32_16x16x32_bf16(Bt[n][k], At[m][k], acc[ai][bj][m][n], 0, 0, 0); __builtin_amdgcn_s_setprio(0); } while (0)
; #define PG8_WAIT_V(n) asm volatile("s_waitcnt vmcnt(" #n ")" ::: "memory")
; #define PG8_WAIT_L(n) asm volatile("s_waitcnt lgkmcnt(" #n ")" ::: "memory")
; #define PG8_BAR __builtin_amdgcn_s_barrier()
; #define PG8_SCHED __builtin_amdgcn_sched_barrier(0)
; template <class Epi, class Sched>
; __device__ __forceinline__ void gemm_phase(LAS unsigned char* lds, const Gemm g, const Sched& S, const Epi& E) {
;     ...
;             PG8_WAIT_V(8); PG8_WAIT_L(0); PG8_BAR; PG8_MMA(1, 0, At, B0); PG8_MMA(1, 1, At, B1); PG8_BAR; PG8_SCHED;
;             PG8_LDB(B0, 1, 0); PG8_LDB(B1, 1, 1); PG8_SCHED; PG8_LDA(At, 1, 0); PG8_STAGE(PG8_SA(0, 1), a2 + hstepA, voffA);
;             PG8_WAIT_V(8); PG8_WAIT_L(0); PG8_BAR; PG8_MMA(0, 0, At, B0); PG8_MMA(0, 1, At, B1); PG8_BAR; PG8_SCHED;
	s_waitcnt lgkmcnt(0)
	v_mfma_f32_16x16x32_bf16 v[62:65], v[130:133], v[162:165], 0
	v_mfma_f32_16x16x32_bf16 v[54:57], v[138:141], v[162:165], 0
	v_mfma_f32_16x16x32_bf16 v[46:49], v[130:133], v[194:197], 0
	v_mfma_f32_16x16x32_bf16 v[38:41], v[138:141], v[194:197], 0
	v_mfma_f32_16x16x32_bf16 v[30:33], v[130:133], v[202:205], 0
	v_mfma_f32_16x16x32_bf16 v[22:25], v[138:141], v[202:205], 0
	v_mfma_f32_16x16x32_bf16 v[14:17], v[130:133], v[228:231], 0
	v_mfma_f32_16x16x32_bf16 v[6:9], v[138:141], v[228:231], 0
	v_mfma_f32_16x16x32_bf16 v[62:65], v[134:137], v[166:169], v[62:65]
	v_mfma_f32_16x16x32_bf16 v[54:57], v[142:145], v[166:169], v[54:57]
	v_mfma_f32_16x16x32_bf16 v[46:49], v[134:137], v[198:201], v[46:49]
	v_mfma_f32_16x16x32_bf16 v[38:41], v[142:145], v[198:201], v[38:41]
	v_mfma_f32_16x16x32_bf16 v[30:33], v[134:137], v[224:227], v[30:33]
	v_mfma_f32_16x16x32_bf16 v[22:25], v[142:145], v[224:227], v[22:25]
	v_mfma_f32_16x16x32_bf16 v[14:17], v[134:137], v[232:235], v[14:17]
	v_mfma_f32_16x16x32_bf16 v[6:9], v[142:145], v[232:235], v[6:9]
	v_mfma_f32_16x16x32_bf16 v[58:61], v[146:149], v[162:165], 0
	v_mfma_f32_16x16x32_bf16 v[50:53], v[154:157], v[162:165], 0
	v_mfma_f32_16x16x32_bf16 v[42:45], v[146:149], v[194:197], 0
	v_mfma_f32_16x16x32_bf16 v[34:37], v[154:157], v[194:197], 0
	v_mfma_f32_16x16x32_bf16 v[26:29], v[146:149], v[202:205], 0
	v_mfma_f32_16x16x32_bf16 v[18:21], v[154:157], v[202:205], 0
	v_mfma_f32_16x16x32_bf16 v[10:13], v[146:149], v[228:231], 0
	v_mfma_f32_16x16x32_bf16 v[2:5], v[154:157], v[228:231], 0
	v_mfma_f32_16x16x32_bf16 v[58:61], v[150:153], v[166:169], v[58:61]
	v_mfma_f32_16x16x32_bf16 v[50:53], v[158:161], v[166:169], v[50:53]
	v_mfma_f32_16x16x32_bf16 v[42:45], v[150:153], v[198:201], v[42:45]
	v_mfma_f32_16x16x32_bf16 v[34:37], v[158:161], v[198:201], v[34:37]
	v_mfma_f32_16x16x32_bf16 v[26:29], v[150:153], v[224:227], v[26:29]
	v_mfma_f32_16x16x32_bf16 v[18:21], v[158:161], v[224:227], v[18:21]
	v_mfma_f32_16x16x32_bf16 v[10:13], v[150:153], v[232:235], v[10:13]
	v_mfma_f32_16x16x32_bf16 v[2:5], v[158:161], v[232:235], v[2:5]
	s_barrier
	s_add_i32 s88, 0, 0x18000
	s_add_i32 s89, 0, 0x1c000
	s_add_u32 s20, s20, 0x40000
	s_addc_u32 s21, s21, 0
	s_mov_b32 m0, s29
	s_nop 0
	global_load_lds_dwordx4 v170, s[20:21]
	s_mov_b32 m0, s30
	s_nop 0
	global_load_lds_dwordx4 v190, s[20:21]
	ds_read_b128 v[130:133], v246 offset:32768
	ds_read_b128 v[134:137], v246 offset:33792
	ds_read_b128 v[138:141], v246 offset:34816
	ds_read_b128 v[142:145], v246 offset:35840
	ds_read_b128 v[146:149], v246 offset:49152
	ds_read_b128 v[150:153], v246 offset:50176
	ds_read_b128 v[154:157], v246 offset:51200
	ds_read_b128 v[158:161], v246 offset:52224
	ds_read_b128 v[162:165], v222 offset:32768
	ds_read_b128 v[166:169], v222 offset:33792
	ds_read_b128 v[194:197], v222 offset:34816
	ds_read_b128 v[198:201], v222 offset:35840
	ds_read_b128 v[202:205], v222 offset:36864
	ds_read_b128 v[224:227], v222 offset:37888
	ds_read_b128 v[228:231], v222 offset:38912
	ds_read_b128 v[232:235], v222 offset:39936
	s_waitcnt vmcnt(8)
	s_waitcnt lgkmcnt(0)
	s_barrier
	s_waitcnt lgkmcnt(0)
	v_mfma_f32_16x16x32_bf16 v[126:129], v[130:133], v[162:165], v[126:129]
	v_mfma_f32_16x16x32_bf16 v[118:121], v[138:141], v[162:165], v[118:121]
	v_mfma_f32_16x16x32_bf16 v[110:113], v[130:133], v[194:197], v[110:113]
	v_mfma_f32_16x16x32_bf16 v[102:105], v[138:141], v[194:197], v[102:105]
	v_mfma_f32_16x16x32_bf16 v[94:97], v[130:133], v[202:205], v[94:97]
	v_mfma_f32_16x16x32_bf16 v[86:89], v[138:141], v[202:205], v[86:89]
	v_mfma_f32_16x16x32_bf16 v[78:81], v[130:133], v[228:231], v[78:81]
	v_mfma_f32_16x16x32_bf16 v[70:73], v[138:141], v[228:231], v[70:73]
	v_mfma_f32_16x16x32_bf16 v[126:129], v[134:137], v[166:169], v[126:129]
	v_mfma_f32_16x16x32_bf16 v[118:121], v[142:145], v[166:169], v[118:121]
	v_mfma_f32_16x16x32_bf16 v[110:113], v[134:137], v[198:201], v[110:113]
	v_mfma_f32_16x16x32_bf16 v[102:105], v[142:145], v[198:201], v[102:105]
	v_mfma_f32_16x16x32_bf16 v[94:97], v[134:137], v[224:227], v[94:97]
	v_mfma_f32_16x16x32_bf16 v[86:89], v[142:145], v[224:227], v[86:89]
	v_mfma_f32_16x16x32_bf16 v[78:81], v[134:137], v[232:235], v[78:81]
	v_mfma_f32_16x16x32_bf16 v[70:73], v[142:145], v[232:235], v[70:73]
	v_mfma_f32_16x16x32_bf16 v[122:125], v[146:149], v[162:165], v[122:125]
	v_mfma_f32_16x16x32_bf16 v[114:117], v[154:157], v[162:165], v[114:117]
	v_mfma_f32_16x16x32_bf16 v[106:109], v[146:149], v[194:197], v[106:109]
	v_mfma_f32_16x16x32_bf16 v[98:101], v[154:157], v[194:197], v[98:101]
	v_mfma_f32_16x16x32_bf16 v[90:93], v[146:149], v[202:205], v[90:93]
	v_mfma_f32_16x16x32_bf16 v[82:85], v[154:157], v[202:205], v[82:85]
	v_mfma_f32_16x16x32_bf16 v[74:77], v[146:149], v[228:231], v[74:77]
	v_mfma_f32_16x16x32_bf16 v[66:69], v[154:157], v[228:231], v[66:69]
	v_mfma_f32_16x16x32_bf16 v[122:125], v[150:153], v[166:169], v[122:125]
	v_mfma_f32_16x16x32_bf16 v[114:117], v[158:161], v[166:169], v[114:117]
	v_mfma_f32_16x16x32_bf16 v[106:109], v[150:153], v[198:201], v[106:109]
	v_mfma_f32_16x16x32_bf16 v[98:101], v[158:161], v[198:201], v[98:101]
	v_mfma_f32_16x16x32_bf16 v[90:93], v[150:153], v[224:227], v[90:93]
	v_mfma_f32_16x16x32_bf16 v[82:85], v[158:161], v[224:227], v[82:85]
	v_mfma_f32_16x16x32_bf16 v[74:77], v[150:153], v[232:235], v[74:77]
	v_mfma_f32_16x16x32_bf16 v[66:69], v[158:161], v[232:235], v[66:69]
	s_barrier
; #define PG8_STAGE(bufoff, gbase, voff) do { _Pragma("unroll") for (int _i = 0; _i < 2; ++_i) \
;         __builtin_amdgcn_global_load_lds((const unsigned*)((const char*)(gbase) + (voff)[_i]), (LAS unsigned*)(lds + (bufoff) + ldsw + _i * 8192), 16, 0, 0); } while (0)
; #define PG8_LDA(dst, b, h) do { _Pragma("unroll") for (int m = 0; m < 4; ++m) _Pragma("unroll") for (int k = 0; k < 2; ++k) dst[m][k] = *(const LAS bf16x8*)(lds + PG8_SA(b, h) + aoff + m * 2048 + k * 1024); } while (0)
; #define PG8_LDB(dst, b, h) do { _Pragma("unroll") for (int n = 0; n < 2; ++n) _Pragma("unroll") for (int k = 0; k < 2; ++k) dst[n][k] = *(const LAS bf16x8*)(lds + PG8_SB(b, h) + boff + n * 2048 + k * 1024); } while (0)
; #define PG8_WAIT_V(n) asm volatile("s_waitcnt vmcnt(" #n ")" ::: "memory")
; #define PG8_BAR __builtin_amdgcn_s_barrier()
; template <class Epi, class Sched>
; __device__ __forceinline__ void gemm_phase(LAS unsigned char* lds, const Gemm g, const Sched& S, const Epi& E) {
;     ...
;         for (int t = 0; t < nt; t += 2) {
;             const bool last = (t == nt - 2);
;             const char* a1 = cA + (size_t)(t + 1) * kstep;
;             const char* a2 = last ? nA : cA + (size_t)(t + 2) * kstep; const char* b2 = last ? nB : cB + (size_t)(t + 2) * kstep;
;             const char* a3 = a2 + kstep; const char* b3 = b2 + kstep;
;             PG8_LDB(B0, 0, 0); PG8_LDB(B1, 0, 1); PG8_SCHED; PG8_LDA(At, 0, 0); PG8_STAGE(PG8_SA(1, 1), a1 + hstepA, voffA);
;             PG8_WAIT_V(8); PG8_WAIT_L(0); PG8_BAR; PG8_MMA(0, 0, At, B0); PG8_MMA(0, 1, At, B1); PG8_BAR; PG8_SCHED;
;             PG8_LDA(At, 0, 1); PG8_STAGE(PG8_SB(0, 0), b2, voffB); PG8_STAGE(PG8_SB(0, 1), b2 + hstepB, voffB); PG8_STAGE(PG8_SA(0, 0), a2, voffA);
;             PG8_WAIT_V(8); PG8_WAIT_L(0); PG8_BAR; PG8_MMA(1, 0, At, B0); PG8_MMA(1, 1, At, B1); PG8_BAR; PG8_SCHED;
;             PG8_LDB(B0, 1, 0); PG8_LDB(B1, 1, 1); PG8_SCHED; PG8_LDA(At, 1, 0); PG8_STAGE(PG8_SA(0, 1), a2 + hstepA, voffA);
;             PG8_WAIT_V(8); PG8_WAIT_L(0); PG8_BAR; PG8_MMA(0, 0, At, B0); PG8_MMA(0, 1, At, B1); PG8_BAR; PG8_SCHED;
;             PG8_LDA(At, 1, 1); PG8_STAGE(PG8_SB(1, 0), b3, voffB); PG8_STAGE(PG8_SB(1, 1), b3 + hstepB, voffB); PG8_STAGE(PG8_SA(1, 0), a3, voffA);
;             PG8_WAIT_V(8); PG8_WAIT_L(0); PG8_BAR; PG8_MMA(1, 0, At, B0); PG8_MMA(1, 1, At, B1); PG8_BAR; PG8_SCHED;
	s_add_i32 s20, s8, 0x18000
	s_add_u32 s88, s86, 0x80
	s_addc_u32 s89, s87, 0
	s_mov_b32 m0, s20
	ds_read_b128 v[162:165], v222 offset:49152
	ds_read_b128 v[166:169], v222 offset:50176
	ds_read_b128 v[194:197], v222 offset:51200
	ds_read_b128 v[198:201], v222 offset:52224
	ds_read_b128 v[202:205], v222 offset:53248
	ds_read_b128 v[224:227], v222 offset:54272
	ds_read_b128 v[228:231], v222 offset:55296
	ds_read_b128 v[232:235], v222 offset:56320
	global_load_lds_dwordx4 v172, s[88:89]
	s_add_i32 m0, s20, 0x2000
	s_add_u32 s20, s86, 0x40080
	s_addc_u32 s21, s87, 0
	s_add_i32 s12, s8, 0x1c000
	global_load_lds_dwordx4 v192, s[88:89]
	s_mov_b32 m0, s12
	s_nop 0
	global_load_lds_dwordx4 v172, s[20:21]
	s_add_i32 m0, s12, 0x2000
	s_nop 0
	global_load_lds_dwordx4 v192, s[20:21]
	s_mov_b32 m0, s31
	s_nop 0
	global_load_lds_dwordx4 v170, s[100:101]
	s_mov_b32 m0, s34
	s_nop 0
	global_load_lds_dwordx4 v190, s[100:101]
	s_waitcnt vmcnt(8)
	s_waitcnt lgkmcnt(0)
	s_barrier
	s_waitcnt lgkmcnt(0)
	v_mfma_f32_16x16x32_bf16 v[62:65], v[130:133], v[162:165], v[62:65]
	v_mfma_f32_16x16x32_bf16 v[54:57], v[138:141], v[162:165], v[54:57]
	v_mfma_f32_16x16x32_bf16 v[46:49], v[130:133], v[194:197], v[46:49]
	v_mfma_f32_16x16x32_bf16 v[38:41], v[138:141], v[194:197], v[38:41]
	v_mfma_f32_16x16x32_bf16 v[30:33], v[130:133], v[202:205], v[30:33]
	v_mfma_f32_16x16x32_bf16 v[22:25], v[138:141], v[202:205], v[22:25]
	v_mfma_f32_16x16x32_bf16 v[14:17], v[130:133], v[228:231], v[14:17]
	v_mfma_f32_16x16x32_bf16 v[6:9], v[138:141], v[228:231], v[6:9]
	v_mfma_f32_16x16x32_bf16 v[62:65], v[134:137], v[166:169], v[62:65]
	v_mfma_f32_16x16x32_bf16 v[54:57], v[142:145], v[166:169], v[54:57]
	v_mfma_f32_16x16x32_bf16 v[46:49], v[134:137], v[198:201], v[46:49]
	v_mfma_f32_16x16x32_bf16 v[38:41], v[142:145], v[198:201], v[38:41]
	v_mfma_f32_16x16x32_bf16 v[30:33], v[134:137], v[224:227], v[30:33]
	v_mfma_f32_16x16x32_bf16 v[22:25], v[142:145], v[224:227], v[22:25]
	v_mfma_f32_16x16x32_bf16 v[14:17], v[134:137], v[232:235], v[14:17]
	v_mfma_f32_16x16x32_bf16 v[6:9], v[142:145], v[232:235], v[6:9]
	v_mfma_f32_16x16x32_bf16 v[58:61], v[146:149], v[162:165], v[58:61]
	v_mfma_f32_16x16x32_bf16 v[50:53], v[154:157], v[162:165], v[50:53]
	v_mfma_f32_16x16x32_bf16 v[42:45], v[146:149], v[194:197], v[42:45]
	v_mfma_f32_16x16x32_bf16 v[34:37], v[154:157], v[194:197], v[34:37]
	v_mfma_f32_16x16x32_bf16 v[26:29], v[146:149], v[202:205], v[26:29]
	v_mfma_f32_16x16x32_bf16 v[18:21], v[154:157], v[202:205], v[18:21]
	v_mfma_f32_16x16x32_bf16 v[10:13], v[146:149], v[228:231], v[10:13]
	v_mfma_f32_16x16x32_bf16 v[2:5], v[154:157], v[228:231], v[2:5]
	v_mfma_f32_16x16x32_bf16 v[58:61], v[150:153], v[166:169], v[58:61]
	v_mfma_f32_16x16x32_bf16 v[50:53], v[158:161], v[166:169], v[50:53]
	v_mfma_f32_16x16x32_bf16 v[42:45], v[150:153], v[198:201], v[42:45]
	v_mfma_f32_16x16x32_bf16 v[34:37], v[158:161], v[198:201], v[34:37]
	v_mfma_f32_16x16x32_bf16 v[26:29], v[150:153], v[224:227], v[26:29]
	v_mfma_f32_16x16x32_bf16 v[18:21], v[158:161], v[224:227], v[18:21]
	v_mfma_f32_16x16x32_bf16 v[10:13], v[150:153], v[232:235], v[10:13]
	v_mfma_f32_16x16x32_bf16 v[2:5], v[158:161], v[232:235], v[2:5]
	s_barrier
	s_add_i32 s83, s83, 2
	s_add_u32 s18, s18, 0x100
	s_addc_u32 s19, s19, 0
	s_add_u32 s54, s54, 0x100
	s_addc_u32 s81, s81, 0
	s_cmp_gt_u32 s83, 13
.LBB0_232:
	s_add_u32 s20, s18, 0xfffc0080
	s_addc_u32 s21, s19, -1
	s_add_i32 s88, 0, 0x10000
	s_cmp_eq_u32 s83, 12
	s_cselect_b32 s21, s43, s21
	s_cselect_b32 s20, s48, s20
	s_cselect_b32 s87, s49, s81
	s_cselect_b32 s86, s53, s54
	s_add_i32 s90, 0, 0x14000
	s_add_u32 s100, s20, 0x80
	s_addc_u32 s101, s21, 0
	s_add_i32 m0, s9, 0xc000
	s_nop 0
	global_load_lds_dwordx4 v170, s[18:19]
	s_add_i32 m0, s9, 0xe000
	s_nop 0
	global_load_lds_dwordx4 v190, s[18:19]
	ds_read_b128 v[130:133], v246
	ds_read_b128 v[134:137], v246 offset:1024
	ds_read_b128 v[138:141], v246 offset:2048
	ds_read_b128 v[142:145], v246 offset:3072
	ds_read_b128 v[146:149], v246 offset:16384
	ds_read_b128 v[150:153], v246 offset:17408
	ds_read_b128 v[154:157], v246 offset:18432
	ds_read_b128 v[158:161], v246 offset:19456
	ds_read_b128 v[162:165], v222
	ds_read_b128 v[166:169], v222 offset:1024
	ds_read_b128 v[194:197], v222 offset:2048
	ds_read_b128 v[198:201], v222 offset:3072
	ds_read_b128 v[202:205], v222 offset:4096
	ds_read_b128 v[224:227], v222 offset:5120
	ds_read_b128 v[228:231], v222 offset:6144
	ds_read_b128 v[232:235], v222 offset:7168
	s_waitcnt vmcnt(8)
	s_waitcnt lgkmcnt(0)
	s_barrier
; #define PG8_STAGE(bufoff, gbase, voff) do { _Pragma("unroll") for (int _i = 0; _i < 2; ++_i) \
;         __builtin_amdgcn_global_load_lds((const unsigned*)((const char*)(gbase) + (voff)[_i]), (LAS unsigned*)(lds + (bufoff) + ldsw + _i * 8192), 16, 0, 0); } while (0)
; #define PG8_LDA(dst, b, h) do { _Pragma("unroll") for (int m = 0; m < 4; ++m) _Pragma("unroll") for (int k = 0; k < 2; ++k) dst[m][k] = *(const LAS bf16x8*)(lds + PG8_SA(b, h) + aoff + m * 2048 + k * 1024); } while (0)
; #define PG8_LDB(dst, b, h) do { _Pragma("unroll") for (int n = 0; n < 2; ++n) _Pragma("unroll") for (int k = 0; k < 2; ++k) dst[n][k] = *(const LAS bf16x8*)(lds + PG8_SB(b, h) + boff + n * 2048 + k * 1024); } while (0)
; #define PG8_MMA(ai, bj, At, Bt) do { __builtin_amdgcn_s_setprio(1); _Pragma("unroll") for (int m = 0; m < 4; ++m) _Pragma("unroll") for (int n = 0; n < 2; ++n) _Pragma("unroll") for (int k = 0; k < 2; ++k) \
;         acc[ai][bj][m][n] = __builtin_amdgcn_mfma_f32_16x16x32_bf16(Bt[n][k], At[m][k], acc[ai][bj][m][n], 0, 0, 0); __builtin_amdgcn_s_setprio(0); } while (0)
; #define PG8_WAIT_V(n) asm volatile("s_waitcnt vmcnt(" #n ")" ::: "memory")
; #define PG8_WAIT_L(n) asm volatile("s_waitcnt lgkmcnt(" #n ")" ::: "memory")
; #define PG8_BAR __builtin_amdgcn_s_barrier()
; #define PG8_SCHED __builtin_amdgcn_sched_barrier(0)
; template <class Epi, class Sched>
; __device__ __forceinline__ void gemm_phase(LAS unsigned char* lds, const Gemm g, const Sched& S, const Epi& E) {
;     ...
;             PG8_LDB(B0, 0, 0); PG8_LDB(B1, 0, 1); PG8_SCHED; PG8_LDA(At, 0, 0); PG8_STAGE(PG8_SA(1, 1), a1 + hstepA, voffA);
;             PG8_WAIT_V(8); PG8_WAIT_L(0); PG8_BAR; PG8_MMA(0, 0, At, B0); PG8_MMA(0, 1, At, B1); PG8_BAR; PG8_SCHED;
;             PG8_LDA(At, 0, 1); PG8_STAGE(PG8_SB(0, 0), b2, voffB); PG8_STAGE(PG8_SB(0, 1), b2 + hstepB, voffB); PG8_STAGE(PG8_SA(0, 0), a2, voffA);
;             PG8_WAIT_V(8); PG8_WAIT_L(0); PG8_BAR; PG8_MMA(1, 0, At, B0); PG8_MMA(1, 1, At, B1); PG8_BAR; PG8_SCHED;
	s_waitcnt lgkmcnt(0)
	v_mfma_f32_16x16x32_bf16 v[126:129], v[130:133], v[162:165], v[126:129]
	v_mfma_f32_16x16x32_bf16 v[118:121], v[138:141], v[162:165], v[118:121]
	v_mfma_f32_16x16x32_bf16 v[110:113], v[130:133], v[194:197], v[110:113]
	v_mfma_f32_16x16x32_bf16 v[102:105], v[138:141], v[194:197], v[102:105]
	v_mfma_f32_16x16x32_bf16 v[94:97], v[130:133], v[202:205], v[94:97]
	v_mfma_f32_16x16x32_bf16 v[86:89], v[138:141], v[202:205], v[86:89]
	v_mfma_f32_16x16x32_bf16 v[78:81], v[130:133], v[228:231], v[78:81]
	v_mfma_f32_16x16x32_bf16 v[70:73], v[138:141], v[228:231], v[70:73]
	v_mfma_f32_16x16x32_bf16 v[126:129], v[134:137], v[166:169], v[126:129]
	v_mfma_f32_16x16x32_bf16 v[118:121], v[142:145], v[166:169], v[118:121]
	v_mfma_f32_16x16x32_bf16 v[110:113], v[134:137], v[198:201], v[110:113]
	v_mfma_f32_16x16x32_bf16 v[102:105], v[142:145], v[198:201], v[102:105]
	v_mfma_f32_16x16x32_bf16 v[94:97], v[134:137], v[224:227], v[94:97]
	v_mfma_f32_16x16x32_bf16 v[86:89], v[142:145], v[224:227], v[86:89]
	v_mfma_f32_16x16x32_bf16 v[78:81], v[134:137], v[232:235], v[78:81]
	v_mfma_f32_16x16x32_bf16 v[70:73], v[142:145], v[232:235], v[70:73]
	v_mfma_f32_16x16x32_bf16 v[122:125], v[146:149], v[162:165], v[122:125]
	v_mfma_f32_16x16x32_bf16 v[114:117], v[154:157], v[162:165], v[114:117]
	v_mfma_f32_16x16x32_bf16 v[106:109], v[146:149], v[194:197], v[106:109]
	v_mfma_f32_16x16x32_bf16 v[98:101], v[154:157], v[194:197], v[98:101]
	v_mfma_f32_16x16x32_bf16 v[90:93], v[146:149], v[202:205], v[90:93]
	v_mfma_f32_16x16x32_bf16 v[82:85], v[154:157], v[202:205], v[82:85]
	v_mfma_f32_16x16x32_bf16 v[74:77], v[146:149], v[228:231], v[74:77]
	v_mfma_f32_16x16x32_bf16 v[66:69], v[154:157], v[228:231], v[66:69]
	v_mfma_f32_16x16x32_bf16 v[122:125], v[150:153], v[166:169], v[122:125]
	v_mfma_f32_16x16x32_bf16 v[114:117], v[158:161], v[166:169], v[114:117]
	v_mfma_f32_16x16x32_bf16 v[106:109], v[150:153], v[198:201], v[106:109]
	v_mfma_f32_16x16x32_bf16 v[98:101], v[158:161], v[198:201], v[98:101]
	v_mfma_f32_16x16x32_bf16 v[90:93], v[150:153], v[224:227], v[90:93]
	v_mfma_f32_16x16x32_bf16 v[82:85], v[158:161], v[224:227], v[82:85]
	v_mfma_f32_16x16x32_bf16 v[74:77], v[150:153], v[232:235], v[74:77]
	v_mfma_f32_16x16x32_bf16 v[66:69], v[158:161], v[232:235], v[66:69]
	s_barrier
	s_add_i32 s88, s88, s8
	s_mov_b32 m0, s88
	ds_read_b128 v[162:165], v222 offset:16384
	ds_read_b128 v[166:169], v222 offset:17408
	ds_read_b128 v[194:197], v222 offset:18432
	ds_read_b128 v[198:201], v222 offset:19456
	ds_read_b128 v[202:205], v222 offset:20480
	ds_read_b128 v[224:227], v222 offset:21504
	ds_read_b128 v[228:231], v222 offset:22528
	ds_read_b128 v[232:235], v222 offset:23552
	global_load_lds_dwordx4 v172, s[86:87]
	s_add_i32 m0, s88, 0x2000
	s_add_u32 s88, s86, 0x40000
	s_addc_u32 s89, s87, 0
	s_add_i32 s90, s90, s8
	global_load_lds_dwordx4 v192, s[86:87]
	s_mov_b32 m0, s90
	s_nop 0
	global_load_lds_dwordx4 v172, s[88:89]
	s_add_i32 m0, s90, 0x2000
	s_nop 0
	global_load_lds_dwordx4 v192, s[88:89]
	s_mov_b32 m0, s9
	s_nop 0
	global_load_lds_dwordx4 v170, s[20:21]
	s_mov_b32 m0, s28
	s_nop 0
	global_load_lds_dwordx4 v190, s[20:21]
	s_waitcnt vmcnt(8)
	s_waitcnt lgkmcnt(0)
	s_barrier
	s_waitcnt lgkmcnt(0)
	v_mfma_f32_16x16x32_bf16 v[62:65], v[130:133], v[162:165], v[62:65]
	v_mfma_f32_16x16x32_bf16 v[54:57], v[138:141], v[162:165], v[54:57]
	v_mfma_f32_16x16x32_bf16 v[46:49], v[130:133], v[194:197], v[46:49]
	v_mfma_f32_16x16x32_bf16 v[38:41], v[138:141], v[194:197], v[38:41]
	v_mfma_f32_16x16x32_bf16 v[30:33], v[130:133], v[202:205], v[30:33]
	v_mfma_f32_16x16x32_bf16 v[22:25], v[138:141], v[202:205], v[22:25]
	v_mfma_f32_16x16x32_bf16 v[14:17], v[130:133], v[228:231], v[14:17]
	v_mfma_f32_16x16x32_bf16 v[6:9], v[138:141], v[228:231], v[6:9]
	v_mfma_f32_16x16x32_bf16 v[62:65], v[134:137], v[166:169], v[62:65]
	v_mfma_f32_16x16x32_bf16 v[54:57], v[142:145], v[166:169], v[54:57]
	v_mfma_f32_16x16x32_bf16 v[46:49], v[134:137], v[198:201], v[46:49]
	v_mfma_f32_16x16x32_bf16 v[38:41], v[142:145], v[198:201], v[38:41]
	v_mfma_f32_16x16x32_bf16 v[30:33], v[134:137], v[224:227], v[30:33]
	v_mfma_f32_16x16x32_bf16 v[22:25], v[142:145], v[224:227], v[22:25]
	v_mfma_f32_16x16x32_bf16 v[14:17], v[134:137], v[232:235], v[14:17]
	v_mfma_f32_16x16x32_bf16 v[6:9], v[142:145], v[232:235], v[6:9]
	v_mfma_f32_16x16x32_bf16 v[58:61], v[146:149], v[162:165], v[58:61]
	v_mfma_f32_16x16x32_bf16 v[50:53], v[154:157], v[162:165], v[50:53]
	v_mfma_f32_16x16x32_bf16 v[42:45], v[146:149], v[194:197], v[42:45]
	v_mfma_f32_16x16x32_bf16 v[34:37], v[154:157], v[194:197], v[34:37]
	v_mfma_f32_16x16x32_bf16 v[26:29], v[146:149], v[202:205], v[26:29]
	v_mfma_f32_16x16x32_bf16 v[18:21], v[154:157], v[202:205], v[18:21]
	v_mfma_f32_16x16x32_bf16 v[10:13], v[146:149], v[228:231], v[10:13]
	v_mfma_f32_16x16x32_bf16 v[2:5], v[154:157], v[228:231], v[2:5]
	v_mfma_f32_16x16x32_bf16 v[58:61], v[150:153], v[166:169], v[58:61]
	v_mfma_f32_16x16x32_bf16 v[50:53], v[158:161], v[166:169], v[50:53]
	v_mfma_f32_16x16x32_bf16 v[42:45], v[150:153], v[198:201], v[42:45]
	v_mfma_f32_16x16x32_bf16 v[34:37], v[158:161], v[198:201], v[34:37]
	v_mfma_f32_16x16x32_bf16 v[26:29], v[150:153], v[224:227], v[26:29]
	v_mfma_f32_16x16x32_bf16 v[18:21], v[158:161], v[224:227], v[18:21]
	v_mfma_f32_16x16x32_bf16 v[10:13], v[150:153], v[232:235], v[10:13]
	v_mfma_f32_16x16x32_bf16 v[2:5], v[158:161], v[232:235], v[2:5]
	s_barrier
; #define PG8_STAGE(bufoff, gbase, voff) do { _Pragma("unroll") for (int _i = 0; _i < 2; ++_i) \
;         __builtin_amdgcn_global_load_lds((const unsigned*)((const char*)(gbase) + (voff)[_i]), (LAS unsigned*)(lds + (bufoff) + ldsw + _i * 8192), 16, 0, 0); } while (0)
; #define PG8_LDA(dst, b, h) do { _Pragma("unroll") for (int m = 0; m < 4; ++m) _Pragma("unroll") for (int k = 0; k < 2; ++k) dst[m][k] = *(const LAS bf16x8*)(lds + PG8_SA(b, h) + aoff + m * 2048 + k * 1024); } while (0)
; #define PG8_LDB(dst, b, h) do { _Pragma("unroll") for (int n = 0; n < 2; ++n) _Pragma("unroll") for (int k = 0; k < 2; ++k) dst[n][k] = *(const LAS bf16x8*)(lds + PG8_SB(b, h) + boff + n * 2048 + k * 1024); } while (0)
; #define PG8_MMA(ai, bj, At, Bt) do { __builtin_amdgcn_s_setprio(1); _Pragma("unroll") for (int m = 0; m < 4; ++m) _Pragma("unroll") for (int n = 0; n < 2; ++n) _Pragma("unroll") for (int k = 0; k < 2; ++k) \
;         acc[ai][bj][m][n] = __builtin_amdgcn_mfma_f32_16x16x32_bf16(Bt[n][k], At[m][k], acc[ai][bj][m][n], 0, 0, 0); __builtin_amdgcn_s_setprio(0); } while (0)
; #define PG8_WAIT_V(n) asm volatile("s_waitcnt vmcnt(" #n ")" ::: "memory")
; #define PG8_WAIT_L(n) asm volatile("s_waitcnt lgkmcnt(" #n ")" ::: "memory")
; #define PG8_BAR __builtin_amdgcn_s_barrier()
; #define PG8_SCHED __builtin_amdgcn_sched_barrier(0)
; template <class Epi, class Sched>
; __device__ __forceinline__ void gemm_phase(LAS unsigned char* lds, const Gemm g, const Sched& S, const Epi& E) {
;     ...
;             PG8_LDB(B0, 1, 0); PG8_LDB(B1, 1, 1); PG8_SCHED; PG8_LDA(At, 1, 0); PG8_STAGE(PG8_SA(0, 1), a2 + hstepA, voffA);
;             PG8_WAIT_V(8); PG8_WAIT_L(0); PG8_BAR; PG8_MMA(0, 0, At, B0); PG8_MMA(0, 1, At, B1); PG8_BAR; PG8_SCHED;
;             PG8_LDA(At, 1, 1); PG8_STAGE(PG8_SB(1, 0), b3, voffB); PG8_STAGE(PG8_SB(1, 1), b3 + hstepB, voffB); PG8_STAGE(PG8_SA(1, 0), a3, voffA);
;             PG8_WAIT_V(8); PG8_WAIT_L(0); PG8_BAR; PG8_MMA(1, 0, At, B0); PG8_MMA(1, 1, At, B1); PG8_BAR; PG8_SCHED;
;         }
	s_add_i32 s88, 0, 0x18000
	s_add_i32 s89, 0, 0x1c000
	s_add_u32 s20, s20, 0x40000
	s_addc_u32 s21, s21, 0
	s_mov_b32 m0, s29
	s_nop 0
	global_load_lds_dwordx4 v170, s[20:21]
	s_mov_b32 m0, s30
	s_nop 0
	global_load_lds_dwordx4 v190, s[20:21]
	ds_read_b128 v[130:133], v246 offset:32768
	ds_read_b128 v[134:137], v246 offset:33792
	ds_read_b128 v[138:141], v246 offset:34816
	ds_read_b128 v[142:145], v246 offset:35840
	ds_read_b128 v[146:149], v246 offset:49152
	ds_read_b128 v[150:153], v246 offset:50176
	ds_read_b128 v[154:157], v246 offset:51200
	ds_read_b128 v[158:161], v246 offset:52224
	ds_read_b128 v[162:165], v222 offset:32768
	ds_read_b128 v[166:169], v222 offset:33792
	ds_read_b128 v[194:197], v222 offset:34816
	ds_read_b128 v[198:201], v222 offset:35840
	ds_read_b128 v[202:205], v222 offset:36864
	ds_read_b128 v[224:227], v222 offset:37888
	ds_read_b128 v[228:231], v222 offset:38912
	ds_read_b128 v[232:235], v222 offset:39936
	s_waitcnt vmcnt(8)
	s_waitcnt lgkmcnt(0)
	s_barrier
	s_waitcnt lgkmcnt(0)
	v_mfma_f32_16x16x32_bf16 v[126:129], v[130:133], v[162:165], v[126:129]
	v_mfma_f32_16x16x32_bf16 v[118:121], v[138:141], v[162:165], v[118:121]
	v_mfma_f32_16x16x32_bf16 v[110:113], v[130:133], v[194:197], v[110:113]
	v_mfma_f32_16x16x32_bf16 v[102:105], v[138:141], v[194:197], v[102:105]
	v_mfma_f32_16x16x32_bf16 v[94:97], v[130:133], v[202:205], v[94:97]
	v_mfma_f32_16x16x32_bf16 v[86:89], v[138:141], v[202:205], v[86:89]
	v_mfma_f32_16x16x32_bf16 v[78:81], v[130:133], v[228:231], v[78:81]
	v_mfma_f32_16x16x32_bf16 v[70:73], v[138:141], v[228:231], v[70:73]
	v_mfma_f32_16x16x32_bf16 v[126:129], v[134:137], v[166:169], v[126:129]
	v_mfma_f32_16x16x32_bf16 v[118:121], v[142:145], v[166:169], v[118:121]
	v_mfma_f32_16x16x32_bf16 v[110:113], v[134:137], v[198:201], v[110:113]
	v_mfma_f32_16x16x32_bf16 v[102:105], v[142:145], v[198:201], v[102:105]
	v_mfma_f32_16x16x32_bf16 v[94:97], v[134:137], v[224:227], v[94:97]
	v_mfma_f32_16x16x32_bf16 v[86:89], v[142:145], v[224:227], v[86:89]
	v_mfma_f32_16x16x32_bf16 v[78:81], v[134:137], v[232:235], v[78:81]
	v_mfma_f32_16x16x32_bf16 v[70:73], v[142:145], v[232:235], v[70:73]
	v_mfma_f32_16x16x32_bf16 v[122:125], v[146:149], v[162:165], v[122:125]
	v_mfma_f32_16x16x32_bf16 v[114:117], v[154:157], v[162:165], v[114:117]
	v_mfma_f32_16x16x32_bf16 v[106:109], v[146:149], v[194:197], v[106:109]
	v_mfma_f32_16x16x32_bf16 v[98:101], v[154:157], v[194:197], v[98:101]
	v_mfma_f32_16x16x32_bf16 v[90:93], v[146:149], v[202:205], v[90:93]
	v_mfma_f32_16x16x32_bf16 v[82:85], v[154:157], v[202:205], v[82:85]
	v_mfma_f32_16x16x32_bf16 v[74:77], v[146:149], v[228:231], v[74:77]
	v_mfma_f32_16x16x32_bf16 v[66:69], v[154:157], v[228:231], v[66:69]
	v_mfma_f32_16x16x32_bf16 v[122:125], v[150:153], v[166:169], v[122:125]
	v_mfma_f32_16x16x32_bf16 v[114:117], v[158:161], v[166:169], v[114:117]
	v_mfma_f32_16x16x32_bf16 v[106:109], v[150:153], v[198:201], v[106:109]
	v_mfma_f32_16x16x32_bf16 v[98:101], v[158:161], v[198:201], v[98:101]
	v_mfma_f32_16x16x32_bf16 v[90:93], v[150:153], v[224:227], v[90:93]
	v_mfma_f32_16x16x32_bf16 v[82:85], v[158:161], v[224:227], v[82:85]
	v_mfma_f32_16x16x32_bf16 v[74:77], v[150:153], v[232:235], v[74:77]
	v_mfma_f32_16x16x32_bf16 v[66:69], v[158:161], v[232:235], v[66:69]
	s_barrier
	s_add_i32 s20, s8, 0x18000
	s_add_u32 s88, s86, 0x80
	s_addc_u32 s89, s87, 0
	s_mov_b32 m0, s20
	ds_read_b128 v[162:165], v222 offset:49152
	ds_read_b128 v[166:169], v222 offset:50176
	ds_read_b128 v[194:197], v222 offset:51200
	ds_read_b128 v[198:201], v222 offset:52224
	ds_read_b128 v[202:205], v222 offset:53248
	ds_read_b128 v[224:227], v222 offset:54272
	ds_read_b128 v[228:231], v222 offset:55296
	ds_read_b128 v[232:235], v222 offset:56320
	global_load_lds_dwordx4 v172, s[88:89]
	s_add_i32 m0, s20, 0x2000
	s_add_u32 s20, s86, 0x40080
	s_addc_u32 s21, s87, 0
	s_add_i32 s12, s8, 0x1c000
	global_load_lds_dwordx4 v192, s[88:89]
	s_mov_b32 m0, s12
	s_nop 0
	global_load_lds_dwordx4 v172, s[20:21]
	s_add_i32 m0, s12, 0x2000
	s_nop 0
	global_load_lds_dwordx4 v192, s[20:21]
	s_mov_b32 m0, s31
	s_nop 0
	global_load_lds_dwordx4 v170, s[100:101]
	s_mov_b32 m0, s34
	s_nop 0
	global_load_lds_dwordx4 v190, s[100:101]
	s_waitcnt vmcnt(8)
	s_waitcnt lgkmcnt(0)
	s_barrier
	s_waitcnt lgkmcnt(0)
	v_mfma_f32_16x16x32_bf16 v[62:65], v[130:133], v[162:165], v[62:65]
	v_mfma_f32_16x16x32_bf16 v[54:57], v[138:141], v[162:165], v[54:57]
	v_mfma_f32_16x16x32_bf16 v[46:49], v[130:133], v[194:197], v[46:49]
	v_mfma_f32_16x16x32_bf16 v[38:41], v[138:141], v[194:197], v[38:41]
	v_mfma_f32_16x16x32_bf16 v[30:33], v[130:133], v[202:205], v[30:33]
	v_mfma_f32_16x16x32_bf16 v[22:25], v[138:141], v[202:205], v[22:25]
	v_mfma_f32_16x16x32_bf16 v[14:17], v[130:133], v[228:231], v[14:17]
	v_mfma_f32_16x16x32_bf16 v[6:9], v[138:141], v[228:231], v[6:9]
	v_mfma_f32_16x16x32_bf16 v[62:65], v[134:137], v[166:169], v[62:65]
	v_mfma_f32_16x16x32_bf16 v[54:57], v[142:145], v[166:169], v[54:57]
	v_mfma_f32_16x16x32_bf16 v[46:49], v[134:137], v[198:201], v[46:49]
	v_mfma_f32_16x16x32_bf16 v[38:41], v[142:145], v[198:201], v[38:41]
	v_mfma_f32_16x16x32_bf16 v[30:33], v[134:137], v[224:227], v[30:33]
	v_mfma_f32_16x16x32_bf16 v[22:25], v[142:145], v[224:227], v[22:25]
	v_mfma_f32_16x16x32_bf16 v[14:17], v[134:137], v[232:235], v[14:17]
	v_mfma_f32_16x16x32_bf16 v[6:9], v[142:145], v[232:235], v[6:9]
	v_mfma_f32_16x16x32_bf16 v[58:61], v[146:149], v[162:165], v[58:61]
	v_mfma_f32_16x16x32_bf16 v[50:53], v[154:157], v[162:165], v[50:53]
	v_mfma_f32_16x16x32_bf16 v[42:45], v[146:149], v[194:197], v[42:45]
	v_mfma_f32_16x16x32_bf16 v[34:37], v[154:157], v[194:197], v[34:37]
	v_mfma_f32_16x16x32_bf16 v[26:29], v[146:149], v[202:205], v[26:29]
	v_mfma_f32_16x16x32_bf16 v[18:21], v[154:157], v[202:205], v[18:21]
	v_mfma_f32_16x16x32_bf16 v[10:13], v[146:149], v[228:231], v[10:13]
	v_mfma_f32_16x16x32_bf16 v[2:5], v[154:157], v[228:231], v[2:5]
	v_mfma_f32_16x16x32_bf16 v[58:61], v[150:153], v[166:169], v[58:61]
	v_mfma_f32_16x16x32_bf16 v[50:53], v[158:161], v[166:169], v[50:53]
	v_mfma_f32_16x16x32_bf16 v[42:45], v[150:153], v[198:201], v[42:45]
	v_mfma_f32_16x16x32_bf16 v[34:37], v[158:161], v[198:201], v[34:37]
	v_mfma_f32_16x16x32_bf16 v[26:29], v[150:153], v[224:227], v[26:29]
	v_mfma_f32_16x16x32_bf16 v[18:21], v[158:161], v[224:227], v[18:21]
	v_mfma_f32_16x16x32_bf16 v[10:13], v[150:153], v[232:235], v[10:13]
	v_mfma_f32_16x16x32_bf16 v[2:5], v[158:161], v[232:235], v[2:5]
	s_barrier
	s_add_i32 s83, s83, 2
	s_add_u32 s18, s18, 0x100
	s_addc_u32 s19, s19, 0
	s_add_u32 s54, s54, 0x100
	s_addc_u32 s81, s81, 0
	s_cmp_gt_u32 s83, 13
	s_cbranch_scc0 .LBB0_232
	s_and_b64 vcc, exec, s[72:73]
	s_cbranch_vccz .LBB0_235
	s_barrier

; #define PG8_STAGE(bufoff, gbase, voff) do { _Pragma("unroll") for (int _i = 0; _i < 2; ++_i) \
;         __builtin_amdgcn_global_load_lds((const unsigned*)((const char*)(gbase) + (voff)[_i]), (LAS unsigned*)(lds + (bufoff) + ldsw + _i * 8192), 16, 0, 0); } while (0)
; #define PG8_LDA(dst, b, h) do { _Pragma("unroll") for (int m = 0; m < 4; ++m) _Pragma("unroll") for (int k = 0; k < 2; ++k) dst[m][k] = *(const LAS bf16x8*)(lds + PG8_SA(b, h) + aoff + m * 2048 + k * 1024); } while (0)
; #define PG8_LDB(dst, b, h) do { _Pragma("unroll") for (int n = 0; n < 2; ++n) _Pragma("unroll") for (int k = 0; k < 2; ++k) dst[n][k] = *(const LAS bf16x8*)(lds + PG8_SB(b, h) + boff + n * 2048 + k * 1024); } while (0)
; #define PG8_MMA(ai, bj, At, Bt) do { __builtin_amdgcn_s_setprio(1); _Pragma("unroll") for (int m = 0; m < 4; ++m) _Pragma("unroll") for (int n = 0; n < 2; ++n) _Pragma("unroll") for (int k = 0; k < 2; ++k) \
;         acc[ai][bj][m][n] = __builtin_amdgcn_mfma_f32_16x16x32_bf16(Bt[n][k], At[m][k], acc[ai][bj][m][n], 0, 0, 0); __builtin_amdgcn_s_setprio(0); } while (0)
; #define PG8_WAIT_V(n) asm volatile("s_waitcnt vmcnt(" #n ")" ::: "memory")
; template <class Epi, class Sched>
; __device__ __forceinline__ void gemm_phase(LAS unsigned char* lds, const Gemm g, const Sched& S, const Epi& E) {
;     ...
;         const char* nA = has_next ? (const char*)g.A + (size_t)nxt.pm * tstepA + (size_t)nxt.pn * g.a_pn_off * 2 : cA; const char* nB = has_next ? (const char*)g.Bt + (size_t)nxt.pn * tstepB : cB;
;         for (int t = 0; t < nt; t += 2) {
;             const bool last = (t == nt - 2);
;             const char* a1 = cA + (size_t)(t + 1) * kstep;
;             const char* a2 = last ? nA : cA + (size_t)(t + 2) * kstep; const char* b2 = last ? nB : cB + (size_t)(t + 2) * kstep;
;             const char* a3 = a2 + kstep; const char* b3 = b2 + kstep;
;             PG8_LDB(B0, 0, 0); PG8_LDB(B1, 0, 1); PG8_SCHED; PG8_LDA(At, 0, 0); PG8_STAGE(PG8_SA(1, 1), a1 + hstepA, voffA);
;             PG8_WAIT_V(8); PG8_WAIT_L(0); PG8_BAR; PG8_MMA(0, 0, At, B0); PG8_MMA(0, 1, At, B1); PG8_BAR; PG8_SCHED;
;             PG8_LDA(At, 0, 1); PG8_STAGE(PG8_SB(0, 0), b2, voffB); PG8_STAGE(PG8_SB(0, 1), b2 + hstepB, voffB); PG8_STAGE(PG8_SA(0, 0), a2, voffA);
;             PG8_WAIT_V(8); PG8_WAIT_L(0); PG8_BAR; PG8_MMA(1, 0, At, B0); PG8_MMA(1, 1, At, B1); PG8_BAR; PG8_SCHED;
.LBB0_348:
	s_ashr_i32 s71, s70, 31
	s_lshl_b64 s[48:49], s[70:71], 19
	s_add_u32 s72, s4, s48
	s_addc_u32 s73, s5, s49
	s_and_b64 s[48:49], s[66:67], exec
	s_cselect_b32 s48, s73, s19
	s_cselect_b32 s49, s72, s18
	s_ashr_i32 s69, s68, 31
	s_lshl_b64 s[74:75], s[68:69], 19
	v_readlane_b32 s12, v248, 13
	s_add_u32 s74, s12, s74
	v_readlane_b32 s12, v248, 14
	s_addc_u32 s75, s12, s75
	s_and_b64 s[76:77], s[66:67], exec
	s_cselect_b32 s53, s75, s21
	s_cselect_b32 s54, s74, s20
	s_add_u32 s18, s18, 0x40080
	s_addc_u32 s19, s19, 0
	s_add_u32 s69, s20, 0x100
	s_addc_u32 s71, s21, 0
	s_mov_b32 s78, -2
	s_waitcnt vmcnt(0)
	v_add_u32_e32 v255, 0x10000, v139
	s_add_u32 s20, s18, 0xfffc0080
	s_addc_u32 s21, s19, -1
	s_add_i32 s79, 0, 0x10000
	s_cmp_eq_u32 s78, 12
	s_cselect_b32 s21, s48, s21
	s_cselect_b32 s20, s49, s20
	s_cselect_b32 s77, s53, s71
	s_cselect_b32 s76, s54, s69
	s_add_u32 s100, s20, 0x80
	s_addc_u32 s101, s21, 0
	s_add_i32 s82, 0, 0x14000
	s_add_i32 m0, s9, 0xc000
	s_nop 0
	global_load_lds_dwordx4 v130, s[18:19]
	s_add_i32 m0, s9, 0xe000
	s_nop 0
	global_load_lds_dwordx4 v134, s[18:19]
	ds_read_b128 v[150:153], v255
	ds_read_b128 v[154:157], v255 offset:1024
	ds_read_b128 v[158:161], v255 offset:2048
	ds_read_b128 v[162:165], v255 offset:3072
	ds_read_b128 v[166:169], v255 offset:16384
	ds_read_b128 v[170:173], v255 offset:17408
	ds_read_b128 v[190:193], v255 offset:18432
	ds_read_b128 v[194:197], v255 offset:19456
	ds_read_b128 v[198:201], v148
	ds_read_b128 v[202:205], v148 offset:1024
	ds_read_b128 v[206:209], v148 offset:2048
	ds_read_b128 v[218:221], v148 offset:3072
	ds_read_b128 v[222:225], v148 offset:4096
	ds_read_b128 v[226:229], v148 offset:5120
	ds_read_b128 v[230:233], v148 offset:6144
	ds_read_b128 v[234:237], v148 offset:7168
	s_waitcnt vmcnt(8)
	s_waitcnt lgkmcnt(0)
	s_barrier
	s_waitcnt lgkmcnt(0)
	v_mfma_f32_16x16x32_bf16 v[126:129], v[150:153], v[198:201], 0
	v_mfma_f32_16x16x32_bf16 v[122:125], v[158:161], v[198:201], 0
	v_mfma_f32_16x16x32_bf16 v[110:113], v[150:153], v[206:209], 0
	v_mfma_f32_16x16x32_bf16 v[106:109], v[158:161], v[206:209], 0
	v_mfma_f32_16x16x32_bf16 v[94:97], v[150:153], v[222:225], 0
	v_mfma_f32_16x16x32_bf16 v[90:93], v[158:161], v[222:225], 0
	v_mfma_f32_16x16x32_bf16 v[82:85], v[150:153], v[230:233], 0
	v_mfma_f32_16x16x32_bf16 v[74:77], v[158:161], v[230:233], 0
	v_mfma_f32_16x16x32_bf16 v[126:129], v[154:157], v[202:205], v[126:129]
	v_mfma_f32_16x16x32_bf16 v[122:125], v[162:165], v[202:205], v[122:125]
	v_mfma_f32_16x16x32_bf16 v[110:113], v[154:157], v[218:221], v[110:113]
	v_mfma_f32_16x16x32_bf16 v[106:109], v[162:165], v[218:221], v[106:109]
	v_mfma_f32_16x16x32_bf16 v[94:97], v[154:157], v[226:229], v[94:97]
	v_mfma_f32_16x16x32_bf16 v[90:93], v[162:165], v[226:229], v[90:93]
	v_mfma_f32_16x16x32_bf16 v[82:85], v[154:157], v[234:237], v[82:85]
	v_mfma_f32_16x16x32_bf16 v[74:77], v[162:165], v[234:237], v[74:77]
	v_mfma_f32_16x16x32_bf16 v[118:121], v[166:169], v[198:201], 0
	v_mfma_f32_16x16x32_bf16 v[114:117], v[190:193], v[198:201], 0
	v_mfma_f32_16x16x32_bf16 v[102:105], v[166:169], v[206:209], 0
	v_mfma_f32_16x16x32_bf16 v[98:101], v[190:193], v[206:209], 0
	v_mfma_f32_16x16x32_bf16 v[86:89], v[166:169], v[222:225], 0
	v_mfma_f32_16x16x32_bf16 v[78:81], v[190:193], v[222:225], 0
	v_mfma_f32_16x16x32_bf16 v[70:73], v[166:169], v[230:233], 0
	v_mfma_f32_16x16x32_bf16 v[66:69], v[190:193], v[230:233], 0
	v_mfma_f32_16x16x32_bf16 v[118:121], v[170:173], v[202:205], v[118:121]
	v_mfma_f32_16x16x32_bf16 v[114:117], v[194:197], v[202:205], v[114:117]
	v_mfma_f32_16x16x32_bf16 v[102:105], v[170:173], v[218:221], v[102:105]
	v_mfma_f32_16x16x32_bf16 v[98:101], v[194:197], v[218:221], v[98:101]
	v_mfma_f32_16x16x32_bf16 v[86:89], v[170:173], v[226:229], v[86:89]
	v_mfma_f32_16x16x32_bf16 v[78:81], v[194:197], v[226:229], v[78:81]
	v_mfma_f32_16x16x32_bf16 v[70:73], v[170:173], v[234:237], v[70:73]
	v_mfma_f32_16x16x32_bf16 v[66:69], v[194:197], v[234:237], v[66:69]
	s_barrier
	s_add_i32 s79, s79, s8
	s_mov_b32 m0, s79
	ds_read_b128 v[198:201], v148 offset:16384
	ds_read_b128 v[202:205], v148 offset:17408
	ds_read_b128 v[206:209], v148 offset:18432
	ds_read_b128 v[218:221], v148 offset:19456
	ds_read_b128 v[222:225], v148 offset:20480
	ds_read_b128 v[226:229], v148 offset:21504
	ds_read_b128 v[230:233], v148 offset:22528
	ds_read_b128 v[234:237], v148 offset:23552
	global_load_lds_dwordx4 v132, s[76:77]
	s_add_i32 m0, s79, 0x2000
	s_add_u32 s80, s76, 0x40000
	s_addc_u32 s81, s77, 0
	s_add_i32 s79, s82, s8
	global_load_lds_dwordx4 v136, s[76:77]
	s_mov_b32 m0, s79
	s_nop 0
	global_load_lds_dwordx4 v132, s[80:81]
	s_add_i32 m0, s79, 0x2000
	s_nop 0
	global_load_lds_dwordx4 v136, s[80:81]
	s_mov_b32 m0, s9
	s_nop 0
	global_load_lds_dwordx4 v130, s[20:21]
	s_mov_b32 m0, s28
	s_nop 0
	global_load_lds_dwordx4 v134, s[20:21]
	s_waitcnt vmcnt(8)
	s_waitcnt lgkmcnt(0)
	s_barrier
; #define PG8_STAGE(bufoff, gbase, voff) do { _Pragma("unroll") for (int _i = 0; _i < 2; ++_i) \
;         __builtin_amdgcn_global_load_lds((const unsigned*)((const char*)(gbase) + (voff)[_i]), (LAS unsigned*)(lds + (bufoff) + ldsw + _i * 8192), 16, 0, 0); } while (0)
; #define PG8_LDA(dst, b, h) do { _Pragma("unroll") for (int m = 0; m < 4; ++m) _Pragma("unroll") for (int k = 0; k < 2; ++k) dst[m][k] = *(const LAS bf16x8*)(lds + PG8_SA(b, h) + aoff + m * 2048 + k * 1024); } while (0)
; #define PG8_LDB(dst, b, h) do { _Pragma("unroll") for (int n = 0; n < 2; ++n) _Pragma("unroll") for (int k = 0; k < 2; ++k) dst[n][k] = *(const LAS bf16x8*)(lds + PG8_SB(b, h) + boff + n * 2048 + k * 1024); } while (0)
; #define PG8_MMA(ai, bj, At, Bt) do { __builtin_amdgcn_s_setprio(1); _Pragma("unroll") for (int m = 0; m < 4; ++m) _Pragma("unroll") for (int n = 0; n < 2; ++n) _Pragma("unroll") for (int k = 0; k < 2; ++k) \
;         acc[ai][bj][m][n] = __builtin_amdgcn_mfma_f32_16x16x32_bf16(Bt[n][k], At[m][k], acc[ai][bj][m][n], 0, 0, 0); __builtin_amdgcn_s_setprio(0); } while (0)
; #define PG8_WAIT_V(n) asm volatile("s_waitcnt vmcnt(" #n ")" ::: "memory")
; #define PG8_WAIT_L(n) asm volatile("s_waitcnt lgkmcnt(" #n ")" ::: "memory")
; #define PG8_BAR __builtin_amdgcn_s_barrier()
; #define PG8_SCHED __builtin_amdgcn_sched_barrier(0)
; template <class Epi, class Sched>
; __device__ __forceinline__ void gemm_phase(LAS unsigned char* lds, const Gemm g, const Sched& S, const Epi& E) {
;     ...
;             PG8_WAIT_V(8); PG8_WAIT_L(0); PG8_BAR; PG8_MMA(1, 0, At, B0); PG8_MMA(1, 1, At, B1); PG8_BAR; PG8_SCHED;
;             PG8_LDB(B0, 1, 0); PG8_LDB(B1, 1, 1); PG8_SCHED; PG8_LDA(At, 1, 0); PG8_STAGE(PG8_SA(0, 1), a2 + hstepA, voffA);
;             PG8_WAIT_V(8); PG8_WAIT_L(0); PG8_BAR; PG8_MMA(0, 0, At, B0); PG8_MMA(0, 1, At, B1); PG8_BAR; PG8_SCHED;
;             PG8_LDA(At, 1, 1); PG8_STAGE(PG8_SB(1, 0), b3, voffB); PG8_STAGE(PG8_SB(1, 1), b3 + hstepB, voffB); PG8_STAGE(PG8_SA(1, 0), a3, voffA);
;             PG8_WAIT_V(8); PG8_WAIT_L(0); PG8_BAR; PG8_MMA(1, 0, At, B0); PG8_MMA(1, 1, At, B1); PG8_BAR; PG8_SCHED;
	s_waitcnt lgkmcnt(0)
	v_mfma_f32_16x16x32_bf16 v[62:65], v[150:153], v[198:201], 0
	v_mfma_f32_16x16x32_bf16 v[58:61], v[158:161], v[198:201], 0
	v_mfma_f32_16x16x32_bf16 v[50:53], v[150:153], v[206:209], 0
	v_mfma_f32_16x16x32_bf16 v[42:45], v[158:161], v[206:209], 0
	v_mfma_f32_16x16x32_bf16 v[30:33], v[150:153], v[222:225], 0
	v_mfma_f32_16x16x32_bf16 v[26:29], v[158:161], v[222:225], 0
	v_mfma_f32_16x16x32_bf16 v[18:21], v[150:153], v[230:233], 0
	v_mfma_f32_16x16x32_bf16 v[10:13], v[158:161], v[230:233], 0
	v_mfma_f32_16x16x32_bf16 v[62:65], v[154:157], v[202:205], v[62:65]
	v_mfma_f32_16x16x32_bf16 v[58:61], v[162:165], v[202:205], v[58:61]
	v_mfma_f32_16x16x32_bf16 v[50:53], v[154:157], v[218:221], v[50:53]
	v_mfma_f32_16x16x32_bf16 v[42:45], v[162:165], v[218:221], v[42:45]
	v_mfma_f32_16x16x32_bf16 v[30:33], v[154:157], v[226:229], v[30:33]
	v_mfma_f32_16x16x32_bf16 v[26:29], v[162:165], v[226:229], v[26:29]
	v_mfma_f32_16x16x32_bf16 v[18:21], v[154:157], v[234:237], v[18:21]
	v_mfma_f32_16x16x32_bf16 v[10:13], v[162:165], v[234:237], v[10:13]
	v_mfma_f32_16x16x32_bf16 v[54:57], v[166:169], v[198:201], 0
	v_mfma_f32_16x16x32_bf16 v[46:49], v[190:193], v[198:201], 0
	v_mfma_f32_16x16x32_bf16 v[38:41], v[166:169], v[206:209], 0
	v_mfma_f32_16x16x32_bf16 v[34:37], v[190:193], v[206:209], 0
	v_mfma_f32_16x16x32_bf16 v[22:25], v[166:169], v[222:225], 0
	v_mfma_f32_16x16x32_bf16 v[14:17], v[190:193], v[222:225], 0
	v_mfma_f32_16x16x32_bf16 v[6:9], v[166:169], v[230:233], 0
	v_mfma_f32_16x16x32_bf16 v[2:5], v[190:193], v[230:233], 0
	v_mfma_f32_16x16x32_bf16 v[54:57], v[170:173], v[202:205], v[54:57]
	v_mfma_f32_16x16x32_bf16 v[46:49], v[194:197], v[202:205], v[46:49]
	v_mfma_f32_16x16x32_bf16 v[38:41], v[170:173], v[218:221], v[38:41]
	v_mfma_f32_16x16x32_bf16 v[34:37], v[194:197], v[218:221], v[34:37]
	v_mfma_f32_16x16x32_bf16 v[22:25], v[170:173], v[226:229], v[22:25]
	v_mfma_f32_16x16x32_bf16 v[14:17], v[194:197], v[226:229], v[14:17]
	v_mfma_f32_16x16x32_bf16 v[6:9], v[170:173], v[234:237], v[6:9]
	v_mfma_f32_16x16x32_bf16 v[2:5], v[194:197], v[234:237], v[2:5]
	s_barrier
	s_add_i32 s79, 0, 0x18000
	s_add_i32 s80, 0, 0x1c000
	s_add_u32 s20, s20, 0x40000
	s_addc_u32 s21, s21, 0
	s_mov_b32 m0, s29
	s_nop 0
	global_load_lds_dwordx4 v130, s[20:21]
	s_mov_b32 m0, s30
	s_nop 0
	global_load_lds_dwordx4 v134, s[20:21]
	ds_read_b128 v[150:153], v255 offset:32768
	ds_read_b128 v[154:157], v255 offset:33792
	ds_read_b128 v[158:161], v255 offset:34816
	ds_read_b128 v[162:165], v255 offset:35840
	ds_read_b128 v[166:169], v255 offset:49152
	ds_read_b128 v[170:173], v255 offset:50176
	ds_read_b128 v[190:193], v255 offset:51200
	ds_read_b128 v[194:197], v255 offset:52224
	ds_read_b128 v[198:201], v148 offset:32768
	ds_read_b128 v[202:205], v148 offset:33792
	ds_read_b128 v[206:209], v148 offset:34816
	ds_read_b128 v[218:221], v148 offset:35840
	ds_read_b128 v[222:225], v148 offset:36864
	ds_read_b128 v[226:229], v148 offset:37888
	ds_read_b128 v[230:233], v148 offset:38912
	ds_read_b128 v[234:237], v148 offset:39936
	s_waitcnt vmcnt(8)
	s_waitcnt lgkmcnt(0)
	s_barrier
	s_waitcnt lgkmcnt(0)
	v_mfma_f32_16x16x32_bf16 v[126:129], v[150:153], v[198:201], v[126:129]
	v_mfma_f32_16x16x32_bf16 v[122:125], v[158:161], v[198:201], v[122:125]
	v_mfma_f32_16x16x32_bf16 v[110:113], v[150:153], v[206:209], v[110:113]
	v_mfma_f32_16x16x32_bf16 v[106:109], v[158:161], v[206:209], v[106:109]
	v_mfma_f32_16x16x32_bf16 v[94:97], v[150:153], v[222:225], v[94:97]
	v_mfma_f32_16x16x32_bf16 v[90:93], v[158:161], v[222:225], v[90:93]
	v_mfma_f32_16x16x32_bf16 v[82:85], v[150:153], v[230:233], v[82:85]
	v_mfma_f32_16x16x32_bf16 v[74:77], v[158:161], v[230:233], v[74:77]
	v_mfma_f32_16x16x32_bf16 v[126:129], v[154:157], v[202:205], v[126:129]
	v_mfma_f32_16x16x32_bf16 v[122:125], v[162:165], v[202:205], v[122:125]
	v_mfma_f32_16x16x32_bf16 v[110:113], v[154:157], v[218:221], v[110:113]
	v_mfma_f32_16x16x32_bf16 v[106:109], v[162:165], v[218:221], v[106:109]
	v_mfma_f32_16x16x32_bf16 v[94:97], v[154:157], v[226:229], v[94:97]
	v_mfma_f32_16x16x32_bf16 v[90:93], v[162:165], v[226:229], v[90:93]
	v_mfma_f32_16x16x32_bf16 v[82:85], v[154:157], v[234:237], v[82:85]
	v_mfma_f32_16x16x32_bf16 v[74:77], v[162:165], v[234:237], v[74:77]
	v_mfma_f32_16x16x32_bf16 v[118:121], v[166:169], v[198:201], v[118:121]
	v_mfma_f32_16x16x32_bf16 v[114:117], v[190:193], v[198:201], v[114:117]
	v_mfma_f32_16x16x32_bf16 v[102:105], v[166:169], v[206:209], v[102:105]
	v_mfma_f32_16x16x32_bf16 v[98:101], v[190:193], v[206:209], v[98:101]
	v_mfma_f32_16x16x32_bf16 v[86:89], v[166:169], v[222:225], v[86:89]
	v_mfma_f32_16x16x32_bf16 v[78:81], v[190:193], v[222:225], v[78:81]
	v_mfma_f32_16x16x32_bf16 v[70:73], v[166:169], v[230:233], v[70:73]
	v_mfma_f32_16x16x32_bf16 v[66:69], v[190:193], v[230:233], v[66:69]
	v_mfma_f32_16x16x32_bf16 v[118:121], v[170:173], v[202:205], v[118:121]
	v_mfma_f32_16x16x32_bf16 v[114:117], v[194:197], v[202:205], v[114:117]
	v_mfma_f32_16x16x32_bf16 v[102:105], v[170:173], v[218:221], v[102:105]
	v_mfma_f32_16x16x32_bf16 v[98:101], v[194:197], v[218:221], v[98:101]
	v_mfma_f32_16x16x32_bf16 v[86:89], v[170:173], v[226:229], v[86:89]
	v_mfma_f32_16x16x32_bf16 v[78:81], v[194:197], v[226:229], v[78:81]
	v_mfma_f32_16x16x32_bf16 v[70:73], v[170:173], v[234:237], v[70:73]
	v_mfma_f32_16x16x32_bf16 v[66:69], v[194:197], v[234:237], v[66:69]
	s_barrier
; #define PG8_STAGE(bufoff, gbase, voff) do { _Pragma("unroll") for (int _i = 0; _i < 2; ++_i) \
;         __builtin_amdgcn_global_load_lds((const unsigned*)((const char*)(gbase) + (voff)[_i]), (LAS unsigned*)(lds + (bufoff) + ldsw + _i * 8192), 16, 0, 0); } while (0)
; #define PG8_LDA(dst, b, h) do { _Pragma("unroll") for (int m = 0; m < 4; ++m) _Pragma("unroll") for (int k = 0; k < 2; ++k) dst[m][k] = *(const LAS bf16x8*)(lds + PG8_SA(b, h) + aoff + m * 2048 + k * 1024); } while (0)
; #define PG8_LDB(dst, b, h) do { _Pragma("unroll") for (int n = 0; n < 2; ++n) _Pragma("unroll") for (int k = 0; k < 2; ++k) dst[n][k] = *(const LAS bf16x8*)(lds + PG8_SB(b, h) + boff + n * 2048 + k * 1024); } while (0)
; #define PG8_MMA(ai, bj, At, Bt) do { __builtin_amdgcn_s_setprio(1); _Pragma("unroll") for (int m = 0; m < 4; ++m) _Pragma("unroll") for (int n = 0; n < 2; ++n) _Pragma("unroll") for (int k = 0; k < 2; ++k) \
;         acc[ai][bj][m][n] = __builtin_amdgcn_mfma_f32_16x16x32_bf16(Bt[n][k], At[m][k], acc[ai][bj][m][n], 0, 0, 0); __builtin_amdgcn_s_setprio(0); } while (0)
; #define PG8_WAIT_V(n) asm volatile("s_waitcnt vmcnt(" #n ")" ::: "memory")
; #define PG8_WAIT_L(n) asm volatile("s_waitcnt lgkmcnt(" #n ")" ::: "memory")
; #define PG8_BAR __builtin_amdgcn_s_barrier()
; #define PG8_SCHED __builtin_amdgcn_sched_barrier(0)
; template <class Epi, class Sched>
; __device__ __forceinline__ void gemm_phase(LAS unsigned char* lds, const Gemm g, const Sched& S, const Epi& E) {
;     ...
;             const char* a1 = cA + (size_t)(t + 1) * kstep;
;             const char* a2 = last ? nA : cA + (size_t)(t + 2) * kstep; const char* b2 = last ? nB : cB + (size_t)(t + 2) * kstep;
;             const char* a3 = a2 + kstep; const char* b3 = b2 + kstep;
;             PG8_LDB(B0, 0, 0); PG8_LDB(B1, 0, 1); PG8_SCHED; PG8_LDA(At, 0, 0); PG8_STAGE(PG8_SA(1, 1), a1 + hstepA, voffA);
;             PG8_WAIT_V(8); PG8_WAIT_L(0); PG8_BAR; PG8_MMA(0, 0, At, B0); PG8_MMA(0, 1, At, B1); PG8_BAR; PG8_SCHED;
;     ...
;             PG8_LDA(At, 1, 1); PG8_STAGE(PG8_SB(1, 0), b3, voffB); PG8_STAGE(PG8_SB(1, 1), b3 + hstepB, voffB); PG8_STAGE(PG8_SA(1, 0), a3, voffA);
;             PG8_WAIT_V(8); PG8_WAIT_L(0); PG8_BAR; PG8_MMA(1, 0, At, B0); PG8_MMA(1, 1, At, B1); PG8_BAR; PG8_SCHED;
;         }
	s_add_i32 s20, s8, 0x18000
	s_add_u32 s80, s76, 0x80
	s_addc_u32 s81, s77, 0
	s_mov_b32 m0, s20
	ds_read_b128 v[198:201], v148 offset:49152
	ds_read_b128 v[202:205], v148 offset:50176
	ds_read_b128 v[206:209], v148 offset:51200
	ds_read_b128 v[218:221], v148 offset:52224
	ds_read_b128 v[222:225], v148 offset:53248
	ds_read_b128 v[226:229], v148 offset:54272
	ds_read_b128 v[230:233], v148 offset:55296
	ds_read_b128 v[234:237], v148 offset:56320
	global_load_lds_dwordx4 v132, s[80:81]
	s_add_i32 m0, s20, 0x2000
	s_add_u32 s20, s76, 0x40080
	s_addc_u32 s21, s77, 0
	s_add_i32 s12, s8, 0x1c000
	global_load_lds_dwordx4 v136, s[80:81]
	s_mov_b32 m0, s12
	s_nop 0
	global_load_lds_dwordx4 v132, s[20:21]
	s_add_i32 m0, s12, 0x2000
	s_nop 0
	global_load_lds_dwordx4 v136, s[20:21]
	s_mov_b32 m0, s31
	s_nop 0
	global_load_lds_dwordx4 v130, s[100:101]
	s_mov_b32 m0, s34
	s_nop 0
	global_load_lds_dwordx4 v134, s[100:101]
	s_waitcnt vmcnt(8)
	s_waitcnt lgkmcnt(0)
	s_barrier
	s_waitcnt lgkmcnt(0)
	v_mfma_f32_16x16x32_bf16 v[62:65], v[150:153], v[198:201], v[62:65]
	v_mfma_f32_16x16x32_bf16 v[58:61], v[158:161], v[198:201], v[58:61]
	v_mfma_f32_16x16x32_bf16 v[50:53], v[150:153], v[206:209], v[50:53]
	v_mfma_f32_16x16x32_bf16 v[42:45], v[158:161], v[206:209], v[42:45]
	v_mfma_f32_16x16x32_bf16 v[30:33], v[150:153], v[222:225], v[30:33]
	v_mfma_f32_16x16x32_bf16 v[26:29], v[158:161], v[222:225], v[26:29]
	v_mfma_f32_16x16x32_bf16 v[18:21], v[150:153], v[230:233], v[18:21]
	v_mfma_f32_16x16x32_bf16 v[10:13], v[158:161], v[230:233], v[10:13]
	v_mfma_f32_16x16x32_bf16 v[62:65], v[154:157], v[202:205], v[62:65]
	v_mfma_f32_16x16x32_bf16 v[58:61], v[162:165], v[202:205], v[58:61]
	v_mfma_f32_16x16x32_bf16 v[50:53], v[154:157], v[218:221], v[50:53]
	v_mfma_f32_16x16x32_bf16 v[42:45], v[162:165], v[218:221], v[42:45]
	v_mfma_f32_16x16x32_bf16 v[30:33], v[154:157], v[226:229], v[30:33]
	v_mfma_f32_16x16x32_bf16 v[26:29], v[162:165], v[226:229], v[26:29]
	v_mfma_f32_16x16x32_bf16 v[18:21], v[154:157], v[234:237], v[18:21]
	v_mfma_f32_16x16x32_bf16 v[10:13], v[162:165], v[234:237], v[10:13]
	v_mfma_f32_16x16x32_bf16 v[54:57], v[166:169], v[198:201], v[54:57]
	v_mfma_f32_16x16x32_bf16 v[46:49], v[190:193], v[198:201], v[46:49]
	v_mfma_f32_16x16x32_bf16 v[38:41], v[166:169], v[206:209], v[38:41]
	v_mfma_f32_16x16x32_bf16 v[34:37], v[190:193], v[206:209], v[34:37]
	v_mfma_f32_16x16x32_bf16 v[22:25], v[166:169], v[222:225], v[22:25]
	v_mfma_f32_16x16x32_bf16 v[14:17], v[190:193], v[222:225], v[14:17]
	v_mfma_f32_16x16x32_bf16 v[6:9], v[166:169], v[230:233], v[6:9]
	v_mfma_f32_16x16x32_bf16 v[2:5], v[190:193], v[230:233], v[2:5]
	v_mfma_f32_16x16x32_bf16 v[54:57], v[170:173], v[202:205], v[54:57]
	v_mfma_f32_16x16x32_bf16 v[46:49], v[194:197], v[202:205], v[46:49]
	v_mfma_f32_16x16x32_bf16 v[38:41], v[170:173], v[218:221], v[38:41]
	v_mfma_f32_16x16x32_bf16 v[34:37], v[194:197], v[218:221], v[34:37]
	v_mfma_f32_16x16x32_bf16 v[22:25], v[170:173], v[226:229], v[22:25]
	v_mfma_f32_16x16x32_bf16 v[14:17], v[194:197], v[226:229], v[14:17]
	v_mfma_f32_16x16x32_bf16 v[6:9], v[170:173], v[234:237], v[6:9]
	v_mfma_f32_16x16x32_bf16 v[2:5], v[194:197], v[234:237], v[2:5]
	s_barrier
	s_add_i32 s78, s78, 2
	s_add_u32 s18, s18, 0x100
	s_addc_u32 s19, s19, 0
	s_add_u32 s69, s69, 0x100
	s_addc_u32 s71, s71, 0
	s_cmp_gt_u32 s78, 13
.LBB0_349:
	s_add_u32 s20, s18, 0xfffc0080
	s_addc_u32 s21, s19, -1
	s_add_i32 s79, 0, 0x10000
	s_cmp_eq_u32 s78, 12
	s_cselect_b32 s21, s48, s21
	s_cselect_b32 s20, s49, s20
	s_cselect_b32 s77, s53, s71
	s_cselect_b32 s76, s54, s69
	s_add_u32 s100, s20, 0x80
	s_addc_u32 s101, s21, 0
	s_add_i32 s82, 0, 0x14000
	s_add_i32 m0, s9, 0xc000
	s_nop 0
	global_load_lds_dwordx4 v130, s[18:19]
	s_add_i32 m0, s9, 0xe000
	s_nop 0
	global_load_lds_dwordx4 v134, s[18:19]
	ds_read_b128 v[150:153], v255
	ds_read_b128 v[154:157], v255 offset:1024
	ds_read_b128 v[158:161], v255 offset:2048
	ds_read_b128 v[162:165], v255 offset:3072
	ds_read_b128 v[166:169], v255 offset:16384
	ds_read_b128 v[170:173], v255 offset:17408
	ds_read_b128 v[190:193], v255 offset:18432
	ds_read_b128 v[194:197], v255 offset:19456
	ds_read_b128 v[198:201], v148
	ds_read_b128 v[202:205], v148 offset:1024
	ds_read_b128 v[206:209], v148 offset:2048
	ds_read_b128 v[218:221], v148 offset:3072
	ds_read_b128 v[222:225], v148 offset:4096
	ds_read_b128 v[226:229], v148 offset:5120
	ds_read_b128 v[230:233], v148 offset:6144
	ds_read_b128 v[234:237], v148 offset:7168
	s_waitcnt vmcnt(8)
	s_waitcnt lgkmcnt(0)
	s_barrier
; #define PG8_STAGE(bufoff, gbase, voff) do { _Pragma("unroll") for (int _i = 0; _i < 2; ++_i) \
;         __builtin_amdgcn_global_load_lds((const unsigned*)((const char*)(gbase) + (voff)[_i]), (LAS unsigned*)(lds + (bufoff) + ldsw + _i * 8192), 16, 0, 0); } while (0)
; #define PG8_LDA(dst, b, h) do { _Pragma("unroll") for (int m = 0; m < 4; ++m) _Pragma("unroll") for (int k = 0; k < 2; ++k) dst[m][k] = *(const LAS bf16x8*)(lds + PG8_SA(b, h) + aoff + m * 2048 + k * 1024); } while (0)
; #define PG8_LDB(dst, b, h) do { _Pragma("unroll") for (int n = 0; n < 2; ++n) _Pragma("unroll") for (int k = 0; k < 2; ++k) dst[n][k] = *(const LAS bf16x8*)(lds + PG8_SB(b, h) + boff + n * 2048 + k * 1024); } while (0)
; #define PG8_MMA(ai, bj, At, Bt) do { __builtin_amdgcn_s_setprio(1); _Pragma("unroll") for (int m = 0; m < 4; ++m) _Pragma("unroll") for (int n = 0; n < 2; ++n) _Pragma("unroll") for (int k = 0; k < 2; ++k) \
;         acc[ai][bj][m][n] = __builtin_amdgcn_mfma_f32_16x16x32_bf16(Bt[n][k], At[m][k], acc[ai][bj][m][n], 0, 0, 0); __builtin_amdgcn_s_setprio(0); } while (0)
; #define PG8_WAIT_V(n) asm volatile("s_waitcnt vmcnt(" #n ")" ::: "memory")
; #define PG8_WAIT_L(n) asm volatile("s_waitcnt lgkmcnt(" #n ")" ::: "memory")
; #define PG8_BAR __builtin_amdgcn_s_barrier()
; #define PG8_SCHED __builtin_amdgcn_sched_barrier(0)
; template <class Epi, class Sched>
; __device__ __forceinline__ void gemm_phase(LAS unsigned char* lds, const Gemm g, const Sched& S, const Epi& E) {
;     ...
;             PG8_WAIT_V(8); PG8_WAIT_L(0); PG8_BAR; PG8_MMA(0, 0, At, B0); PG8_MMA(0, 1, At, B1); PG8_BAR; PG8_SCHED;
;             PG8_LDA(At, 0, 1); PG8_STAGE(PG8_SB(0, 0), b2, voffB); PG8_STAGE(PG8_SB(0, 1), b2 + hstepB, voffB); PG8_STAGE(PG8_SA(0, 0), a2, voffA);
;             PG8_WAIT_V(8); PG8_WAIT_L(0); PG8_BAR; PG8_MMA(1, 0, At, B0); PG8_MMA(1, 1, At, B1); PG8_BAR; PG8_SCHED;
;             PG8_LDB(B0, 1, 0); PG8_LDB(B1, 1, 1); PG8_SCHED; PG8_LDA(At, 1, 0); PG8_STAGE(PG8_SA(0, 1), a2 + hstepA, voffA);
;             PG8_WAIT_V(8); PG8_WAIT_L(0); PG8_BAR; PG8_MMA(0, 0, At, B0); PG8_MMA(0, 1, At, B1); PG8_BAR; PG8_SCHED;
	s_waitcnt lgkmcnt(0)
	v_mfma_f32_16x16x32_bf16 v[126:129], v[150:153], v[198:201], v[126:129]
	v_mfma_f32_16x16x32_bf16 v[122:125], v[158:161], v[198:201], v[122:125]
	v_mfma_f32_16x16x32_bf16 v[110:113], v[150:153], v[206:209], v[110:113]
	v_mfma_f32_16x16x32_bf16 v[106:109], v[158:161], v[206:209], v[106:109]
	v_mfma_f32_16x16x32_bf16 v[94:97], v[150:153], v[222:225], v[94:97]
	v_mfma_f32_16x16x32_bf16 v[90:93], v[158:161], v[222:225], v[90:93]
	v_mfma_f32_16x16x32_bf16 v[82:85], v[150:153], v[230:233], v[82:85]
	v_mfma_f32_16x16x32_bf16 v[74:77], v[158:161], v[230:233], v[74:77]
	v_mfma_f32_16x16x32_bf16 v[126:129], v[154:157], v[202:205], v[126:129]
	v_mfma_f32_16x16x32_bf16 v[122:125], v[162:165], v[202:205], v[122:125]
	v_mfma_f32_16x16x32_bf16 v[110:113], v[154:157], v[218:221], v[110:113]
	v_mfma_f32_16x16x32_bf16 v[106:109], v[162:165], v[218:221], v[106:109]
	v_mfma_f32_16x16x32_bf16 v[94:97], v[154:157], v[226:229], v[94:97]
	v_mfma_f32_16x16x32_bf16 v[90:93], v[162:165], v[226:229], v[90:93]
	v_mfma_f32_16x16x32_bf16 v[82:85], v[154:157], v[234:237], v[82:85]
	v_mfma_f32_16x16x32_bf16 v[74:77], v[162:165], v[234:237], v[74:77]
	v_mfma_f32_16x16x32_bf16 v[118:121], v[166:169], v[198:201], v[118:121]
	v_mfma_f32_16x16x32_bf16 v[114:117], v[190:193], v[198:201], v[114:117]
	v_mfma_f32_16x16x32_bf16 v[102:105], v[166:169], v[206:209], v[102:105]
	v_mfma_f32_16x16x32_bf16 v[98:101], v[190:193], v[206:209], v[98:101]
	v_mfma_f32_16x16x32_bf16 v[86:89], v[166:169], v[222:225], v[86:89]
	v_mfma_f32_16x16x32_bf16 v[78:81], v[190:193], v[222:225], v[78:81]
	v_mfma_f32_16x16x32_bf16 v[70:73], v[166:169], v[230:233], v[70:73]
	v_mfma_f32_16x16x32_bf16 v[66:69], v[190:193], v[230:233], v[66:69]
	v_mfma_f32_16x16x32_bf16 v[118:121], v[170:173], v[202:205], v[118:121]
	v_mfma_f32_16x16x32_bf16 v[114:117], v[194:197], v[202:205], v[114:117]
	v_mfma_f32_16x16x32_bf16 v[102:105], v[170:173], v[218:221], v[102:105]
	v_mfma_f32_16x16x32_bf16 v[98:101], v[194:197], v[218:221], v[98:101]
	v_mfma_f32_16x16x32_bf16 v[86:89], v[170:173], v[226:229], v[86:89]
	v_mfma_f32_16x16x32_bf16 v[78:81], v[194:197], v[226:229], v[78:81]
	v_mfma_f32_16x16x32_bf16 v[70:73], v[170:173], v[234:237], v[70:73]
	v_mfma_f32_16x16x32_bf16 v[66:69], v[194:197], v[234:237], v[66:69]
	s_barrier
	s_add_i32 s79, s79, s8
	s_mov_b32 m0, s79
	ds_read_b128 v[198:201], v148 offset:16384
	ds_read_b128 v[202:205], v148 offset:17408
	ds_read_b128 v[206:209], v148 offset:18432
	ds_read_b128 v[218:221], v148 offset:19456
	ds_read_b128 v[222:225], v148 offset:20480
	ds_read_b128 v[226:229], v148 offset:21504
	ds_read_b128 v[230:233], v148 offset:22528
	ds_read_b128 v[234:237], v148 offset:23552
	global_load_lds_dwordx4 v132, s[76:77]
	s_add_i32 m0, s79, 0x2000
	s_add_u32 s80, s76, 0x40000
	s_addc_u32 s81, s77, 0
	s_add_i32 s79, s82, s8
	global_load_lds_dwordx4 v136, s[76:77]
	s_mov_b32 m0, s79
	s_nop 0
	global_load_lds_dwordx4 v132, s[80:81]
	s_add_i32 m0, s79, 0x2000
	s_nop 0
	global_load_lds_dwordx4 v136, s[80:81]
	s_mov_b32 m0, s9
	s_nop 0
	global_load_lds_dwordx4 v130, s[20:21]
	s_mov_b32 m0, s28
	s_nop 0
	global_load_lds_dwordx4 v134, s[20:21]
	s_waitcnt vmcnt(8)
	s_waitcnt lgkmcnt(0)
	s_barrier
	s_waitcnt lgkmcnt(0)
	v_mfma_f32_16x16x32_bf16 v[62:65], v[150:153], v[198:201], v[62:65]
	v_mfma_f32_16x16x32_bf16 v[58:61], v[158:161], v[198:201], v[58:61]
	v_mfma_f32_16x16x32_bf16 v[50:53], v[150:153], v[206:209], v[50:53]
	v_mfma_f32_16x16x32_bf16 v[42:45], v[158:161], v[206:209], v[42:45]
	v_mfma_f32_16x16x32_bf16 v[30:33], v[150:153], v[222:225], v[30:33]
	v_mfma_f32_16x16x32_bf16 v[26:29], v[158:161], v[222:225], v[26:29]
	v_mfma_f32_16x16x32_bf16 v[18:21], v[150:153], v[230:233], v[18:21]
	v_mfma_f32_16x16x32_bf16 v[10:13], v[158:161], v[230:233], v[10:13]
	v_mfma_f32_16x16x32_bf16 v[62:65], v[154:157], v[202:205], v[62:65]
	v_mfma_f32_16x16x32_bf16 v[58:61], v[162:165], v[202:205], v[58:61]
	v_mfma_f32_16x16x32_bf16 v[50:53], v[154:157], v[218:221], v[50:53]
	v_mfma_f32_16x16x32_bf16 v[42:45], v[162:165], v[218:221], v[42:45]
	v_mfma_f32_16x16x32_bf16 v[30:33], v[154:157], v[226:229], v[30:33]
	v_mfma_f32_16x16x32_bf16 v[26:29], v[162:165], v[226:229], v[26:29]
	v_mfma_f32_16x16x32_bf16 v[18:21], v[154:157], v[234:237], v[18:21]
	v_mfma_f32_16x16x32_bf16 v[10:13], v[162:165], v[234:237], v[10:13]
	v_mfma_f32_16x16x32_bf16 v[54:57], v[166:169], v[198:201], v[54:57]
	v_mfma_f32_16x16x32_bf16 v[46:49], v[190:193], v[198:201], v[46:49]
	v_mfma_f32_16x16x32_bf16 v[38:41], v[166:169], v[206:209], v[38:41]
	v_mfma_f32_16x16x32_bf16 v[34:37], v[190:193], v[206:209], v[34:37]
	v_mfma_f32_16x16x32_bf16 v[22:25], v[166:169], v[222:225], v[22:25]
	v_mfma_f32_16x16x32_bf16 v[14:17], v[190:193], v[222:225], v[14:17]
	v_mfma_f32_16x16x32_bf16 v[6:9], v[166:169], v[230:233], v[6:9]
	v_mfma_f32_16x16x32_bf16 v[2:5], v[190:193], v[230:233], v[2:5]
	v_mfma_f32_16x16x32_bf16 v[54:57], v[170:173], v[202:205], v[54:57]
	v_mfma_f32_16x16x32_bf16 v[46:49], v[194:197], v[202:205], v[46:49]
	v_mfma_f32_16x16x32_bf16 v[38:41], v[170:173], v[218:221], v[38:41]
	v_mfma_f32_16x16x32_bf16 v[34:37], v[194:197], v[218:221], v[34:37]
	v_mfma_f32_16x16x32_bf16 v[22:25], v[170:173], v[226:229], v[22:25]
	v_mfma_f32_16x16x32_bf16 v[14:17], v[194:197], v[226:229], v[14:17]
	v_mfma_f32_16x16x32_bf16 v[6:9], v[170:173], v[234:237], v[6:9]
	v_mfma_f32_16x16x32_bf16 v[2:5], v[194:197], v[234:237], v[2:5]
	s_barrier
; #define PG8_STAGE(bufoff, gbase, voff) do { _Pragma("unroll") for (int _i = 0; _i < 2; ++_i) \
;         __builtin_amdgcn_global_load_lds((const unsigned*)((const char*)(gbase) + (voff)[_i]), (LAS unsigned*)(lds + (bufoff) + ldsw + _i * 8192), 16, 0, 0); } while (0)
; #define PG8_LDA(dst, b, h) do { _Pragma("unroll") for (int m = 0; m < 4; ++m) _Pragma("unroll") for (int k = 0; k < 2; ++k) dst[m][k] = *(const LAS bf16x8*)(lds + PG8_SA(b, h) + aoff + m * 2048 + k * 1024); } while (0)
; #define PG8_LDB(dst, b, h) do { _Pragma("unroll") for (int n = 0; n < 2; ++n) _Pragma("unroll") for (int k = 0; k < 2; ++k) dst[n][k] = *(const LAS bf16x8*)(lds + PG8_SB(b, h) + boff + n * 2048 + k * 1024); } while (0)
; #define PG8_MMA(ai, bj, At, Bt) do { __builtin_amdgcn_s_setprio(1); _Pragma("unroll") for (int m = 0; m < 4; ++m) _Pragma("unroll") for (int n = 0; n < 2; ++n) _Pragma("unroll") for (int k = 0; k < 2; ++k) \
;         acc[ai][bj][m][n] = __builtin_amdgcn_mfma_f32_16x16x32_bf16(Bt[n][k], At[m][k], acc[ai][bj][m][n], 0, 0, 0); __builtin_amdgcn_s_setprio(0); } while (0)
; #define PG8_WAIT_V(n) asm volatile("s_waitcnt vmcnt(" #n ")" ::: "memory")
; #define PG8_WAIT_L(n) asm volatile("s_waitcnt lgkmcnt(" #n ")" ::: "memory")
; #define PG8_BAR __builtin_amdgcn_s_barrier()
; #define PG8_SCHED __builtin_amdgcn_sched_barrier(0)
; template <class Epi, class Sched>
; __device__ __forceinline__ void gemm_phase(LAS unsigned char* lds, const Gemm g, const Sched& S, const Epi& E) {
;     ...
;             PG8_LDB(B0, 1, 0); PG8_LDB(B1, 1, 1); PG8_SCHED; PG8_LDA(At, 1, 0); PG8_STAGE(PG8_SA(0, 1), a2 + hstepA, voffA);
;             PG8_WAIT_V(8); PG8_WAIT_L(0); PG8_BAR; PG8_MMA(0, 0, At, B0); PG8_MMA(0, 1, At, B1); PG8_BAR; PG8_SCHED;
;             PG8_LDA(At, 1, 1); PG8_STAGE(PG8_SB(1, 0), b3, voffB); PG8_STAGE(PG8_SB(1, 1), b3 + hstepB, voffB); PG8_STAGE(PG8_SA(1, 0), a3, voffA);
;             PG8_WAIT_V(8); PG8_WAIT_L(0); PG8_BAR; PG8_MMA(1, 0, At, B0); PG8_MMA(1, 1, At, B1); PG8_BAR; PG8_SCHED;
;         }
	s_add_i32 s79, 0, 0x18000
	s_add_i32 s80, 0, 0x1c000
	s_add_u32 s20, s20, 0x40000
	s_addc_u32 s21, s21, 0
	s_mov_b32 m0, s29
	s_nop 0
	global_load_lds_dwordx4 v130, s[20:21]
	s_mov_b32 m0, s30
	s_nop 0
	global_load_lds_dwordx4 v134, s[20:21]
	ds_read_b128 v[150:153], v255 offset:32768
	ds_read_b128 v[154:157], v255 offset:33792
	ds_read_b128 v[158:161], v255 offset:34816
	ds_read_b128 v[162:165], v255 offset:35840
	ds_read_b128 v[166:169], v255 offset:49152
	ds_read_b128 v[170:173], v255 offset:50176
	ds_read_b128 v[190:193], v255 offset:51200
	ds_read_b128 v[194:197], v255 offset:52224
	ds_read_b128 v[198:201], v148 offset:32768
	ds_read_b128 v[202:205], v148 offset:33792
	ds_read_b128 v[206:209], v148 offset:34816
	ds_read_b128 v[218:221], v148 offset:35840
	ds_read_b128 v[222:225], v148 offset:36864
	ds_read_b128 v[226:229], v148 offset:37888
	ds_read_b128 v[230:233], v148 offset:38912
	ds_read_b128 v[234:237], v148 offset:39936
	s_waitcnt vmcnt(8)
	s_waitcnt lgkmcnt(0)
	s_barrier
	s_waitcnt lgkmcnt(0)
	v_mfma_f32_16x16x32_bf16 v[126:129], v[150:153], v[198:201], v[126:129]
	v_mfma_f32_16x16x32_bf16 v[122:125], v[158:161], v[198:201], v[122:125]
	v_mfma_f32_16x16x32_bf16 v[110:113], v[150:153], v[206:209], v[110:113]
	v_mfma_f32_16x16x32_bf16 v[106:109], v[158:161], v[206:209], v[106:109]
	v_mfma_f32_16x16x32_bf16 v[94:97], v[150:153], v[222:225], v[94:97]
	v_mfma_f32_16x16x32_bf16 v[90:93], v[158:161], v[222:225], v[90:93]
	v_mfma_f32_16x16x32_bf16 v[82:85], v[150:153], v[230:233], v[82:85]
	v_mfma_f32_16x16x32_bf16 v[74:77], v[158:161], v[230:233], v[74:77]
	v_mfma_f32_16x16x32_bf16 v[126:129], v[154:157], v[202:205], v[126:129]
	v_mfma_f32_16x16x32_bf16 v[122:125], v[162:165], v[202:205], v[122:125]
	v_mfma_f32_16x16x32_bf16 v[110:113], v[154:157], v[218:221], v[110:113]
	v_mfma_f32_16x16x32_bf16 v[106:109], v[162:165], v[218:221], v[106:109]
	v_mfma_f32_16x16x32_bf16 v[94:97], v[154:157], v[226:229], v[94:97]
	v_mfma_f32_16x16x32_bf16 v[90:93], v[162:165], v[226:229], v[90:93]
	v_mfma_f32_16x16x32_bf16 v[82:85], v[154:157], v[234:237], v[82:85]
	v_mfma_f32_16x16x32_bf16 v[74:77], v[162:165], v[234:237], v[74:77]
	v_mfma_f32_16x16x32_bf16 v[118:121], v[166:169], v[198:201], v[118:121]
	v_mfma_f32_16x16x32_bf16 v[114:117], v[190:193], v[198:201], v[114:117]
	v_mfma_f32_16x16x32_bf16 v[102:105], v[166:169], v[206:209], v[102:105]
	v_mfma_f32_16x16x32_bf16 v[98:101], v[190:193], v[206:209], v[98:101]
	v_mfma_f32_16x16x32_bf16 v[86:89], v[166:169], v[222:225], v[86:89]
	v_mfma_f32_16x16x32_bf16 v[78:81], v[190:193], v[222:225], v[78:81]
	v_mfma_f32_16x16x32_bf16 v[70:73], v[166:169], v[230:233], v[70:73]
	v_mfma_f32_16x16x32_bf16 v[66:69], v[190:193], v[230:233], v[66:69]
	v_mfma_f32_16x16x32_bf16 v[118:121], v[170:173], v[202:205], v[118:121]
	v_mfma_f32_16x16x32_bf16 v[114:117], v[194:197], v[202:205], v[114:117]
	v_mfma_f32_16x16x32_bf16 v[102:105], v[170:173], v[218:221], v[102:105]
	v_mfma_f32_16x16x32_bf16 v[98:101], v[194:197], v[218:221], v[98:101]
	v_mfma_f32_16x16x32_bf16 v[86:89], v[170:173], v[226:229], v[86:89]
	v_mfma_f32_16x16x32_bf16 v[78:81], v[194:197], v[226:229], v[78:81]
	v_mfma_f32_16x16x32_bf16 v[70:73], v[170:173], v[234:237], v[70:73]
	v_mfma_f32_16x16x32_bf16 v[66:69], v[194:197], v[234:237], v[66:69]
	s_barrier
	s_add_i32 s20, s8, 0x18000
	s_add_u32 s80, s76, 0x80
	s_addc_u32 s81, s77, 0
	s_mov_b32 m0, s20
	ds_read_b128 v[198:201], v148 offset:49152
	ds_read_b128 v[202:205], v148 offset:50176
	ds_read_b128 v[206:209], v148 offset:51200
	ds_read_b128 v[218:221], v148 offset:52224
	ds_read_b128 v[222:225], v148 offset:53248
	ds_read_b128 v[226:229], v148 offset:54272
	ds_read_b128 v[230:233], v148 offset:55296
	ds_read_b128 v[234:237], v148 offset:56320
	global_load_lds_dwordx4 v132, s[80:81]
	s_add_i32 m0, s20, 0x2000
	s_add_u32 s20, s76, 0x40080
	s_addc_u32 s21, s77, 0
	s_add_i32 s12, s8, 0x1c000
	global_load_lds_dwordx4 v136, s[80:81]
	s_mov_b32 m0, s12
	s_nop 0
	global_load_lds_dwordx4 v132, s[20:21]
	s_add_i32 m0, s12, 0x2000
	s_nop 0
	global_load_lds_dwordx4 v136, s[20:21]
	s_mov_b32 m0, s31
	s_nop 0
	global_load_lds_dwordx4 v130, s[100:101]
	s_mov_b32 m0, s34
	s_nop 0
	global_load_lds_dwordx4 v134, s[100:101]
	s_waitcnt vmcnt(8)
	s_waitcnt lgkmcnt(0)
	s_barrier
	s_waitcnt lgkmcnt(0)
	v_mfma_f32_16x16x32_bf16 v[62:65], v[150:153], v[198:201], v[62:65]
	v_mfma_f32_16x16x32_bf16 v[58:61], v[158:161], v[198:201], v[58:61]
	v_mfma_f32_16x16x32_bf16 v[50:53], v[150:153], v[206:209], v[50:53]
	v_mfma_f32_16x16x32_bf16 v[42:45], v[158:161], v[206:209], v[42:45]
	v_mfma_f32_16x16x32_bf16 v[30:33], v[150:153], v[222:225], v[30:33]
	v_mfma_f32_16x16x32_bf16 v[26:29], v[158:161], v[222:225], v[26:29]
	v_mfma_f32_16x16x32_bf16 v[18:21], v[150:153], v[230:233], v[18:21]
	v_mfma_f32_16x16x32_bf16 v[10:13], v[158:161], v[230:233], v[10:13]
	v_mfma_f32_16x16x32_bf16 v[62:65], v[154:157], v[202:205], v[62:65]
	v_mfma_f32_16x16x32_bf16 v[58:61], v[162:165], v[202:205], v[58:61]
	v_mfma_f32_16x16x32_bf16 v[50:53], v[154:157], v[218:221], v[50:53]
	v_mfma_f32_16x16x32_bf16 v[42:45], v[162:165], v[218:221], v[42:45]
	v_mfma_f32_16x16x32_bf16 v[30:33], v[154:157], v[226:229], v[30:33]
	v_mfma_f32_16x16x32_bf16 v[26:29], v[162:165], v[226:229], v[26:29]
	v_mfma_f32_16x16x32_bf16 v[18:21], v[154:157], v[234:237], v[18:21]
	v_mfma_f32_16x16x32_bf16 v[10:13], v[162:165], v[234:237], v[10:13]
	v_mfma_f32_16x16x32_bf16 v[54:57], v[166:169], v[198:201], v[54:57]
	v_mfma_f32_16x16x32_bf16 v[46:49], v[190:193], v[198:201], v[46:49]
	v_mfma_f32_16x16x32_bf16 v[38:41], v[166:169], v[206:209], v[38:41]
	v_mfma_f32_16x16x32_bf16 v[34:37], v[190:193], v[206:209], v[34:37]
	v_mfma_f32_16x16x32_bf16 v[22:25], v[166:169], v[222:225], v[22:25]
	v_mfma_f32_16x16x32_bf16 v[14:17], v[190:193], v[222:225], v[14:17]
	v_mfma_f32_16x16x32_bf16 v[6:9], v[166:169], v[230:233], v[6:9]
	v_mfma_f32_16x16x32_bf16 v[2:5], v[190:193], v[230:233], v[2:5]
	v_mfma_f32_16x16x32_bf16 v[54:57], v[170:173], v[202:205], v[54:57]
	v_mfma_f32_16x16x32_bf16 v[46:49], v[194:197], v[202:205], v[46:49]
	v_mfma_f32_16x16x32_bf16 v[38:41], v[170:173], v[218:221], v[38:41]
	v_mfma_f32_16x16x32_bf16 v[34:37], v[194:197], v[218:221], v[34:37]
	v_mfma_f32_16x16x32_bf16 v[22:25], v[170:173], v[226:229], v[22:25]
	v_mfma_f32_16x16x32_bf16 v[14:17], v[194:197], v[226:229], v[14:17]
	v_mfma_f32_16x16x32_bf16 v[6:9], v[170:173], v[234:237], v[6:9]
	v_mfma_f32_16x16x32_bf16 v[2:5], v[194:197], v[234:237], v[2:5]
	s_barrier
	s_add_i32 s78, s78, 2
	s_add_u32 s18, s18, 0x100
	s_addc_u32 s19, s19, 0
	s_add_u32 s69, s69, 0x100
	s_addc_u32 s71, s71, 0
	s_cmp_gt_u32 s78, 13
	s_cbranch_scc0 .LBB0_349
	s_and_b64 vcc, exec, s[36:37]
	s_cbranch_vccz .LBB0_352
	s_barrier

; #define PG8_STAGE(bufoff, gbase, voff) do { _Pragma("unroll") for (int _i = 0; _i < 2; ++_i) \
;         __builtin_amdgcn_global_load_lds((const unsigned*)((const char*)(gbase) + (voff)[_i]), (LAS unsigned*)(lds + (bufoff) + ldsw + _i * 8192), 16, 0, 0); } while (0)
; #define PG8_LDA(dst, b, h) do { _Pragma("unroll") for (int m = 0; m < 4; ++m) _Pragma("unroll") for (int k = 0; k < 2; ++k) dst[m][k] = *(const LAS bf16x8*)(lds + PG8_SA(b, h) + aoff + m * 2048 + k * 1024); } while (0)
; #define PG8_LDB(dst, b, h) do { _Pragma("unroll") for (int n = 0; n < 2; ++n) _Pragma("unroll") for (int k = 0; k < 2; ++k) dst[n][k] = *(const LAS bf16x8*)(lds + PG8_SB(b, h) + boff + n * 2048 + k * 1024); } while (0)
; #define PG8_MMA(ai, bj, At, Bt) do { __builtin_amdgcn_s_setprio(1); _Pragma("unroll") for (int m = 0; m < 4; ++m) _Pragma("unroll") for (int n = 0; n < 2; ++n) _Pragma("unroll") for (int k = 0; k < 2; ++k) \
;         acc[ai][bj][m][n] = __builtin_amdgcn_mfma_f32_16x16x32_bf16(Bt[n][k], At[m][k], acc[ai][bj][m][n], 0, 0, 0); __builtin_amdgcn_s_setprio(0); } while (0)
; #define PG8_WAIT_V(n) asm volatile("s_waitcnt vmcnt(" #n ")" ::: "memory")
; template <class Epi, class Sched>
; __device__ __forceinline__ void gemm_phase(LAS unsigned char* lds, const Gemm g, const Sched& S, const Epi& E) {
;     ...
;         const char* nA = has_next ? (const char*)g.A + (size_t)nxt.pm * tstepA + (size_t)nxt.pn * g.a_pn_off * 2 : cA; const char* nB = has_next ? (const char*)g.Bt + (size_t)nxt.pn * tstepB : cB;
;         for (int t = 0; t < nt; t += 2) {
;             const bool last = (t == nt - 2);
;             const char* a1 = cA + (size_t)(t + 1) * kstep;
;             const char* a2 = last ? nA : cA + (size_t)(t + 2) * kstep; const char* b2 = last ? nB : cB + (size_t)(t + 2) * kstep;
;             const char* a3 = a2 + kstep; const char* b3 = b2 + kstep;
;             PG8_LDB(B0, 0, 0); PG8_LDB(B1, 0, 1); PG8_SCHED; PG8_LDA(At, 0, 0); PG8_STAGE(PG8_SA(1, 1), a1 + hstepA, voffA);
;             PG8_WAIT_V(8); PG8_WAIT_L(0); PG8_BAR; PG8_MMA(0, 0, At, B0); PG8_MMA(0, 1, At, B1); PG8_BAR; PG8_SCHED;
;             PG8_LDA(At, 0, 1); PG8_STAGE(PG8_SB(0, 0), b2, voffB); PG8_STAGE(PG8_SB(0, 1), b2 + hstepB, voffB); PG8_STAGE(PG8_SA(0, 0), a2, voffA);
;             PG8_WAIT_V(8); PG8_WAIT_L(0); PG8_BAR; PG8_MMA(1, 0, At, B0); PG8_MMA(1, 1, At, B1); PG8_BAR; PG8_SCHED;
.LBB0_377:
	s_ashr_i32 s71, s70, 31
	s_lshl_b64 s[48:49], s[70:71], 19
	v_readlane_b32 s12, v248, 21
	s_add_u32 s72, s12, s48
	v_readlane_b32 s12, v248, 22
	s_addc_u32 s73, s12, s49
	s_and_b64 s[48:49], s[66:67], exec
	s_cselect_b32 s43, s73, s19
	s_cselect_b32 s48, s72, s18
	s_ashr_i32 s69, s68, 31
	s_lshl_b64 s[74:75], s[68:69], 19
	s_add_u32 s74, s4, s74
	s_addc_u32 s75, s5, s75
	s_and_b64 s[76:77], s[66:67], exec
	s_cselect_b32 s49, s75, s21
	s_cselect_b32 s53, s74, s20
	s_add_u32 s18, s18, 0x40080
	s_addc_u32 s19, s19, 0
	s_add_u32 s69, s20, 0x100
	s_addc_u32 s71, s21, 0
	s_mov_b32 s78, -2
	v_add_u32_e32 v255, 0x10000, v158
	s_add_u32 s20, s18, 0xfffc0080
	s_addc_u32 s21, s19, -1
	s_add_i32 s79, 0, 0x10000
	s_cmp_eq_u32 s78, 12
	s_cselect_b32 s21, s43, s21
	s_cselect_b32 s20, s48, s20
	s_cselect_b32 s77, s49, s71
	s_cselect_b32 s76, s53, s69
	s_add_u32 s100, s20, 0x80
	s_addc_u32 s101, s21, 0
	s_add_i32 s82, 0, 0x14000
	s_add_i32 m0, s9, 0xc000
	s_nop 0
	global_load_lds_dwordx4 v146, s[18:19]
	s_add_i32 m0, s9, 0xe000
	s_nop 0
	global_load_lds_dwordx4 v150, s[18:19]
	ds_read_b128 v[130:133], v255
	ds_read_b128 v[134:137], v255 offset:1024
	ds_read_b128 v[138:141], v255 offset:2048
	ds_read_b128 v[142:145], v255 offset:3072
	ds_read_b128 v[162:165], v255 offset:16384
	ds_read_b128 v[166:169], v255 offset:17408
	ds_read_b128 v[170:173], v255 offset:18432
	ds_read_b128 v[190:193], v255 offset:19456
	ds_read_b128 v[194:197], v160
	ds_read_b128 v[198:201], v160 offset:1024
	ds_read_b128 v[202:205], v160 offset:2048
	ds_read_b128 v[206:209], v160 offset:3072
	ds_read_b128 v[218:221], v160 offset:4096
	ds_read_b128 v[222:225], v160 offset:5120
	ds_read_b128 v[226:229], v160 offset:6144
	ds_read_b128 v[230:233], v160 offset:7168
	s_waitcnt vmcnt(8)
	s_waitcnt lgkmcnt(0)
	s_barrier
	s_waitcnt lgkmcnt(0)
	v_mfma_f32_16x16x32_bf16 v[126:129], v[130:133], v[194:197], 0
	v_mfma_f32_16x16x32_bf16 v[122:125], v[138:141], v[194:197], 0
	v_mfma_f32_16x16x32_bf16 v[118:121], v[130:133], v[202:205], 0
	v_mfma_f32_16x16x32_bf16 v[110:113], v[138:141], v[202:205], 0
	v_mfma_f32_16x16x32_bf16 v[102:105], v[130:133], v[218:221], 0
	v_mfma_f32_16x16x32_bf16 v[94:97], v[138:141], v[218:221], 0
	v_mfma_f32_16x16x32_bf16 v[86:89], v[130:133], v[226:229], 0
	v_mfma_f32_16x16x32_bf16 v[78:81], v[138:141], v[226:229], 0
	v_mfma_f32_16x16x32_bf16 v[126:129], v[134:137], v[198:201], v[126:129]
	v_mfma_f32_16x16x32_bf16 v[122:125], v[142:145], v[198:201], v[122:125]
	v_mfma_f32_16x16x32_bf16 v[118:121], v[134:137], v[206:209], v[118:121]
	v_mfma_f32_16x16x32_bf16 v[110:113], v[142:145], v[206:209], v[110:113]
	v_mfma_f32_16x16x32_bf16 v[102:105], v[134:137], v[222:225], v[102:105]
	v_mfma_f32_16x16x32_bf16 v[94:97], v[142:145], v[222:225], v[94:97]
	v_mfma_f32_16x16x32_bf16 v[86:89], v[134:137], v[230:233], v[86:89]
	v_mfma_f32_16x16x32_bf16 v[78:81], v[142:145], v[230:233], v[78:81]
	v_mfma_f32_16x16x32_bf16 v[114:117], v[162:165], v[194:197], 0
	v_mfma_f32_16x16x32_bf16 v[106:109], v[170:173], v[194:197], 0
	v_mfma_f32_16x16x32_bf16 v[98:101], v[162:165], v[202:205], 0
	v_mfma_f32_16x16x32_bf16 v[90:93], v[170:173], v[202:205], 0
	v_mfma_f32_16x16x32_bf16 v[82:85], v[162:165], v[218:221], 0
	v_mfma_f32_16x16x32_bf16 v[74:77], v[170:173], v[218:221], 0
	v_mfma_f32_16x16x32_bf16 v[70:73], v[162:165], v[226:229], 0
	v_mfma_f32_16x16x32_bf16 v[66:69], v[170:173], v[226:229], 0
	v_mfma_f32_16x16x32_bf16 v[114:117], v[166:169], v[198:201], v[114:117]
	v_mfma_f32_16x16x32_bf16 v[106:109], v[190:193], v[198:201], v[106:109]
	v_mfma_f32_16x16x32_bf16 v[98:101], v[166:169], v[206:209], v[98:101]
	v_mfma_f32_16x16x32_bf16 v[90:93], v[190:193], v[206:209], v[90:93]
	v_mfma_f32_16x16x32_bf16 v[82:85], v[166:169], v[222:225], v[82:85]
	v_mfma_f32_16x16x32_bf16 v[74:77], v[190:193], v[222:225], v[74:77]
	v_mfma_f32_16x16x32_bf16 v[70:73], v[166:169], v[230:233], v[70:73]
	v_mfma_f32_16x16x32_bf16 v[66:69], v[190:193], v[230:233], v[66:69]
	s_barrier
	s_add_i32 s79, s79, s8
	s_mov_b32 m0, s79
	ds_read_b128 v[194:197], v160 offset:16384
	ds_read_b128 v[198:201], v160 offset:17408
	ds_read_b128 v[202:205], v160 offset:18432
	ds_read_b128 v[206:209], v160 offset:19456
	ds_read_b128 v[218:221], v160 offset:20480
	ds_read_b128 v[222:225], v160 offset:21504
	ds_read_b128 v[226:229], v160 offset:22528
	ds_read_b128 v[230:233], v160 offset:23552
	global_load_lds_dwordx4 v148, s[76:77]
	s_add_i32 m0, s79, 0x2000
	s_add_u32 s80, s76, 0x40000
	s_addc_u32 s81, s77, 0
	s_add_i32 s79, s82, s8
	global_load_lds_dwordx4 v152, s[76:77]
	s_mov_b32 m0, s79
	s_nop 0
	global_load_lds_dwordx4 v148, s[80:81]
	s_add_i32 m0, s79, 0x2000
	s_nop 0
	global_load_lds_dwordx4 v152, s[80:81]
	s_mov_b32 m0, s9
	s_nop 0
	global_load_lds_dwordx4 v146, s[20:21]
	s_mov_b32 m0, s28
	s_nop 0
	global_load_lds_dwordx4 v150, s[20:21]
	s_waitcnt vmcnt(8)
	s_waitcnt lgkmcnt(0)
	s_barrier
; #define PG8_STAGE(bufoff, gbase, voff) do { _Pragma("unroll") for (int _i = 0; _i < 2; ++_i) \
;         __builtin_amdgcn_global_load_lds((const unsigned*)((const char*)(gbase) + (voff)[_i]), (LAS unsigned*)(lds + (bufoff) + ldsw + _i * 8192), 16, 0, 0); } while (0)
; #define PG8_LDA(dst, b, h) do { _Pragma("unroll") for (int m = 0; m < 4; ++m) _Pragma("unroll") for (int k = 0; k < 2; ++k) dst[m][k] = *(const LAS bf16x8*)(lds + PG8_SA(b, h) + aoff + m * 2048 + k * 1024); } while (0)
; #define PG8_LDB(dst, b, h) do { _Pragma("unroll") for (int n = 0; n < 2; ++n) _Pragma("unroll") for (int k = 0; k < 2; ++k) dst[n][k] = *(const LAS bf16x8*)(lds + PG8_SB(b, h) + boff + n * 2048 + k * 1024); } while (0)
; #define PG8_MMA(ai, bj, At, Bt) do { __builtin_amdgcn_s_setprio(1); _Pragma("unroll") for (int m = 0; m < 4; ++m) _Pragma("unroll") for (int n = 0; n < 2; ++n) _Pragma("unroll") for (int k = 0; k < 2; ++k) \
;         acc[ai][bj][m][n] = __builtin_amdgcn_mfma_f32_16x16x32_bf16(Bt[n][k], At[m][k], acc[ai][bj][m][n], 0, 0, 0); __builtin_amdgcn_s_setprio(0); } while (0)
; #define PG8_WAIT_V(n) asm volatile("s_waitcnt vmcnt(" #n ")" ::: "memory")
; #define PG8_WAIT_L(n) asm volatile("s_waitcnt lgkmcnt(" #n ")" ::: "memory")
; #define PG8_BAR __builtin_amdgcn_s_barrier()
; #define PG8_SCHED __builtin_amdgcn_sched_barrier(0)
; template <class Epi, class Sched>
; __device__ __forceinline__ void gemm_phase(LAS unsigned char* lds, const Gemm g, const Sched& S, const Epi& E) {
;     ...
;             PG8_WAIT_V(8); PG8_WAIT_L(0); PG8_BAR; PG8_MMA(1, 0, At, B0); PG8_MMA(1, 1, At, B1); PG8_BAR; PG8_SCHED;
;             PG8_LDB(B0, 1, 0); PG8_LDB(B1, 1, 1); PG8_SCHED; PG8_LDA(At, 1, 0); PG8_STAGE(PG8_SA(0, 1), a2 + hstepA, voffA);
;             PG8_WAIT_V(8); PG8_WAIT_L(0); PG8_BAR; PG8_MMA(0, 0, At, B0); PG8_MMA(0, 1, At, B1); PG8_BAR; PG8_SCHED;
;             PG8_LDA(At, 1, 1); PG8_STAGE(PG8_SB(1, 0), b3, voffB); PG8_STAGE(PG8_SB(1, 1), b3 + hstepB, voffB); PG8_STAGE(PG8_SA(1, 0), a3, voffA);
;             PG8_WAIT_V(8); PG8_WAIT_L(0); PG8_BAR; PG8_MMA(1, 0, At, B0); PG8_MMA(1, 1, At, B1); PG8_BAR; PG8_SCHED;
	s_waitcnt lgkmcnt(0)
	v_mfma_f32_16x16x32_bf16 v[62:65], v[130:133], v[194:197], 0
	v_mfma_f32_16x16x32_bf16 v[58:61], v[138:141], v[194:197], 0
	v_mfma_f32_16x16x32_bf16 v[54:57], v[130:133], v[202:205], 0
	v_mfma_f32_16x16x32_bf16 v[46:49], v[138:141], v[202:205], 0
	v_mfma_f32_16x16x32_bf16 v[38:41], v[130:133], v[218:221], 0
	v_mfma_f32_16x16x32_bf16 v[30:33], v[138:141], v[218:221], 0
	v_mfma_f32_16x16x32_bf16 v[22:25], v[130:133], v[226:229], 0
	v_mfma_f32_16x16x32_bf16 v[14:17], v[138:141], v[226:229], 0
	v_mfma_f32_16x16x32_bf16 v[62:65], v[134:137], v[198:201], v[62:65]
	v_mfma_f32_16x16x32_bf16 v[58:61], v[142:145], v[198:201], v[58:61]
	v_mfma_f32_16x16x32_bf16 v[54:57], v[134:137], v[206:209], v[54:57]
	v_mfma_f32_16x16x32_bf16 v[46:49], v[142:145], v[206:209], v[46:49]
	v_mfma_f32_16x16x32_bf16 v[38:41], v[134:137], v[222:225], v[38:41]
	v_mfma_f32_16x16x32_bf16 v[30:33], v[142:145], v[222:225], v[30:33]
	v_mfma_f32_16x16x32_bf16 v[22:25], v[134:137], v[230:233], v[22:25]
	v_mfma_f32_16x16x32_bf16 v[14:17], v[142:145], v[230:233], v[14:17]
	v_mfma_f32_16x16x32_bf16 v[50:53], v[162:165], v[194:197], 0
	v_mfma_f32_16x16x32_bf16 v[42:45], v[170:173], v[194:197], 0
	v_mfma_f32_16x16x32_bf16 v[34:37], v[162:165], v[202:205], 0
	v_mfma_f32_16x16x32_bf16 v[26:29], v[170:173], v[202:205], 0
	v_mfma_f32_16x16x32_bf16 v[18:21], v[162:165], v[218:221], 0
	v_mfma_f32_16x16x32_bf16 v[10:13], v[170:173], v[218:221], 0
	v_mfma_f32_16x16x32_bf16 v[6:9], v[162:165], v[226:229], 0
	v_mfma_f32_16x16x32_bf16 v[2:5], v[170:173], v[226:229], 0
	v_mfma_f32_16x16x32_bf16 v[50:53], v[166:169], v[198:201], v[50:53]
	v_mfma_f32_16x16x32_bf16 v[42:45], v[190:193], v[198:201], v[42:45]
	v_mfma_f32_16x16x32_bf16 v[34:37], v[166:169], v[206:209], v[34:37]
	v_mfma_f32_16x16x32_bf16 v[26:29], v[190:193], v[206:209], v[26:29]
	v_mfma_f32_16x16x32_bf16 v[18:21], v[166:169], v[222:225], v[18:21]
	v_mfma_f32_16x16x32_bf16 v[10:13], v[190:193], v[222:225], v[10:13]
	v_mfma_f32_16x16x32_bf16 v[6:9], v[166:169], v[230:233], v[6:9]
	v_mfma_f32_16x16x32_bf16 v[2:5], v[190:193], v[230:233], v[2:5]
	s_barrier
	s_add_i32 s79, 0, 0x18000
	s_add_i32 s80, 0, 0x1c000
	s_add_u32 s20, s20, 0x40000
	s_addc_u32 s21, s21, 0
	s_mov_b32 m0, s29
	s_nop 0
	global_load_lds_dwordx4 v146, s[20:21]
	s_mov_b32 m0, s30
	s_nop 0
	global_load_lds_dwordx4 v150, s[20:21]
	ds_read_b128 v[130:133], v255 offset:32768
	ds_read_b128 v[134:137], v255 offset:33792
	ds_read_b128 v[138:141], v255 offset:34816
	ds_read_b128 v[142:145], v255 offset:35840
	ds_read_b128 v[162:165], v255 offset:49152
	ds_read_b128 v[166:169], v255 offset:50176
	ds_read_b128 v[170:173], v255 offset:51200
	ds_read_b128 v[190:193], v255 offset:52224
	ds_read_b128 v[194:197], v160 offset:32768
	ds_read_b128 v[198:201], v160 offset:33792
	ds_read_b128 v[202:205], v160 offset:34816
	ds_read_b128 v[206:209], v160 offset:35840
	ds_read_b128 v[218:221], v160 offset:36864
	ds_read_b128 v[222:225], v160 offset:37888
	ds_read_b128 v[226:229], v160 offset:38912
	ds_read_b128 v[230:233], v160 offset:39936
	s_waitcnt vmcnt(8)
	s_waitcnt lgkmcnt(0)
	s_barrier
	s_waitcnt lgkmcnt(0)
	v_mfma_f32_16x16x32_bf16 v[126:129], v[130:133], v[194:197], v[126:129]
	v_mfma_f32_16x16x32_bf16 v[122:125], v[138:141], v[194:197], v[122:125]
	v_mfma_f32_16x16x32_bf16 v[118:121], v[130:133], v[202:205], v[118:121]
	v_mfma_f32_16x16x32_bf16 v[110:113], v[138:141], v[202:205], v[110:113]
	v_mfma_f32_16x16x32_bf16 v[102:105], v[130:133], v[218:221], v[102:105]
	v_mfma_f32_16x16x32_bf16 v[94:97], v[138:141], v[218:221], v[94:97]
	v_mfma_f32_16x16x32_bf16 v[86:89], v[130:133], v[226:229], v[86:89]
	v_mfma_f32_16x16x32_bf16 v[78:81], v[138:141], v[226:229], v[78:81]
	v_mfma_f32_16x16x32_bf16 v[126:129], v[134:137], v[198:201], v[126:129]
	v_mfma_f32_16x16x32_bf16 v[122:125], v[142:145], v[198:201], v[122:125]
	v_mfma_f32_16x16x32_bf16 v[118:121], v[134:137], v[206:209], v[118:121]
	v_mfma_f32_16x16x32_bf16 v[110:113], v[142:145], v[206:209], v[110:113]
	v_mfma_f32_16x16x32_bf16 v[102:105], v[134:137], v[222:225], v[102:105]
	v_mfma_f32_16x16x32_bf16 v[94:97], v[142:145], v[222:225], v[94:97]
	v_mfma_f32_16x16x32_bf16 v[86:89], v[134:137], v[230:233], v[86:89]
	v_mfma_f32_16x16x32_bf16 v[78:81], v[142:145], v[230:233], v[78:81]
	v_mfma_f32_16x16x32_bf16 v[114:117], v[162:165], v[194:197], v[114:117]
	v_mfma_f32_16x16x32_bf16 v[106:109], v[170:173], v[194:197], v[106:109]
	v_mfma_f32_16x16x32_bf16 v[98:101], v[162:165], v[202:205], v[98:101]
	v_mfma_f32_16x16x32_bf16 v[90:93], v[170:173], v[202:205], v[90:93]
	v_mfma_f32_16x16x32_bf16 v[82:85], v[162:165], v[218:221], v[82:85]
	v_mfma_f32_16x16x32_bf16 v[74:77], v[170:173], v[218:221], v[74:77]
	v_mfma_f32_16x16x32_bf16 v[70:73], v[162:165], v[226:229], v[70:73]
	v_mfma_f32_16x16x32_bf16 v[66:69], v[170:173], v[226:229], v[66:69]
	v_mfma_f32_16x16x32_bf16 v[114:117], v[166:169], v[198:201], v[114:117]
	v_mfma_f32_16x16x32_bf16 v[106:109], v[190:193], v[198:201], v[106:109]
	v_mfma_f32_16x16x32_bf16 v[98:101], v[166:169], v[206:209], v[98:101]
	v_mfma_f32_16x16x32_bf16 v[90:93], v[190:193], v[206:209], v[90:93]
	v_mfma_f32_16x16x32_bf16 v[82:85], v[166:169], v[222:225], v[82:85]
	v_mfma_f32_16x16x32_bf16 v[74:77], v[190:193], v[222:225], v[74:77]
	v_mfma_f32_16x16x32_bf16 v[70:73], v[166:169], v[230:233], v[70:73]
	v_mfma_f32_16x16x32_bf16 v[66:69], v[190:193], v[230:233], v[66:69]
	s_barrier
; #define PG8_STAGE(bufoff, gbase, voff) do { _Pragma("unroll") for (int _i = 0; _i < 2; ++_i) \
;         __builtin_amdgcn_global_load_lds((const unsigned*)((const char*)(gbase) + (voff)[_i]), (LAS unsigned*)(lds + (bufoff) + ldsw + _i * 8192), 16, 0, 0); } while (0)
; #define PG8_LDA(dst, b, h) do { _Pragma("unroll") for (int m = 0; m < 4; ++m) _Pragma("unroll") for (int k = 0; k < 2; ++k) dst[m][k] = *(const LAS bf16x8*)(lds + PG8_SA(b, h) + aoff + m * 2048 + k * 1024); } while (0)
; #define PG8_LDB(dst, b, h) do { _Pragma("unroll") for (int n = 0; n < 2; ++n) _Pragma("unroll") for (int k = 0; k < 2; ++k) dst[n][k] = *(const LAS bf16x8*)(lds + PG8_SB(b, h) + boff + n * 2048 + k * 1024); } while (0)
; #define PG8_MMA(ai, bj, At, Bt) do { __builtin_amdgcn_s_setprio(1); _Pragma("unroll") for (int m = 0; m < 4; ++m) _Pragma("unroll") for (int n = 0; n < 2; ++n) _Pragma("unroll") for (int k = 0; k < 2; ++k) \
;         acc[ai][bj][m][n] = __builtin_amdgcn_mfma_f32_16x16x32_bf16(Bt[n][k], At[m][k], acc[ai][bj][m][n], 0, 0, 0); __builtin_amdgcn_s_setprio(0); } while (0)
; #define PG8_WAIT_V(n) asm volatile("s_waitcnt vmcnt(" #n ")" ::: "memory")
; #define PG8_WAIT_L(n) asm volatile("s_waitcnt lgkmcnt(" #n ")" ::: "memory")
; #define PG8_BAR __builtin_amdgcn_s_barrier()
; #define PG8_SCHED __builtin_amdgcn_sched_barrier(0)
; template <class Epi, class Sched>
; __device__ __forceinline__ void gemm_phase(LAS unsigned char* lds, const Gemm g, const Sched& S, const Epi& E) {
;     ...
;             const char* a1 = cA + (size_t)(t + 1) * kstep;
;             const char* a2 = last ? nA : cA + (size_t)(t + 2) * kstep; const char* b2 = last ? nB : cB + (size_t)(t + 2) * kstep;
;             const char* a3 = a2 + kstep; const char* b3 = b2 + kstep;
;             PG8_LDB(B0, 0, 0); PG8_LDB(B1, 0, 1); PG8_SCHED; PG8_LDA(At, 0, 0); PG8_STAGE(PG8_SA(1, 1), a1 + hstepA, voffA);
;             PG8_WAIT_V(8); PG8_WAIT_L(0); PG8_BAR; PG8_MMA(0, 0, At, B0); PG8_MMA(0, 1, At, B1); PG8_BAR; PG8_SCHED;
;     ...
;             PG8_LDA(At, 1, 1); PG8_STAGE(PG8_SB(1, 0), b3, voffB); PG8_STAGE(PG8_SB(1, 1), b3 + hstepB, voffB); PG8_STAGE(PG8_SA(1, 0), a3, voffA);
;             PG8_WAIT_V(8); PG8_WAIT_L(0); PG8_BAR; PG8_MMA(1, 0, At, B0); PG8_MMA(1, 1, At, B1); PG8_BAR; PG8_SCHED;
;         }
	s_add_i32 s20, s8, 0x18000
	s_add_u32 s80, s76, 0x80
	s_addc_u32 s81, s77, 0
	s_mov_b32 m0, s20
	ds_read_b128 v[194:197], v160 offset:49152
	ds_read_b128 v[198:201], v160 offset:50176
	ds_read_b128 v[202:205], v160 offset:51200
	ds_read_b128 v[206:209], v160 offset:52224
	ds_read_b128 v[218:221], v160 offset:53248
	ds_read_b128 v[222:225], v160 offset:54272
	ds_read_b128 v[226:229], v160 offset:55296
	ds_read_b128 v[230:233], v160 offset:56320
	global_load_lds_dwordx4 v148, s[80:81]
	s_add_i32 m0, s20, 0x2000
	s_add_u32 s20, s76, 0x40080
	s_addc_u32 s21, s77, 0
	s_add_i32 s12, s8, 0x1c000
	global_load_lds_dwordx4 v152, s[80:81]
	s_mov_b32 m0, s12
	s_nop 0
	global_load_lds_dwordx4 v148, s[20:21]
	s_add_i32 m0, s12, 0x2000
	s_nop 0
	global_load_lds_dwordx4 v152, s[20:21]
	s_mov_b32 m0, s31
	s_nop 0
	global_load_lds_dwordx4 v146, s[100:101]
	s_mov_b32 m0, s34
	s_nop 0
	global_load_lds_dwordx4 v150, s[100:101]
	s_waitcnt vmcnt(8)
	s_waitcnt lgkmcnt(0)
	s_barrier
	s_waitcnt lgkmcnt(0)
	v_mfma_f32_16x16x32_bf16 v[62:65], v[130:133], v[194:197], v[62:65]
	v_mfma_f32_16x16x32_bf16 v[58:61], v[138:141], v[194:197], v[58:61]
	v_mfma_f32_16x16x32_bf16 v[54:57], v[130:133], v[202:205], v[54:57]
	v_mfma_f32_16x16x32_bf16 v[46:49], v[138:141], v[202:205], v[46:49]
	v_mfma_f32_16x16x32_bf16 v[38:41], v[130:133], v[218:221], v[38:41]
	v_mfma_f32_16x16x32_bf16 v[30:33], v[138:141], v[218:221], v[30:33]
	v_mfma_f32_16x16x32_bf16 v[22:25], v[130:133], v[226:229], v[22:25]
	v_mfma_f32_16x16x32_bf16 v[14:17], v[138:141], v[226:229], v[14:17]
	v_mfma_f32_16x16x32_bf16 v[62:65], v[134:137], v[198:201], v[62:65]
	v_mfma_f32_16x16x32_bf16 v[58:61], v[142:145], v[198:201], v[58:61]
	v_mfma_f32_16x16x32_bf16 v[54:57], v[134:137], v[206:209], v[54:57]
	v_mfma_f32_16x16x32_bf16 v[46:49], v[142:145], v[206:209], v[46:49]
	v_mfma_f32_16x16x32_bf16 v[38:41], v[134:137], v[222:225], v[38:41]
	v_mfma_f32_16x16x32_bf16 v[30:33], v[142:145], v[222:225], v[30:33]
	v_mfma_f32_16x16x32_bf16 v[22:25], v[134:137], v[230:233], v[22:25]
	v_mfma_f32_16x16x32_bf16 v[14:17], v[142:145], v[230:233], v[14:17]
	v_mfma_f32_16x16x32_bf16 v[50:53], v[162:165], v[194:197], v[50:53]
	v_mfma_f32_16x16x32_bf16 v[42:45], v[170:173], v[194:197], v[42:45]
	v_mfma_f32_16x16x32_bf16 v[34:37], v[162:165], v[202:205], v[34:37]
	v_mfma_f32_16x16x32_bf16 v[26:29], v[170:173], v[202:205], v[26:29]
	v_mfma_f32_16x16x32_bf16 v[18:21], v[162:165], v[218:221], v[18:21]
	v_mfma_f32_16x16x32_bf16 v[10:13], v[170:173], v[218:221], v[10:13]
	v_mfma_f32_16x16x32_bf16 v[6:9], v[162:165], v[226:229], v[6:9]
	v_mfma_f32_16x16x32_bf16 v[2:5], v[170:173], v[226:229], v[2:5]
	v_mfma_f32_16x16x32_bf16 v[50:53], v[166:169], v[198:201], v[50:53]
	v_mfma_f32_16x16x32_bf16 v[42:45], v[190:193], v[198:201], v[42:45]
	v_mfma_f32_16x16x32_bf16 v[34:37], v[166:169], v[206:209], v[34:37]
	v_mfma_f32_16x16x32_bf16 v[26:29], v[190:193], v[206:209], v[26:29]
	v_mfma_f32_16x16x32_bf16 v[18:21], v[166:169], v[222:225], v[18:21]
	v_mfma_f32_16x16x32_bf16 v[10:13], v[190:193], v[222:225], v[10:13]
	v_mfma_f32_16x16x32_bf16 v[6:9], v[166:169], v[230:233], v[6:9]
	v_mfma_f32_16x16x32_bf16 v[2:5], v[190:193], v[230:233], v[2:5]
	s_barrier
	s_add_i32 s78, s78, 2
	s_add_u32 s18, s18, 0x100
	s_addc_u32 s19, s19, 0
	s_add_u32 s69, s69, 0x100
	s_addc_u32 s71, s71, 0
	s_cmp_gt_u32 s78, 13
.LBB0_378:
	s_add_u32 s20, s18, 0xfffc0080
	s_addc_u32 s21, s19, -1
	s_add_i32 s79, 0, 0x10000
	s_cmp_eq_u32 s78, 12
	s_cselect_b32 s21, s43, s21
	s_cselect_b32 s20, s48, s20
	s_cselect_b32 s77, s49, s71
	s_cselect_b32 s76, s53, s69
	s_add_u32 s100, s20, 0x80
	s_addc_u32 s101, s21, 0
	s_add_i32 s82, 0, 0x14000
	s_add_i32 m0, s9, 0xc000
	s_nop 0
	global_load_lds_dwordx4 v146, s[18:19]
	s_add_i32 m0, s9, 0xe000
	s_nop 0
	global_load_lds_dwordx4 v150, s[18:19]
	ds_read_b128 v[130:133], v255
	ds_read_b128 v[134:137], v255 offset:1024
	ds_read_b128 v[138:141], v255 offset:2048
	ds_read_b128 v[142:145], v255 offset:3072
	ds_read_b128 v[162:165], v255 offset:16384
	ds_read_b128 v[166:169], v255 offset:17408
	ds_read_b128 v[170:173], v255 offset:18432
	ds_read_b128 v[190:193], v255 offset:19456
	ds_read_b128 v[194:197], v160
	ds_read_b128 v[198:201], v160 offset:1024
	ds_read_b128 v[202:205], v160 offset:2048
	ds_read_b128 v[206:209], v160 offset:3072
	ds_read_b128 v[218:221], v160 offset:4096
	ds_read_b128 v[222:225], v160 offset:5120
	ds_read_b128 v[226:229], v160 offset:6144
	ds_read_b128 v[230:233], v160 offset:7168
	s_waitcnt vmcnt(8)
	s_waitcnt lgkmcnt(0)
	s_barrier
; #define PG8_STAGE(bufoff, gbase, voff) do { _Pragma("unroll") for (int _i = 0; _i < 2; ++_i) \
;         __builtin_amdgcn_global_load_lds((const unsigned*)((const char*)(gbase) + (voff)[_i]), (LAS unsigned*)(lds + (bufoff) + ldsw + _i * 8192), 16, 0, 0); } while (0)
; #define PG8_LDA(dst, b, h) do { _Pragma("unroll") for (int m = 0; m < 4; ++m) _Pragma("unroll") for (int k = 0; k < 2; ++k) dst[m][k] = *(const LAS bf16x8*)(lds + PG8_SA(b, h) + aoff + m * 2048 + k * 1024); } while (0)
; #define PG8_LDB(dst, b, h) do { _Pragma("unroll") for (int n = 0; n < 2; ++n) _Pragma("unroll") for (int k = 0; k < 2; ++k) dst[n][k] = *(const LAS bf16x8*)(lds + PG8_SB(b, h) + boff + n * 2048 + k * 1024); } while (0)
; #define PG8_MMA(ai, bj, At, Bt) do { __builtin_amdgcn_s_setprio(1); _Pragma("unroll") for (int m = 0; m < 4; ++m) _Pragma("unroll") for (int n = 0; n < 2; ++n) _Pragma("unroll") for (int k = 0; k < 2; ++k) \
;         acc[ai][bj][m][n] = __builtin_amdgcn_mfma_f32_16x16x32_bf16(Bt[n][k], At[m][k], acc[ai][bj][m][n], 0, 0, 0); __builtin_amdgcn_s_setprio(0); } while (0)
; #define PG8_WAIT_V(n) asm volatile("s_waitcnt vmcnt(" #n ")" ::: "memory")
; #define PG8_WAIT_L(n) asm volatile("s_waitcnt lgkmcnt(" #n ")" ::: "memory")
; #define PG8_BAR __builtin_amdgcn_s_barrier()
; #define PG8_SCHED __builtin_amdgcn_sched_barrier(0)
; template <class Epi, class Sched>
; __device__ __forceinline__ void gemm_phase(LAS unsigned char* lds, const Gemm g, const Sched& S, const Epi& E) {
;     ...
;             PG8_WAIT_V(8); PG8_WAIT_L(0); PG8_BAR; PG8_MMA(0, 0, At, B0); PG8_MMA(0, 1, At, B1); PG8_BAR; PG8_SCHED;
;             PG8_LDA(At, 0, 1); PG8_STAGE(PG8_SB(0, 0), b2, voffB); PG8_STAGE(PG8_SB(0, 1), b2 + hstepB, voffB); PG8_STAGE(PG8_SA(0, 0), a2, voffA);
;             PG8_WAIT_V(8); PG8_WAIT_L(0); PG8_BAR; PG8_MMA(1, 0, At, B0); PG8_MMA(1, 1, At, B1); PG8_BAR; PG8_SCHED;
;             PG8_LDB(B0, 1, 0); PG8_LDB(B1, 1, 1); PG8_SCHED; PG8_LDA(At, 1, 0); PG8_STAGE(PG8_SA(0, 1), a2 + hstepA, voffA);
;             PG8_WAIT_V(8); PG8_WAIT_L(0); PG8_BAR; PG8_MMA(0, 0, At, B0); PG8_MMA(0, 1, At, B1); PG8_BAR; PG8_SCHED;
	s_waitcnt lgkmcnt(0)
	v_mfma_f32_16x16x32_bf16 v[126:129], v[130:133], v[194:197], v[126:129]
	v_mfma_f32_16x16x32_bf16 v[122:125], v[138:141], v[194:197], v[122:125]
	v_mfma_f32_16x16x32_bf16 v[118:121], v[130:133], v[202:205], v[118:121]
	v_mfma_f32_16x16x32_bf16 v[110:113], v[138:141], v[202:205], v[110:113]
	v_mfma_f32_16x16x32_bf16 v[102:105], v[130:133], v[218:221], v[102:105]
	v_mfma_f32_16x16x32_bf16 v[94:97], v[138:141], v[218:221], v[94:97]
	v_mfma_f32_16x16x32_bf16 v[86:89], v[130:133], v[226:229], v[86:89]
	v_mfma_f32_16x16x32_bf16 v[78:81], v[138:141], v[226:229], v[78:81]
	v_mfma_f32_16x16x32_bf16 v[126:129], v[134:137], v[198:201], v[126:129]
	v_mfma_f32_16x16x32_bf16 v[122:125], v[142:145], v[198:201], v[122:125]
	v_mfma_f32_16x16x32_bf16 v[118:121], v[134:137], v[206:209], v[118:121]
	v_mfma_f32_16x16x32_bf16 v[110:113], v[142:145], v[206:209], v[110:113]
	v_mfma_f32_16x16x32_bf16 v[102:105], v[134:137], v[222:225], v[102:105]
	v_mfma_f32_16x16x32_bf16 v[94:97], v[142:145], v[222:225], v[94:97]
	v_mfma_f32_16x16x32_bf16 v[86:89], v[134:137], v[230:233], v[86:89]
	v_mfma_f32_16x16x32_bf16 v[78:81], v[142:145], v[230:233], v[78:81]
	v_mfma_f32_16x16x32_bf16 v[114:117], v[162:165], v[194:197], v[114:117]
	v_mfma_f32_16x16x32_bf16 v[106:109], v[170:173], v[194:197], v[106:109]
	v_mfma_f32_16x16x32_bf16 v[98:101], v[162:165], v[202:205], v[98:101]
	v_mfma_f32_16x16x32_bf16 v[90:93], v[170:173], v[202:205], v[90:93]
	v_mfma_f32_16x16x32_bf16 v[82:85], v[162:165], v[218:221], v[82:85]
	v_mfma_f32_16x16x32_bf16 v[74:77], v[170:173], v[218:221], v[74:77]
	v_mfma_f32_16x16x32_bf16 v[70:73], v[162:165], v[226:229], v[70:73]
	v_mfma_f32_16x16x32_bf16 v[66:69], v[170:173], v[226:229], v[66:69]
	v_mfma_f32_16x16x32_bf16 v[114:117], v[166:169], v[198:201], v[114:117]
	v_mfma_f32_16x16x32_bf16 v[106:109], v[190:193], v[198:201], v[106:109]
	v_mfma_f32_16x16x32_bf16 v[98:101], v[166:169], v[206:209], v[98:101]
	v_mfma_f32_16x16x32_bf16 v[90:93], v[190:193], v[206:209], v[90:93]
	v_mfma_f32_16x16x32_bf16 v[82:85], v[166:169], v[222:225], v[82:85]
	v_mfma_f32_16x16x32_bf16 v[74:77], v[190:193], v[222:225], v[74:77]
	v_mfma_f32_16x16x32_bf16 v[70:73], v[166:169], v[230:233], v[70:73]
	v_mfma_f32_16x16x32_bf16 v[66:69], v[190:193], v[230:233], v[66:69]
	s_barrier
	s_add_i32 s79, s79, s8
	s_mov_b32 m0, s79
	ds_read_b128 v[194:197], v160 offset:16384
	ds_read_b128 v[198:201], v160 offset:17408
	ds_read_b128 v[202:205], v160 offset:18432
	ds_read_b128 v[206:209], v160 offset:19456
	ds_read_b128 v[218:221], v160 offset:20480
	ds_read_b128 v[222:225], v160 offset:21504
	ds_read_b128 v[226:229], v160 offset:22528
	ds_read_b128 v[230:233], v160 offset:23552
	global_load_lds_dwordx4 v148, s[76:77]
	s_add_i32 m0, s79, 0x2000
	s_add_u32 s80, s76, 0x40000
	s_addc_u32 s81, s77, 0
	s_add_i32 s79, s82, s8
	global_load_lds_dwordx4 v152, s[76:77]
	s_mov_b32 m0, s79
	s_nop 0
	global_load_lds_dwordx4 v148, s[80:81]
	s_add_i32 m0, s79, 0x2000
	s_nop 0
	global_load_lds_dwordx4 v152, s[80:81]
	s_mov_b32 m0, s9
	s_nop 0
	global_load_lds_dwordx4 v146, s[20:21]
	s_mov_b32 m0, s28
	s_nop 0
	global_load_lds_dwordx4 v150, s[20:21]
	s_waitcnt vmcnt(8)
	s_waitcnt lgkmcnt(0)
	s_barrier
	s_waitcnt lgkmcnt(0)
	v_mfma_f32_16x16x32_bf16 v[62:65], v[130:133], v[194:197], v[62:65]
	v_mfma_f32_16x16x32_bf16 v[58:61], v[138:141], v[194:197], v[58:61]
	v_mfma_f32_16x16x32_bf16 v[54:57], v[130:133], v[202:205], v[54:57]
	v_mfma_f32_16x16x32_bf16 v[46:49], v[138:141], v[202:205], v[46:49]
	v_mfma_f32_16x16x32_bf16 v[38:41], v[130:133], v[218:221], v[38:41]
	v_mfma_f32_16x16x32_bf16 v[30:33], v[138:141], v[218:221], v[30:33]
	v_mfma_f32_16x16x32_bf16 v[22:25], v[130:133], v[226:229], v[22:25]
	v_mfma_f32_16x16x32_bf16 v[14:17], v[138:141], v[226:229], v[14:17]
	v_mfma_f32_16x16x32_bf16 v[62:65], v[134:137], v[198:201], v[62:65]
	v_mfma_f32_16x16x32_bf16 v[58:61], v[142:145], v[198:201], v[58:61]
	v_mfma_f32_16x16x32_bf16 v[54:57], v[134:137], v[206:209], v[54:57]
	v_mfma_f32_16x16x32_bf16 v[46:49], v[142:145], v[206:209], v[46:49]
	v_mfma_f32_16x16x32_bf16 v[38:41], v[134:137], v[222:225], v[38:41]
	v_mfma_f32_16x16x32_bf16 v[30:33], v[142:145], v[222:225], v[30:33]
	v_mfma_f32_16x16x32_bf16 v[22:25], v[134:137], v[230:233], v[22:25]
	v_mfma_f32_16x16x32_bf16 v[14:17], v[142:145], v[230:233], v[14:17]
	v_mfma_f32_16x16x32_bf16 v[50:53], v[162:165], v[194:197], v[50:53]
	v_mfma_f32_16x16x32_bf16 v[42:45], v[170:173], v[194:197], v[42:45]
	v_mfma_f32_16x16x32_bf16 v[34:37], v[162:165], v[202:205], v[34:37]
	v_mfma_f32_16x16x32_bf16 v[26:29], v[170:173], v[202:205], v[26:29]
	v_mfma_f32_16x16x32_bf16 v[18:21], v[162:165], v[218:221], v[18:21]
	v_mfma_f32_16x16x32_bf16 v[10:13], v[170:173], v[218:221], v[10:13]
	v_mfma_f32_16x16x32_bf16 v[6:9], v[162:165], v[226:229], v[6:9]
	v_mfma_f32_16x16x32_bf16 v[2:5], v[170:173], v[226:229], v[2:5]
	v_mfma_f32_16x16x32_bf16 v[50:53], v[166:169], v[198:201], v[50:53]
	v_mfma_f32_16x16x32_bf16 v[42:45], v[190:193], v[198:201], v[42:45]
	v_mfma_f32_16x16x32_bf16 v[34:37], v[166:169], v[206:209], v[34:37]
	v_mfma_f32_16x16x32_bf16 v[26:29], v[190:193], v[206:209], v[26:29]
	v_mfma_f32_16x16x32_bf16 v[18:21], v[166:169], v[222:225], v[18:21]
	v_mfma_f32_16x16x32_bf16 v[10:13], v[190:193], v[222:225], v[10:13]
	v_mfma_f32_16x16x32_bf16 v[6:9], v[166:169], v[230:233], v[6:9]
	v_mfma_f32_16x16x32_bf16 v[2:5], v[190:193], v[230:233], v[2:5]
	s_barrier
; #define PG8_STAGE(bufoff, gbase, voff) do { _Pragma("unroll") for (int _i = 0; _i < 2; ++_i) \
;         __builtin_amdgcn_global_load_lds((const unsigned*)((const char*)(gbase) + (voff)[_i]), (LAS unsigned*)(lds + (bufoff) + ldsw + _i * 8192), 16, 0, 0); } while (0)
; #define PG8_LDA(dst, b, h) do { _Pragma("unroll") for (int m = 0; m < 4; ++m) _Pragma("unroll") for (int k = 0; k < 2; ++k) dst[m][k] = *(const LAS bf16x8*)(lds + PG8_SA(b, h) + aoff + m * 2048 + k * 1024); } while (0)
; #define PG8_LDB(dst, b, h) do { _Pragma("unroll") for (int n = 0; n < 2; ++n) _Pragma("unroll") for (int k = 0; k < 2; ++k) dst[n][k] = *(const LAS bf16x8*)(lds + PG8_SB(b, h) + boff + n * 2048 + k * 1024); } while (0)
; #define PG8_MMA(ai, bj, At, Bt) do { __builtin_amdgcn_s_setprio(1); _Pragma("unroll") for (int m = 0; m < 4; ++m) _Pragma("unroll") for (int n = 0; n < 2; ++n) _Pragma("unroll") for (int k = 0; k < 2; ++k) \
;         acc[ai][bj][m][n] = __builtin_amdgcn_mfma_f32_16x16x32_bf16(Bt[n][k], At[m][k], acc[ai][bj][m][n], 0, 0, 0); __builtin_amdgcn_s_setprio(0); } while (0)
; #define PG8_WAIT_V(n) asm volatile("s_waitcnt vmcnt(" #n ")" ::: "memory")
; #define PG8_WAIT_L(n) asm volatile("s_waitcnt lgkmcnt(" #n ")" ::: "memory")
; #define PG8_BAR __builtin_amdgcn_s_barrier()
; #define PG8_SCHED __builtin_amdgcn_sched_barrier(0)
; template <class Epi, class Sched>
; __device__ __forceinline__ void gemm_phase(LAS unsigned char* lds, const Gemm g, const Sched& S, const Epi& E) {
;     ...
;             PG8_LDB(B0, 1, 0); PG8_LDB(B1, 1, 1); PG8_SCHED; PG8_LDA(At, 1, 0); PG8_STAGE(PG8_SA(0, 1), a2 + hstepA, voffA);
;             PG8_WAIT_V(8); PG8_WAIT_L(0); PG8_BAR; PG8_MMA(0, 0, At, B0); PG8_MMA(0, 1, At, B1); PG8_BAR; PG8_SCHED;
;             PG8_LDA(At, 1, 1); PG8_STAGE(PG8_SB(1, 0), b3, voffB); PG8_STAGE(PG8_SB(1, 1), b3 + hstepB, voffB); PG8_STAGE(PG8_SA(1, 0), a3, voffA);
;             PG8_WAIT_V(8); PG8_WAIT_L(0); PG8_BAR; PG8_MMA(1, 0, At, B0); PG8_MMA(1, 1, At, B1); PG8_BAR; PG8_SCHED;
;         }
	s_add_i32 s79, 0, 0x18000
	s_add_i32 s80, 0, 0x1c000
	s_add_u32 s20, s20, 0x40000
	s_addc_u32 s21, s21, 0
	s_mov_b32 m0, s29
	s_nop 0
	global_load_lds_dwordx4 v146, s[20:21]
	s_mov_b32 m0, s30
	s_nop 0
	global_load_lds_dwordx4 v150, s[20:21]
	ds_read_b128 v[130:133], v255 offset:32768
	ds_read_b128 v[134:137], v255 offset:33792
	ds_read_b128 v[138:141], v255 offset:34816
	ds_read_b128 v[142:145], v255 offset:35840
	ds_read_b128 v[162:165], v255 offset:49152
	ds_read_b128 v[166:169], v255 offset:50176
	ds_read_b128 v[170:173], v255 offset:51200
	ds_read_b128 v[190:193], v255 offset:52224
	ds_read_b128 v[194:197], v160 offset:32768
	ds_read_b128 v[198:201], v160 offset:33792
	ds_read_b128 v[202:205], v160 offset:34816
	ds_read_b128 v[206:209], v160 offset:35840
	ds_read_b128 v[218:221], v160 offset:36864
	ds_read_b128 v[222:225], v160 offset:37888
	ds_read_b128 v[226:229], v160 offset:38912
	ds_read_b128 v[230:233], v160 offset:39936
	s_waitcnt vmcnt(8)
	s_waitcnt lgkmcnt(0)
	s_barrier
	s_waitcnt lgkmcnt(0)
	v_mfma_f32_16x16x32_bf16 v[126:129], v[130:133], v[194:197], v[126:129]
	v_mfma_f32_16x16x32_bf16 v[122:125], v[138:141], v[194:197], v[122:125]
	v_mfma_f32_16x16x32_bf16 v[118:121], v[130:133], v[202:205], v[118:121]
	v_mfma_f32_16x16x32_bf16 v[110:113], v[138:141], v[202:205], v[110:113]
	v_mfma_f32_16x16x32_bf16 v[102:105], v[130:133], v[218:221], v[102:105]
	v_mfma_f32_16x16x32_bf16 v[94:97], v[138:141], v[218:221], v[94:97]
	v_mfma_f32_16x16x32_bf16 v[86:89], v[130:133], v[226:229], v[86:89]
	v_mfma_f32_16x16x32_bf16 v[78:81], v[138:141], v[226:229], v[78:81]
	v_mfma_f32_16x16x32_bf16 v[126:129], v[134:137], v[198:201], v[126:129]
	v_mfma_f32_16x16x32_bf16 v[122:125], v[142:145], v[198:201], v[122:125]
	v_mfma_f32_16x16x32_bf16 v[118:121], v[134:137], v[206:209], v[118:121]
	v_mfma_f32_16x16x32_bf16 v[110:113], v[142:145], v[206:209], v[110:113]
	v_mfma_f32_16x16x32_bf16 v[102:105], v[134:137], v[222:225], v[102:105]
	v_mfma_f32_16x16x32_bf16 v[94:97], v[142:145], v[222:225], v[94:97]
	v_mfma_f32_16x16x32_bf16 v[86:89], v[134:137], v[230:233], v[86:89]
	v_mfma_f32_16x16x32_bf16 v[78:81], v[142:145], v[230:233], v[78:81]
	v_mfma_f32_16x16x32_bf16 v[114:117], v[162:165], v[194:197], v[114:117]
	v_mfma_f32_16x16x32_bf16 v[106:109], v[170:173], v[194:197], v[106:109]
	v_mfma_f32_16x16x32_bf16 v[98:101], v[162:165], v[202:205], v[98:101]
	v_mfma_f32_16x16x32_bf16 v[90:93], v[170:173], v[202:205], v[90:93]
	v_mfma_f32_16x16x32_bf16 v[82:85], v[162:165], v[218:221], v[82:85]
	v_mfma_f32_16x16x32_bf16 v[74:77], v[170:173], v[218:221], v[74:77]
	v_mfma_f32_16x16x32_bf16 v[70:73], v[162:165], v[226:229], v[70:73]
	v_mfma_f32_16x16x32_bf16 v[66:69], v[170:173], v[226:229], v[66:69]
	v_mfma_f32_16x16x32_bf16 v[114:117], v[166:169], v[198:201], v[114:117]
	v_mfma_f32_16x16x32_bf16 v[106:109], v[190:193], v[198:201], v[106:109]
	v_mfma_f32_16x16x32_bf16 v[98:101], v[166:169], v[206:209], v[98:101]
	v_mfma_f32_16x16x32_bf16 v[90:93], v[190:193], v[206:209], v[90:93]
	v_mfma_f32_16x16x32_bf16 v[82:85], v[166:169], v[222:225], v[82:85]
	v_mfma_f32_16x16x32_bf16 v[74:77], v[190:193], v[222:225], v[74:77]
	v_mfma_f32_16x16x32_bf16 v[70:73], v[166:169], v[230:233], v[70:73]
	v_mfma_f32_16x16x32_bf16 v[66:69], v[190:193], v[230:233], v[66:69]
	s_barrier
	s_add_i32 s20, s8, 0x18000
	s_add_u32 s80, s76, 0x80
	s_addc_u32 s81, s77, 0
	s_mov_b32 m0, s20
	ds_read_b128 v[194:197], v160 offset:49152
	ds_read_b128 v[198:201], v160 offset:50176
	ds_read_b128 v[202:205], v160 offset:51200
	ds_read_b128 v[206:209], v160 offset:52224
	ds_read_b128 v[218:221], v160 offset:53248
	ds_read_b128 v[222:225], v160 offset:54272
	ds_read_b128 v[226:229], v160 offset:55296
	ds_read_b128 v[230:233], v160 offset:56320
	global_load_lds_dwordx4 v148, s[80:81]
	s_add_i32 m0, s20, 0x2000
	s_add_u32 s20, s76, 0x40080
	s_addc_u32 s21, s77, 0
	s_add_i32 s12, s8, 0x1c000
	global_load_lds_dwordx4 v152, s[80:81]
	s_mov_b32 m0, s12
	s_nop 0
	global_load_lds_dwordx4 v148, s[20:21]
	s_add_i32 m0, s12, 0x2000
	s_nop 0
	global_load_lds_dwordx4 v152, s[20:21]
	s_mov_b32 m0, s31
	s_nop 0
	global_load_lds_dwordx4 v146, s[100:101]
	s_mov_b32 m0, s34
	s_nop 0
	global_load_lds_dwordx4 v150, s[100:101]
	s_waitcnt vmcnt(8)
	s_waitcnt lgkmcnt(0)
	s_barrier
	s_waitcnt lgkmcnt(0)
	v_mfma_f32_16x16x32_bf16 v[62:65], v[130:133], v[194:197], v[62:65]
	v_mfma_f32_16x16x32_bf16 v[58:61], v[138:141], v[194:197], v[58:61]
	v_mfma_f32_16x16x32_bf16 v[54:57], v[130:133], v[202:205], v[54:57]
	v_mfma_f32_16x16x32_bf16 v[46:49], v[138:141], v[202:205], v[46:49]
	v_mfma_f32_16x16x32_bf16 v[38:41], v[130:133], v[218:221], v[38:41]
	v_mfma_f32_16x16x32_bf16 v[30:33], v[138:141], v[218:221], v[30:33]
	v_mfma_f32_16x16x32_bf16 v[22:25], v[130:133], v[226:229], v[22:25]
	v_mfma_f32_16x16x32_bf16 v[14:17], v[138:141], v[226:229], v[14:17]
	v_mfma_f32_16x16x32_bf16 v[62:65], v[134:137], v[198:201], v[62:65]
	v_mfma_f32_16x16x32_bf16 v[58:61], v[142:145], v[198:201], v[58:61]
	v_mfma_f32_16x16x32_bf16 v[54:57], v[134:137], v[206:209], v[54:57]
	v_mfma_f32_16x16x32_bf16 v[46:49], v[142:145], v[206:209], v[46:49]
	v_mfma_f32_16x16x32_bf16 v[38:41], v[134:137], v[222:225], v[38:41]
	v_mfma_f32_16x16x32_bf16 v[30:33], v[142:145], v[222:225], v[30:33]
	v_mfma_f32_16x16x32_bf16 v[22:25], v[134:137], v[230:233], v[22:25]
	v_mfma_f32_16x16x32_bf16 v[14:17], v[142:145], v[230:233], v[14:17]
	v_mfma_f32_16x16x32_bf16 v[50:53], v[162:165], v[194:197], v[50:53]
	v_mfma_f32_16x16x32_bf16 v[42:45], v[170:173], v[194:197], v[42:45]
	v_mfma_f32_16x16x32_bf16 v[34:37], v[162:165], v[202:205], v[34:37]
	v_mfma_f32_16x16x32_bf16 v[26:29], v[170:173], v[202:205], v[26:29]
	v_mfma_f32_16x16x32_bf16 v[18:21], v[162:165], v[218:221], v[18:21]
	v_mfma_f32_16x16x32_bf16 v[10:13], v[170:173], v[218:221], v[10:13]
	v_mfma_f32_16x16x32_bf16 v[6:9], v[162:165], v[226:229], v[6:9]
	v_mfma_f32_16x16x32_bf16 v[2:5], v[170:173], v[226:229], v[2:5]
	v_mfma_f32_16x16x32_bf16 v[50:53], v[166:169], v[198:201], v[50:53]
	v_mfma_f32_16x16x32_bf16 v[42:45], v[190:193], v[198:201], v[42:45]
	v_mfma_f32_16x16x32_bf16 v[34:37], v[166:169], v[206:209], v[34:37]
	v_mfma_f32_16x16x32_bf16 v[26:29], v[190:193], v[206:209], v[26:29]
	v_mfma_f32_16x16x32_bf16 v[18:21], v[166:169], v[222:225], v[18:21]
	v_mfma_f32_16x16x32_bf16 v[10:13], v[190:193], v[222:225], v[10:13]
	v_mfma_f32_16x16x32_bf16 v[6:9], v[166:169], v[230:233], v[6:9]
	v_mfma_f32_16x16x32_bf16 v[2:5], v[190:193], v[230:233], v[2:5]
	s_barrier
	s_add_i32 s78, s78, 2
	s_add_u32 s18, s18, 0x100
	s_addc_u32 s19, s19, 0
	s_add_u32 s69, s69, 0x100
	s_addc_u32 s71, s71, 0
	s_cmp_gt_u32 s78, 13
	s_cbranch_scc0 .LBB0_378
	s_and_b64 vcc, exec, s[36:37]
	s_cbranch_vccz .LBB0_381
	s_barrier

; #define PG8_STAGE(bufoff, gbase, voff) do { _Pragma("unroll") for (int _i = 0; _i < 2; ++_i) \
;         __builtin_amdgcn_global_load_lds((const unsigned*)((const char*)(gbase) + (voff)[_i]), (LAS unsigned*)(lds + (bufoff) + ldsw + _i * 8192), 16, 0, 0); } while (0)
; #define PG8_LDA(dst, b, h) do { _Pragma("unroll") for (int m = 0; m < 4; ++m) _Pragma("unroll") for (int k = 0; k < 2; ++k) dst[m][k] = *(const LAS bf16x8*)(lds + PG8_SA(b, h) + aoff + m * 2048 + k * 1024); } while (0)
; #define PG8_LDB(dst, b, h) do { _Pragma("unroll") for (int n = 0; n < 2; ++n) _Pragma("unroll") for (int k = 0; k < 2; ++k) dst[n][k] = *(const LAS bf16x8*)(lds + PG8_SB(b, h) + boff + n * 2048 + k * 1024); } while (0)
; #define PG8_MMA(ai, bj, At, Bt) do { __builtin_amdgcn_s_setprio(1); _Pragma("unroll") for (int m = 0; m < 4; ++m) _Pragma("unroll") for (int n = 0; n < 2; ++n) _Pragma("unroll") for (int k = 0; k < 2; ++k) \
;         acc[ai][bj][m][n] = __builtin_amdgcn_mfma_f32_16x16x32_bf16(Bt[n][k], At[m][k], acc[ai][bj][m][n], 0, 0, 0); __builtin_amdgcn_s_setprio(0); } while (0)
; #define PG8_WAIT_V(n) asm volatile("s_waitcnt vmcnt(" #n ")" ::: "memory")
; #define PG8_WAIT_L(n) asm volatile("s_waitcnt lgkmcnt(" #n ")" ::: "memory")
; #define PG8_BAR __builtin_amdgcn_s_barrier()
; #define PG8_SCHED __builtin_amdgcn_sched_barrier(0)
; template <class Epi, class Sched>
; __device__ __forceinline__ void gemm_phase(LAS unsigned char* lds, const Gemm g, const Sched& S, const Epi& E) {
;     ...
;             const bool last = (t == nt - 2);
;             const char* a1 = cA + (size_t)(t + 1) * kstep;
;             const char* a2 = last ? nA : cA + (size_t)(t + 2) * kstep; const char* b2 = last ? nB : cB + (size_t)(t + 2) * kstep;
;             const char* a3 = a2 + kstep; const char* b3 = b2 + kstep;
;             PG8_LDB(B0, 0, 0); PG8_LDB(B1, 0, 1); PG8_SCHED; PG8_LDA(At, 0, 0); PG8_STAGE(PG8_SA(1, 1), a1 + hstepA, voffA);
;             PG8_WAIT_V(8); PG8_WAIT_L(0); PG8_BAR; PG8_MMA(0, 0, At, B0); PG8_MMA(0, 1, At, B1); PG8_BAR; PG8_SCHED;
;             PG8_LDA(At, 0, 1); PG8_STAGE(PG8_SB(0, 0), b2, voffB); PG8_STAGE(PG8_SB(0, 1), b2 + hstepB, voffB); PG8_STAGE(PG8_SA(0, 0), a2, voffA);
;             PG8_WAIT_V(8); PG8_WAIT_L(0); PG8_BAR; PG8_MMA(1, 0, At, B0); PG8_MMA(1, 1, At, B1); PG8_BAR; PG8_SCHED;
.LBB0_598:
	s_add_i32 vcc_lo, s20, 2
	s_add_u32 s90, s18, 0x80
	s_addc_u32 s21, s19, 0
	s_add_i32 s92, 0, 0x10000
	s_cmp_eq_u32 s43, s20
	s_cselect_b32 s21, s37, s21
	s_cselect_b32 s20, s36, s90
	s_cselect_b32 s91, s71, s87
	s_cselect_b32 s90, s70, s86
	s_add_i32 s93, 0, 0x14000
	s_add_i32 m0, s35, 0xc000
	s_nop 0
	global_load_lds_dwordx4 v138, s[18:19]
	s_add_i32 m0, s35, 0xe000
	s_nop 0
	global_load_lds_dwordx4 v140, s[18:19]
	ds_read_b128 v[142:145], v255
	ds_read_b128 v[150:153], v255 offset:1024
	ds_read_b128 v[154:157], v255 offset:2048
	ds_read_b128 v[158:161], v255 offset:3072
	ds_read_b128 v[162:165], v255 offset:16384
	ds_read_b128 v[166:169], v255 offset:17408
	ds_read_b128 v[170:173], v255 offset:18432
	ds_read_b128 v[190:193], v255 offset:19456
	ds_read_b128 v[194:197], v148
	ds_read_b128 v[198:201], v148 offset:1024
	ds_read_b128 v[202:205], v148 offset:2048
	ds_read_b128 v[206:209], v148 offset:3072
	ds_read_b128 v[218:221], v148 offset:4096
	ds_read_b128 v[222:225], v148 offset:5120
	ds_read_b128 v[226:229], v148 offset:6144
	ds_read_b128 v[230:233], v148 offset:7168
	s_waitcnt vmcnt(8)
	s_waitcnt lgkmcnt(0)
	s_barrier
	s_waitcnt lgkmcnt(0)
	v_mfma_f32_16x16x32_bf16 v[114:117], v[142:145], v[194:197], v[114:117]
	v_mfma_f32_16x16x32_bf16 v[118:121], v[154:157], v[194:197], v[118:121]
	v_mfma_f32_16x16x32_bf16 v[94:97], v[142:145], v[202:205], v[94:97]
	v_mfma_f32_16x16x32_bf16 v[98:101], v[154:157], v[202:205], v[98:101]
	v_mfma_f32_16x16x32_bf16 v[62:65], v[142:145], v[218:221], v[62:65]
	v_mfma_f32_16x16x32_bf16 v[66:69], v[154:157], v[218:221], v[66:69]
	v_mfma_f32_16x16x32_bf16 v[22:25], v[142:145], v[226:229], v[22:25]
	v_mfma_f32_16x16x32_bf16 v[34:37], v[154:157], v[226:229], v[34:37]
	v_mfma_f32_16x16x32_bf16 v[114:117], v[150:153], v[198:201], v[114:117]
	v_mfma_f32_16x16x32_bf16 v[118:121], v[158:161], v[198:201], v[118:121]
	v_mfma_f32_16x16x32_bf16 v[94:97], v[150:153], v[206:209], v[94:97]
	v_mfma_f32_16x16x32_bf16 v[98:101], v[158:161], v[206:209], v[98:101]
	v_mfma_f32_16x16x32_bf16 v[62:65], v[150:153], v[222:225], v[62:65]
	v_mfma_f32_16x16x32_bf16 v[66:69], v[158:161], v[222:225], v[66:69]
	v_mfma_f32_16x16x32_bf16 v[22:25], v[150:153], v[230:233], v[22:25]
	v_mfma_f32_16x16x32_bf16 v[34:37], v[158:161], v[230:233], v[34:37]
	v_mfma_f32_16x16x32_bf16 v[122:125], v[162:165], v[194:197], v[122:125]
	v_mfma_f32_16x16x32_bf16 v[126:129], v[170:173], v[194:197], v[126:129]
	v_mfma_f32_16x16x32_bf16 v[102:105], v[162:165], v[202:205], v[102:105]
	v_mfma_f32_16x16x32_bf16 v[106:109], v[170:173], v[202:205], v[106:109]
	v_mfma_f32_16x16x32_bf16 v[70:73], v[162:165], v[218:221], v[70:73]
	v_mfma_f32_16x16x32_bf16 v[78:81], v[170:173], v[218:221], v[78:81]
	v_mfma_f32_16x16x32_bf16 v[38:41], v[162:165], v[226:229], v[38:41]
	v_mfma_f32_16x16x32_bf16 v[46:49], v[170:173], v[226:229], v[46:49]
	v_mfma_f32_16x16x32_bf16 v[122:125], v[166:169], v[198:201], v[122:125]
	v_mfma_f32_16x16x32_bf16 v[126:129], v[190:193], v[198:201], v[126:129]
	v_mfma_f32_16x16x32_bf16 v[102:105], v[166:169], v[206:209], v[102:105]
	v_mfma_f32_16x16x32_bf16 v[106:109], v[190:193], v[206:209], v[106:109]
	v_mfma_f32_16x16x32_bf16 v[70:73], v[166:169], v[222:225], v[70:73]
	v_mfma_f32_16x16x32_bf16 v[78:81], v[190:193], v[222:225], v[78:81]
	v_mfma_f32_16x16x32_bf16 v[38:41], v[166:169], v[230:233], v[38:41]
	v_mfma_f32_16x16x32_bf16 v[46:49], v[190:193], v[230:233], v[46:49]
	s_barrier
	s_add_i32 s92, s92, s34
	s_add_u32 s98, s90, 0x80
	s_addc_u32 s99, s91, 0
	s_add_u32 s100, s20, 0x80
	s_addc_u32 s101, s21, 0
	s_mov_b32 m0, s92
	ds_read_b128 v[194:197], v148 offset:16384
	ds_read_b128 v[198:201], v148 offset:17408
	ds_read_b128 v[202:205], v148 offset:18432
	ds_read_b128 v[206:209], v148 offset:19456
	ds_read_b128 v[218:221], v148 offset:20480
	ds_read_b128 v[222:225], v148 offset:21504
	ds_read_b128 v[226:229], v148 offset:22528
	ds_read_b128 v[230:233], v148 offset:23552
	global_load_lds_dwordx4 v132, s[90:91]
	s_add_i32 m0, s92, 0x2000
	s_add_i32 s92, s93, s34
	global_load_lds_dwordx4 v136, s[90:91]
	s_add_u32 s90, s90, s29
	s_addc_u32 s91, s91, 0
	s_mov_b32 m0, s92
	s_nop 0
	global_load_lds_dwordx4 v132, s[90:91]
	s_add_i32 m0, s92, 0x2000
	s_nop 0
	global_load_lds_dwordx4 v136, s[90:91]
	s_mov_b32 m0, s35
	s_nop 0
	global_load_lds_dwordx4 v130, s[20:21]
	s_mov_b32 m0, s8
	s_nop 0
	global_load_lds_dwordx4 v134, s[20:21]
	s_waitcnt vmcnt(8)
	s_waitcnt lgkmcnt(0)
	s_barrier
	s_waitcnt lgkmcnt(0)
	v_mfma_f32_16x16x32_bf16 v[14:17], v[142:145], v[194:197], v[14:17]
	v_mfma_f32_16x16x32_bf16 v[26:29], v[154:157], v[194:197], v[26:29]
	v_mfma_f32_16x16x32_bf16 v[74:77], v[142:145], v[202:205], v[74:77]
	v_mfma_f32_16x16x32_bf16 v[82:85], v[154:157], v[202:205], v[82:85]
	v_mfma_f32_16x16x32_bf16 v[42:45], v[142:145], v[218:221], v[42:45]
	v_mfma_f32_16x16x32_bf16 v[50:53], v[154:157], v[218:221], v[50:53]
	v_mfma_f32_16x16x32_bf16 v[2:5], v[142:145], v[226:229], v[2:5]
	v_mfma_f32_16x16x32_bf16 v[6:9], v[154:157], v[226:229], v[6:9]
	v_mfma_f32_16x16x32_bf16 v[14:17], v[150:153], v[198:201], v[14:17]
	v_mfma_f32_16x16x32_bf16 v[26:29], v[158:161], v[198:201], v[26:29]
	v_mfma_f32_16x16x32_bf16 v[74:77], v[150:153], v[206:209], v[74:77]
	v_mfma_f32_16x16x32_bf16 v[82:85], v[158:161], v[206:209], v[82:85]
	v_mfma_f32_16x16x32_bf16 v[42:45], v[150:153], v[222:225], v[42:45]
	v_mfma_f32_16x16x32_bf16 v[50:53], v[158:161], v[222:225], v[50:53]
	v_mfma_f32_16x16x32_bf16 v[2:5], v[150:153], v[230:233], v[2:5]
	v_mfma_f32_16x16x32_bf16 v[6:9], v[158:161], v[230:233], v[6:9]
	v_mfma_f32_16x16x32_bf16 v[30:33], v[162:165], v[194:197], v[30:33]
	v_mfma_f32_16x16x32_bf16 v[110:113], v[170:173], v[194:197], v[110:113]
	v_mfma_f32_16x16x32_bf16 v[86:89], v[162:165], v[202:205], v[86:89]
	v_mfma_f32_16x16x32_bf16 v[90:93], v[170:173], v[202:205], v[90:93]
	v_mfma_f32_16x16x32_bf16 v[54:57], v[162:165], v[218:221], v[54:57]
	v_mfma_f32_16x16x32_bf16 v[58:61], v[170:173], v[218:221], v[58:61]
	v_mfma_f32_16x16x32_bf16 v[10:13], v[162:165], v[226:229], v[10:13]
	v_mfma_f32_16x16x32_bf16 v[18:21], v[170:173], v[226:229], v[18:21]
	v_mfma_f32_16x16x32_bf16 v[30:33], v[166:169], v[198:201], v[30:33]
	v_mfma_f32_16x16x32_bf16 v[110:113], v[190:193], v[198:201], v[110:113]
	v_mfma_f32_16x16x32_bf16 v[86:89], v[166:169], v[206:209], v[86:89]
	v_mfma_f32_16x16x32_bf16 v[90:93], v[190:193], v[206:209], v[90:93]
	v_mfma_f32_16x16x32_bf16 v[54:57], v[166:169], v[222:225], v[54:57]
	v_mfma_f32_16x16x32_bf16 v[58:61], v[190:193], v[222:225], v[58:61]
	v_mfma_f32_16x16x32_bf16 v[10:13], v[166:169], v[230:233], v[10:13]
	v_mfma_f32_16x16x32_bf16 v[18:21], v[190:193], v[230:233], v[18:21]
	s_barrier
; #define PG8_STAGE(bufoff, gbase, voff) do { _Pragma("unroll") for (int _i = 0; _i < 2; ++_i) \
;         __builtin_amdgcn_global_load_lds((const unsigned*)((const char*)(gbase) + (voff)[_i]), (LAS unsigned*)(lds + (bufoff) + ldsw + _i * 8192), 16, 0, 0); } while (0)
; #define PG8_LDA(dst, b, h) do { _Pragma("unroll") for (int m = 0; m < 4; ++m) _Pragma("unroll") for (int k = 0; k < 2; ++k) dst[m][k] = *(const LAS bf16x8*)(lds + PG8_SA(b, h) + aoff + m * 2048 + k * 1024); } while (0)
; #define PG8_LDB(dst, b, h) do { _Pragma("unroll") for (int n = 0; n < 2; ++n) _Pragma("unroll") for (int k = 0; k < 2; ++k) dst[n][k] = *(const LAS bf16x8*)(lds + PG8_SB(b, h) + boff + n * 2048 + k * 1024); } while (0)
; #define PG8_MMA(ai, bj, At, Bt) do { __builtin_amdgcn_s_setprio(1); _Pragma("unroll") for (int m = 0; m < 4; ++m) _Pragma("unroll") for (int n = 0; n < 2; ++n) _Pragma("unroll") for (int k = 0; k < 2; ++k) \
;         acc[ai][bj][m][n] = __builtin_amdgcn_mfma_f32_16x16x32_bf16(Bt[n][k], At[m][k], acc[ai][bj][m][n], 0, 0, 0); __builtin_amdgcn_s_setprio(0); } while (0)
; #define PG8_WAIT_V(n) asm volatile("s_waitcnt vmcnt(" #n ")" ::: "memory")
; #define PG8_WAIT_L(n) asm volatile("s_waitcnt lgkmcnt(" #n ")" ::: "memory")
; #define PG8_BAR __builtin_amdgcn_s_barrier()
; #define PG8_SCHED __builtin_amdgcn_sched_barrier(0)
; template <class Epi, class Sched>
; __device__ __forceinline__ void gemm_phase(LAS unsigned char* lds, const Gemm g, const Sched& S, const Epi& E) {
;     ...
;             PG8_LDB(B0, 1, 0); PG8_LDB(B1, 1, 1); PG8_SCHED; PG8_LDA(At, 1, 0); PG8_STAGE(PG8_SA(0, 1), a2 + hstepA, voffA);
;             PG8_WAIT_V(8); PG8_WAIT_L(0); PG8_BAR; PG8_MMA(0, 0, At, B0); PG8_MMA(0, 1, At, B1); PG8_BAR; PG8_SCHED;
;             PG8_LDA(At, 1, 1); PG8_STAGE(PG8_SB(1, 0), b3, voffB); PG8_STAGE(PG8_SB(1, 1), b3 + hstepB, voffB); PG8_STAGE(PG8_SA(1, 0), a3, voffA);
;             PG8_WAIT_V(8); PG8_WAIT_L(0); PG8_BAR; PG8_MMA(1, 0, At, B0); PG8_MMA(1, 1, At, B1); PG8_BAR; PG8_SCHED;
;         }
	s_add_u32 s20, s20, s80
	s_addc_u32 s21, s21, 0
	s_mov_b32 m0, s9
	s_nop 0
	global_load_lds_dwordx4 v130, s[20:21]
	s_mov_b32 m0, s40
	s_nop 0
	global_load_lds_dwordx4 v134, s[20:21]
	ds_read_b128 v[142:145], v255 offset:32768
	ds_read_b128 v[150:153], v255 offset:33792
	ds_read_b128 v[154:157], v255 offset:34816
	ds_read_b128 v[158:161], v255 offset:35840
	ds_read_b128 v[162:165], v255 offset:49152
	ds_read_b128 v[166:169], v255 offset:50176
	ds_read_b128 v[170:173], v255 offset:51200
	ds_read_b128 v[190:193], v255 offset:52224
	ds_read_b128 v[194:197], v148 offset:32768
	ds_read_b128 v[198:201], v148 offset:33792
	ds_read_b128 v[202:205], v148 offset:34816
	ds_read_b128 v[206:209], v148 offset:35840
	ds_read_b128 v[218:221], v148 offset:36864
	ds_read_b128 v[222:225], v148 offset:37888
	ds_read_b128 v[226:229], v148 offset:38912
	ds_read_b128 v[230:233], v148 offset:39936
	s_waitcnt vmcnt(8)
	s_waitcnt lgkmcnt(0)
	s_barrier
	s_waitcnt lgkmcnt(0)
	v_mfma_f32_16x16x32_bf16 v[114:117], v[142:145], v[194:197], v[114:117]
	v_mfma_f32_16x16x32_bf16 v[118:121], v[154:157], v[194:197], v[118:121]
	v_mfma_f32_16x16x32_bf16 v[94:97], v[142:145], v[202:205], v[94:97]
	v_mfma_f32_16x16x32_bf16 v[98:101], v[154:157], v[202:205], v[98:101]
	v_mfma_f32_16x16x32_bf16 v[62:65], v[142:145], v[218:221], v[62:65]
	v_mfma_f32_16x16x32_bf16 v[66:69], v[154:157], v[218:221], v[66:69]
	v_mfma_f32_16x16x32_bf16 v[22:25], v[142:145], v[226:229], v[22:25]
	v_mfma_f32_16x16x32_bf16 v[34:37], v[154:157], v[226:229], v[34:37]
	v_mfma_f32_16x16x32_bf16 v[114:117], v[150:153], v[198:201], v[114:117]
	v_mfma_f32_16x16x32_bf16 v[118:121], v[158:161], v[198:201], v[118:121]
	v_mfma_f32_16x16x32_bf16 v[94:97], v[150:153], v[206:209], v[94:97]
	v_mfma_f32_16x16x32_bf16 v[98:101], v[158:161], v[206:209], v[98:101]
	v_mfma_f32_16x16x32_bf16 v[62:65], v[150:153], v[222:225], v[62:65]
	v_mfma_f32_16x16x32_bf16 v[66:69], v[158:161], v[222:225], v[66:69]
	v_mfma_f32_16x16x32_bf16 v[22:25], v[150:153], v[230:233], v[22:25]
	v_mfma_f32_16x16x32_bf16 v[34:37], v[158:161], v[230:233], v[34:37]
	v_mfma_f32_16x16x32_bf16 v[122:125], v[162:165], v[194:197], v[122:125]
	v_mfma_f32_16x16x32_bf16 v[126:129], v[170:173], v[194:197], v[126:129]
	v_mfma_f32_16x16x32_bf16 v[102:105], v[162:165], v[202:205], v[102:105]
	v_mfma_f32_16x16x32_bf16 v[106:109], v[170:173], v[202:205], v[106:109]
	v_mfma_f32_16x16x32_bf16 v[70:73], v[162:165], v[218:221], v[70:73]
	v_mfma_f32_16x16x32_bf16 v[78:81], v[170:173], v[218:221], v[78:81]
	v_mfma_f32_16x16x32_bf16 v[38:41], v[162:165], v[226:229], v[38:41]
	v_mfma_f32_16x16x32_bf16 v[46:49], v[170:173], v[226:229], v[46:49]
	v_mfma_f32_16x16x32_bf16 v[122:125], v[166:169], v[198:201], v[122:125]
	v_mfma_f32_16x16x32_bf16 v[126:129], v[190:193], v[198:201], v[126:129]
	v_mfma_f32_16x16x32_bf16 v[102:105], v[166:169], v[206:209], v[102:105]
	v_mfma_f32_16x16x32_bf16 v[106:109], v[190:193], v[206:209], v[106:109]
	v_mfma_f32_16x16x32_bf16 v[70:73], v[166:169], v[222:225], v[70:73]
	v_mfma_f32_16x16x32_bf16 v[78:81], v[190:193], v[222:225], v[78:81]
	v_mfma_f32_16x16x32_bf16 v[38:41], v[166:169], v[230:233], v[38:41]
	v_mfma_f32_16x16x32_bf16 v[46:49], v[190:193], v[230:233], v[46:49]
	s_barrier
	s_add_i32 s20, s34, 0x18000
	s_mov_b32 m0, s20
	ds_read_b128 v[194:197], v148 offset:49152
	ds_read_b128 v[198:201], v148 offset:50176
	ds_read_b128 v[202:205], v148 offset:51200
	ds_read_b128 v[206:209], v148 offset:52224
	ds_read_b128 v[218:221], v148 offset:53248
	ds_read_b128 v[222:225], v148 offset:54272
	ds_read_b128 v[226:229], v148 offset:55296
	ds_read_b128 v[230:233], v148 offset:56320
	global_load_lds_dwordx4 v132, s[98:99]
	s_add_i32 m0, s20, 0x2000
	s_add_i32 s20, s34, 0x1c000
	global_load_lds_dwordx4 v136, s[98:99]
	s_add_u32 s98, s98, s29
	s_addc_u32 s99, s99, 0
	s_mov_b32 m0, s20
	s_nop 0
	global_load_lds_dwordx4 v132, s[98:99]
	s_add_i32 m0, s20, 0x2000
	s_nop 0
	global_load_lds_dwordx4 v136, s[98:99]
	s_mov_b32 m0, s41
	s_nop 0
	global_load_lds_dwordx4 v130, s[100:101]
	s_mov_b32 m0, s42
	s_nop 0
	global_load_lds_dwordx4 v134, s[100:101]
	s_waitcnt vmcnt(8)
	s_waitcnt lgkmcnt(0)
	s_barrier
	s_waitcnt lgkmcnt(0)
	v_mfma_f32_16x16x32_bf16 v[14:17], v[142:145], v[194:197], v[14:17]
	v_mfma_f32_16x16x32_bf16 v[26:29], v[154:157], v[194:197], v[26:29]
	v_mfma_f32_16x16x32_bf16 v[74:77], v[142:145], v[202:205], v[74:77]
	v_mfma_f32_16x16x32_bf16 v[82:85], v[154:157], v[202:205], v[82:85]
	v_mfma_f32_16x16x32_bf16 v[42:45], v[142:145], v[218:221], v[42:45]
	v_mfma_f32_16x16x32_bf16 v[50:53], v[154:157], v[218:221], v[50:53]
	v_mfma_f32_16x16x32_bf16 v[2:5], v[142:145], v[226:229], v[2:5]
	v_mfma_f32_16x16x32_bf16 v[6:9], v[154:157], v[226:229], v[6:9]
	v_mfma_f32_16x16x32_bf16 v[14:17], v[150:153], v[198:201], v[14:17]
	v_mfma_f32_16x16x32_bf16 v[26:29], v[158:161], v[198:201], v[26:29]
	v_mfma_f32_16x16x32_bf16 v[74:77], v[150:153], v[206:209], v[74:77]
	v_mfma_f32_16x16x32_bf16 v[82:85], v[158:161], v[206:209], v[82:85]
	v_mfma_f32_16x16x32_bf16 v[42:45], v[150:153], v[222:225], v[42:45]
	v_mfma_f32_16x16x32_bf16 v[50:53], v[158:161], v[222:225], v[50:53]
	v_mfma_f32_16x16x32_bf16 v[2:5], v[150:153], v[230:233], v[2:5]
	v_mfma_f32_16x16x32_bf16 v[6:9], v[158:161], v[230:233], v[6:9]
	v_mfma_f32_16x16x32_bf16 v[30:33], v[162:165], v[194:197], v[30:33]
	v_mfma_f32_16x16x32_bf16 v[110:113], v[170:173], v[194:197], v[110:113]
	v_mfma_f32_16x16x32_bf16 v[86:89], v[162:165], v[202:205], v[86:89]
	v_mfma_f32_16x16x32_bf16 v[90:93], v[170:173], v[202:205], v[90:93]
	v_mfma_f32_16x16x32_bf16 v[54:57], v[162:165], v[218:221], v[54:57]
	v_mfma_f32_16x16x32_bf16 v[58:61], v[170:173], v[218:221], v[58:61]
	v_mfma_f32_16x16x32_bf16 v[10:13], v[162:165], v[226:229], v[10:13]
	v_mfma_f32_16x16x32_bf16 v[18:21], v[170:173], v[226:229], v[18:21]
	v_mfma_f32_16x16x32_bf16 v[30:33], v[166:169], v[198:201], v[30:33]
	v_mfma_f32_16x16x32_bf16 v[110:113], v[190:193], v[198:201], v[110:113]
	v_mfma_f32_16x16x32_bf16 v[86:89], v[166:169], v[206:209], v[86:89]
	v_mfma_f32_16x16x32_bf16 v[90:93], v[190:193], v[206:209], v[90:93]
	v_mfma_f32_16x16x32_bf16 v[54:57], v[166:169], v[222:225], v[54:57]
	v_mfma_f32_16x16x32_bf16 v[58:61], v[190:193], v[222:225], v[58:61]
	v_mfma_f32_16x16x32_bf16 v[10:13], v[166:169], v[230:233], v[10:13]
	v_mfma_f32_16x16x32_bf16 v[18:21], v[190:193], v[230:233], v[18:21]
	s_barrier
	s_add_u32 s18, s18, 0x100
	s_addc_u32 s19, s19, 0
	s_add_u32 s86, s86, 0x100
	s_addc_u32 s87, s87, 0
	s_cmp_ge_u32 vcc_lo, s48
	s_mov_b32 s20, vcc_lo
	s_cbranch_scc0 .LBB0_598
	s_and_b64 vcc, exec, s[84:85]
	s_cbranch_vccz .LBB0_601
	s_barrier

; #define PG8_STAGE(bufoff, gbase, voff) do { _Pragma("unroll") for (int _i = 0; _i < 2; ++_i) \
;         __builtin_amdgcn_global_load_lds((const unsigned*)((const char*)(gbase) + (voff)[_i]), (LAS unsigned*)(lds + (bufoff) + ldsw + _i * 8192), 16, 0, 0); } while (0)
; #define PG8_LDA(dst, b, h) do { _Pragma("unroll") for (int m = 0; m < 4; ++m) _Pragma("unroll") for (int k = 0; k < 2; ++k) dst[m][k] = *(const LAS bf16x8*)(lds + PG8_SA(b, h) + aoff + m * 2048 + k * 1024); } while (0)
; #define PG8_LDB(dst, b, h) do { _Pragma("unroll") for (int n = 0; n < 2; ++n) _Pragma("unroll") for (int k = 0; k < 2; ++k) dst[n][k] = *(const LAS bf16x8*)(lds + PG8_SB(b, h) + boff + n * 2048 + k * 1024); } while (0)
; #define PG8_MMA(ai, bj, At, Bt) do { __builtin_amdgcn_s_setprio(1); _Pragma("unroll") for (int m = 0; m < 4; ++m) _Pragma("unroll") for (int n = 0; n < 2; ++n) _Pragma("unroll") for (int k = 0; k < 2; ++k) \
;         acc[ai][bj][m][n] = __builtin_amdgcn_mfma_f32_16x16x32_bf16(Bt[n][k], At[m][k], acc[ai][bj][m][n], 0, 0, 0); __builtin_amdgcn_s_setprio(0); } while (0)
; #define PG8_WAIT_V(n) asm volatile("s_waitcnt vmcnt(" #n ")" ::: "memory")
; #define PG8_WAIT_L(n) asm volatile("s_waitcnt lgkmcnt(" #n ")" ::: "memory")
; #define PG8_BAR __builtin_amdgcn_s_barrier()
; #define PG8_SCHED __builtin_amdgcn_sched_barrier(0)
; template <class Epi, class Sched>
; __device__ __forceinline__ void gemm_phase(LAS unsigned char* lds, const Gemm g, const Sched& S, const Epi& E) {
;     ...
;             const bool last = (t == nt - 2);
;             const char* a1 = cA + (size_t)(t + 1) * kstep;
;             const char* a2 = last ? nA : cA + (size_t)(t + 2) * kstep; const char* b2 = last ? nB : cB + (size_t)(t + 2) * kstep;
;             const char* a3 = a2 + kstep; const char* b3 = b2 + kstep;
;             PG8_LDB(B0, 0, 0); PG8_LDB(B1, 0, 1); PG8_SCHED; PG8_LDA(At, 0, 0); PG8_STAGE(PG8_SA(1, 1), a1 + hstepA, voffA);
;             PG8_WAIT_V(8); PG8_WAIT_L(0); PG8_BAR; PG8_MMA(0, 0, At, B0); PG8_MMA(0, 1, At, B1); PG8_BAR; PG8_SCHED;
;             PG8_LDA(At, 0, 1); PG8_STAGE(PG8_SB(0, 0), b2, voffB); PG8_STAGE(PG8_SB(0, 1), b2 + hstepB, voffB); PG8_STAGE(PG8_SA(0, 0), a2, voffA);
;             PG8_WAIT_V(8); PG8_WAIT_L(0); PG8_BAR; PG8_MMA(1, 0, At, B0); PG8_MMA(1, 1, At, B1); PG8_BAR; PG8_SCHED;
.LBB0_640:
	s_add_i32 s87, s20, 2
	s_add_u32 s88, s18, 0x80
	s_addc_u32 s21, s19, 0
	s_add_i32 s90, 0, 0x10000
	s_cmp_eq_u32 s43, s20
	s_cselect_b32 s21, s69, s21
	s_cselect_b32 s20, s68, s88
	s_cselect_b32 s89, s81, s83
	s_cselect_b32 s88, s80, s82
	s_add_i32 s91, 0, 0x14000
	s_add_i32 m0, s30, 0xc000
	s_nop 0
	global_load_lds_dwordx4 v138, s[18:19]
	s_add_i32 m0, s30, 0xe000
	s_nop 0
	global_load_lds_dwordx4 v140, s[18:19]
	ds_read_b128 v[146:149], v255
	ds_read_b128 v[150:153], v255 offset:1024
	ds_read_b128 v[154:157], v255 offset:2048
	ds_read_b128 v[158:161], v255 offset:3072
	ds_read_b128 v[162:165], v255 offset:16384
	ds_read_b128 v[166:169], v255 offset:17408
	ds_read_b128 v[170:173], v255 offset:18432
	ds_read_b128 v[190:193], v255 offset:19456
	ds_read_b128 v[194:197], v144
	ds_read_b128 v[198:201], v144 offset:1024
	ds_read_b128 v[202:205], v144 offset:2048
	ds_read_b128 v[206:209], v144 offset:3072
	ds_read_b128 v[218:221], v144 offset:4096
	ds_read_b128 v[222:225], v144 offset:5120
	ds_read_b128 v[226:229], v144 offset:6144
	ds_read_b128 v[230:233], v144 offset:7168
	s_waitcnt vmcnt(8)
	s_waitcnt lgkmcnt(0)
	s_barrier
	s_waitcnt lgkmcnt(0)
	v_mfma_f32_16x16x32_bf16 v[2:5], v[146:149], v[194:197], v[2:5]
	v_mfma_f32_16x16x32_bf16 v[6:9], v[154:157], v[194:197], v[6:9]
	v_mfma_f32_16x16x32_bf16 v[10:13], v[146:149], v[202:205], v[10:13]
	v_mfma_f32_16x16x32_bf16 v[14:17], v[154:157], v[202:205], v[14:17]
	v_mfma_f32_16x16x32_bf16 v[26:29], v[146:149], v[218:221], v[26:29]
	v_mfma_f32_16x16x32_bf16 v[30:33], v[154:157], v[218:221], v[30:33]
	v_mfma_f32_16x16x32_bf16 v[42:45], v[146:149], v[226:229], v[42:45]
	v_mfma_f32_16x16x32_bf16 v[46:49], v[154:157], v[226:229], v[46:49]
	v_mfma_f32_16x16x32_bf16 v[2:5], v[150:153], v[198:201], v[2:5]
	v_mfma_f32_16x16x32_bf16 v[6:9], v[158:161], v[198:201], v[6:9]
	v_mfma_f32_16x16x32_bf16 v[10:13], v[150:153], v[206:209], v[10:13]
	v_mfma_f32_16x16x32_bf16 v[14:17], v[158:161], v[206:209], v[14:17]
	v_mfma_f32_16x16x32_bf16 v[26:29], v[150:153], v[222:225], v[26:29]
	v_mfma_f32_16x16x32_bf16 v[30:33], v[158:161], v[222:225], v[30:33]
	v_mfma_f32_16x16x32_bf16 v[42:45], v[150:153], v[230:233], v[42:45]
	v_mfma_f32_16x16x32_bf16 v[46:49], v[158:161], v[230:233], v[46:49]
	v_mfma_f32_16x16x32_bf16 v[18:21], v[162:165], v[194:197], v[18:21]
	v_mfma_f32_16x16x32_bf16 v[22:25], v[170:173], v[194:197], v[22:25]
	v_mfma_f32_16x16x32_bf16 v[34:37], v[162:165], v[202:205], v[34:37]
	v_mfma_f32_16x16x32_bf16 v[38:41], v[170:173], v[202:205], v[38:41]
	v_mfma_f32_16x16x32_bf16 v[50:53], v[162:165], v[218:221], v[50:53]
	v_mfma_f32_16x16x32_bf16 v[54:57], v[170:173], v[218:221], v[54:57]
	v_mfma_f32_16x16x32_bf16 v[58:61], v[162:165], v[226:229], v[58:61]
	v_mfma_f32_16x16x32_bf16 v[66:69], v[170:173], v[226:229], v[66:69]
	v_mfma_f32_16x16x32_bf16 v[18:21], v[166:169], v[198:201], v[18:21]
	v_mfma_f32_16x16x32_bf16 v[22:25], v[190:193], v[198:201], v[22:25]
	v_mfma_f32_16x16x32_bf16 v[34:37], v[166:169], v[206:209], v[34:37]
	v_mfma_f32_16x16x32_bf16 v[38:41], v[190:193], v[206:209], v[38:41]
	v_mfma_f32_16x16x32_bf16 v[50:53], v[166:169], v[222:225], v[50:53]
	v_mfma_f32_16x16x32_bf16 v[54:57], v[190:193], v[222:225], v[54:57]
	v_mfma_f32_16x16x32_bf16 v[58:61], v[166:169], v[230:233], v[58:61]
	v_mfma_f32_16x16x32_bf16 v[66:69], v[190:193], v[230:233], v[66:69]
	s_barrier
	s_add_i32 s90, s90, s29
	s_add_u32 s98, s88, 0x80
	s_addc_u32 s99, s89, 0
	s_add_u32 s100, s20, 0x80
	s_addc_u32 s101, s21, 0
	s_mov_b32 m0, s90
	ds_read_b128 v[194:197], v144 offset:16384
	ds_read_b128 v[198:201], v144 offset:17408
	ds_read_b128 v[202:205], v144 offset:18432
	ds_read_b128 v[206:209], v144 offset:19456
	ds_read_b128 v[218:221], v144 offset:20480
	ds_read_b128 v[222:225], v144 offset:21504
	ds_read_b128 v[226:229], v144 offset:22528
	ds_read_b128 v[230:233], v144 offset:23552
	global_load_lds_dwordx4 v132, s[88:89]
	s_add_i32 m0, s90, 0x2000
	s_add_i32 s90, s91, s29
	global_load_lds_dwordx4 v136, s[88:89]
	s_add_u32 s88, s88, s8
	s_addc_u32 s89, s89, 0
	s_mov_b32 m0, s90
	s_nop 0
	global_load_lds_dwordx4 v132, s[88:89]
	s_add_i32 m0, s90, 0x2000
	s_nop 0
	global_load_lds_dwordx4 v136, s[88:89]
	s_mov_b32 m0, s30
	s_nop 0
	global_load_lds_dwordx4 v130, s[20:21]
	s_mov_b32 m0, s31
	s_nop 0
	global_load_lds_dwordx4 v134, s[20:21]
	s_waitcnt vmcnt(8)
	s_waitcnt lgkmcnt(0)
	s_barrier
	s_waitcnt lgkmcnt(0)
	v_mfma_f32_16x16x32_bf16 v[62:65], v[146:149], v[194:197], v[62:65]
	v_mfma_f32_16x16x32_bf16 v[70:73], v[154:157], v[194:197], v[70:73]
	v_mfma_f32_16x16x32_bf16 v[78:81], v[146:149], v[202:205], v[78:81]
	v_mfma_f32_16x16x32_bf16 v[82:85], v[154:157], v[202:205], v[82:85]
	v_mfma_f32_16x16x32_bf16 v[90:93], v[146:149], v[218:221], v[90:93]
	v_mfma_f32_16x16x32_bf16 v[94:97], v[154:157], v[218:221], v[94:97]
	v_mfma_f32_16x16x32_bf16 v[106:109], v[146:149], v[226:229], v[106:109]
	v_mfma_f32_16x16x32_bf16 v[110:113], v[154:157], v[226:229], v[110:113]
	v_mfma_f32_16x16x32_bf16 v[62:65], v[150:153], v[198:201], v[62:65]
	v_mfma_f32_16x16x32_bf16 v[70:73], v[158:161], v[198:201], v[70:73]
	v_mfma_f32_16x16x32_bf16 v[78:81], v[150:153], v[206:209], v[78:81]
	v_mfma_f32_16x16x32_bf16 v[82:85], v[158:161], v[206:209], v[82:85]
	v_mfma_f32_16x16x32_bf16 v[90:93], v[150:153], v[222:225], v[90:93]
	v_mfma_f32_16x16x32_bf16 v[94:97], v[158:161], v[222:225], v[94:97]
	v_mfma_f32_16x16x32_bf16 v[106:109], v[150:153], v[230:233], v[106:109]
	v_mfma_f32_16x16x32_bf16 v[110:113], v[158:161], v[230:233], v[110:113]
	v_mfma_f32_16x16x32_bf16 v[74:77], v[162:165], v[194:197], v[74:77]
	v_mfma_f32_16x16x32_bf16 v[86:89], v[170:173], v[194:197], v[86:89]
	v_mfma_f32_16x16x32_bf16 v[98:101], v[162:165], v[202:205], v[98:101]
	v_mfma_f32_16x16x32_bf16 v[102:105], v[170:173], v[202:205], v[102:105]
	v_mfma_f32_16x16x32_bf16 v[114:117], v[162:165], v[218:221], v[114:117]
	v_mfma_f32_16x16x32_bf16 v[118:121], v[170:173], v[218:221], v[118:121]
	v_mfma_f32_16x16x32_bf16 v[122:125], v[162:165], v[226:229], v[122:125]
	v_mfma_f32_16x16x32_bf16 v[126:129], v[170:173], v[226:229], v[126:129]
	v_mfma_f32_16x16x32_bf16 v[74:77], v[166:169], v[198:201], v[74:77]
	v_mfma_f32_16x16x32_bf16 v[86:89], v[190:193], v[198:201], v[86:89]
	v_mfma_f32_16x16x32_bf16 v[98:101], v[166:169], v[206:209], v[98:101]
	v_mfma_f32_16x16x32_bf16 v[102:105], v[190:193], v[206:209], v[102:105]
	v_mfma_f32_16x16x32_bf16 v[114:117], v[166:169], v[222:225], v[114:117]
	v_mfma_f32_16x16x32_bf16 v[118:121], v[190:193], v[222:225], v[118:121]
	v_mfma_f32_16x16x32_bf16 v[122:125], v[166:169], v[230:233], v[122:125]
	v_mfma_f32_16x16x32_bf16 v[126:129], v[190:193], v[230:233], v[126:129]
	s_barrier
; #define PG8_STAGE(bufoff, gbase, voff) do { _Pragma("unroll") for (int _i = 0; _i < 2; ++_i) \
;         __builtin_amdgcn_global_load_lds((const unsigned*)((const char*)(gbase) + (voff)[_i]), (LAS unsigned*)(lds + (bufoff) + ldsw + _i * 8192), 16, 0, 0); } while (0)
; #define PG8_LDA(dst, b, h) do { _Pragma("unroll") for (int m = 0; m < 4; ++m) _Pragma("unroll") for (int k = 0; k < 2; ++k) dst[m][k] = *(const LAS bf16x8*)(lds + PG8_SA(b, h) + aoff + m * 2048 + k * 1024); } while (0)
; #define PG8_LDB(dst, b, h) do { _Pragma("unroll") for (int n = 0; n < 2; ++n) _Pragma("unroll") for (int k = 0; k < 2; ++k) dst[n][k] = *(const LAS bf16x8*)(lds + PG8_SB(b, h) + boff + n * 2048 + k * 1024); } while (0)
; #define PG8_MMA(ai, bj, At, Bt) do { __builtin_amdgcn_s_setprio(1); _Pragma("unroll") for (int m = 0; m < 4; ++m) _Pragma("unroll") for (int n = 0; n < 2; ++n) _Pragma("unroll") for (int k = 0; k < 2; ++k) \
;         acc[ai][bj][m][n] = __builtin_amdgcn_mfma_f32_16x16x32_bf16(Bt[n][k], At[m][k], acc[ai][bj][m][n], 0, 0, 0); __builtin_amdgcn_s_setprio(0); } while (0)
; #define PG8_WAIT_V(n) asm volatile("s_waitcnt vmcnt(" #n ")" ::: "memory")
; #define PG8_WAIT_L(n) asm volatile("s_waitcnt lgkmcnt(" #n ")" ::: "memory")
; #define PG8_BAR __builtin_amdgcn_s_barrier()
; #define PG8_SCHED __builtin_amdgcn_sched_barrier(0)
; template <class Epi, class Sched>
; __device__ __forceinline__ void gemm_phase(LAS unsigned char* lds, const Gemm g, const Sched& S, const Epi& E) {
;     ...
;             PG8_LDB(B0, 1, 0); PG8_LDB(B1, 1, 1); PG8_SCHED; PG8_LDA(At, 1, 0); PG8_STAGE(PG8_SA(0, 1), a2 + hstepA, voffA);
;             PG8_WAIT_V(8); PG8_WAIT_L(0); PG8_BAR; PG8_MMA(0, 0, At, B0); PG8_MMA(0, 1, At, B1); PG8_BAR; PG8_SCHED;
;             PG8_LDA(At, 1, 1); PG8_STAGE(PG8_SB(1, 0), b3, voffB); PG8_STAGE(PG8_SB(1, 1), b3 + hstepB, voffB); PG8_STAGE(PG8_SA(1, 0), a3, voffA);
;             PG8_WAIT_V(8); PG8_WAIT_L(0); PG8_BAR; PG8_MMA(1, 0, At, B0); PG8_MMA(1, 1, At, B1); PG8_BAR; PG8_SCHED;
;         }
	s_add_u32 s20, s20, s54
	s_addc_u32 s21, s21, 0
	s_mov_b32 m0, s34
	s_nop 0
	global_load_lds_dwordx4 v130, s[20:21]
	s_mov_b32 m0, s35
	s_nop 0
	global_load_lds_dwordx4 v134, s[20:21]
	ds_read_b128 v[146:149], v255 offset:32768
	ds_read_b128 v[150:153], v255 offset:33792
	ds_read_b128 v[154:157], v255 offset:34816
	ds_read_b128 v[158:161], v255 offset:35840
	ds_read_b128 v[162:165], v255 offset:49152
	ds_read_b128 v[166:169], v255 offset:50176
	ds_read_b128 v[170:173], v255 offset:51200
	ds_read_b128 v[190:193], v255 offset:52224
	ds_read_b128 v[194:197], v144 offset:32768
	ds_read_b128 v[198:201], v144 offset:33792
	ds_read_b128 v[202:205], v144 offset:34816
	ds_read_b128 v[206:209], v144 offset:35840
	ds_read_b128 v[218:221], v144 offset:36864
	ds_read_b128 v[222:225], v144 offset:37888
	ds_read_b128 v[226:229], v144 offset:38912
	ds_read_b128 v[230:233], v144 offset:39936
	s_waitcnt vmcnt(8)
	s_waitcnt lgkmcnt(0)
	s_barrier
	s_waitcnt lgkmcnt(0)
	v_mfma_f32_16x16x32_bf16 v[2:5], v[146:149], v[194:197], v[2:5]
	v_mfma_f32_16x16x32_bf16 v[6:9], v[154:157], v[194:197], v[6:9]
	v_mfma_f32_16x16x32_bf16 v[10:13], v[146:149], v[202:205], v[10:13]
	v_mfma_f32_16x16x32_bf16 v[14:17], v[154:157], v[202:205], v[14:17]
	v_mfma_f32_16x16x32_bf16 v[26:29], v[146:149], v[218:221], v[26:29]
	v_mfma_f32_16x16x32_bf16 v[30:33], v[154:157], v[218:221], v[30:33]
	v_mfma_f32_16x16x32_bf16 v[42:45], v[146:149], v[226:229], v[42:45]
	v_mfma_f32_16x16x32_bf16 v[46:49], v[154:157], v[226:229], v[46:49]
	v_mfma_f32_16x16x32_bf16 v[2:5], v[150:153], v[198:201], v[2:5]
	v_mfma_f32_16x16x32_bf16 v[6:9], v[158:161], v[198:201], v[6:9]
	v_mfma_f32_16x16x32_bf16 v[10:13], v[150:153], v[206:209], v[10:13]
	v_mfma_f32_16x16x32_bf16 v[14:17], v[158:161], v[206:209], v[14:17]
	v_mfma_f32_16x16x32_bf16 v[26:29], v[150:153], v[222:225], v[26:29]
	v_mfma_f32_16x16x32_bf16 v[30:33], v[158:161], v[222:225], v[30:33]
	v_mfma_f32_16x16x32_bf16 v[42:45], v[150:153], v[230:233], v[42:45]
	v_mfma_f32_16x16x32_bf16 v[46:49], v[158:161], v[230:233], v[46:49]
	v_mfma_f32_16x16x32_bf16 v[18:21], v[162:165], v[194:197], v[18:21]
	v_mfma_f32_16x16x32_bf16 v[22:25], v[170:173], v[194:197], v[22:25]
	v_mfma_f32_16x16x32_bf16 v[34:37], v[162:165], v[202:205], v[34:37]
	v_mfma_f32_16x16x32_bf16 v[38:41], v[170:173], v[202:205], v[38:41]
	v_mfma_f32_16x16x32_bf16 v[50:53], v[162:165], v[218:221], v[50:53]
	v_mfma_f32_16x16x32_bf16 v[54:57], v[170:173], v[218:221], v[54:57]
	v_mfma_f32_16x16x32_bf16 v[58:61], v[162:165], v[226:229], v[58:61]
	v_mfma_f32_16x16x32_bf16 v[66:69], v[170:173], v[226:229], v[66:69]
	v_mfma_f32_16x16x32_bf16 v[18:21], v[166:169], v[198:201], v[18:21]
	v_mfma_f32_16x16x32_bf16 v[22:25], v[190:193], v[198:201], v[22:25]
	v_mfma_f32_16x16x32_bf16 v[34:37], v[166:169], v[206:209], v[34:37]
	v_mfma_f32_16x16x32_bf16 v[38:41], v[190:193], v[206:209], v[38:41]
	v_mfma_f32_16x16x32_bf16 v[50:53], v[166:169], v[222:225], v[50:53]
	v_mfma_f32_16x16x32_bf16 v[54:57], v[190:193], v[222:225], v[54:57]
	v_mfma_f32_16x16x32_bf16 v[58:61], v[166:169], v[230:233], v[58:61]
	v_mfma_f32_16x16x32_bf16 v[66:69], v[190:193], v[230:233], v[66:69]
	s_barrier
	s_add_i32 s20, s29, 0x18000
	s_mov_b32 m0, s20
	ds_read_b128 v[194:197], v144 offset:49152
	ds_read_b128 v[198:201], v144 offset:50176
	ds_read_b128 v[202:205], v144 offset:51200
	ds_read_b128 v[206:209], v144 offset:52224
	ds_read_b128 v[218:221], v144 offset:53248
	ds_read_b128 v[222:225], v144 offset:54272
	ds_read_b128 v[226:229], v144 offset:55296
	ds_read_b128 v[230:233], v144 offset:56320
	global_load_lds_dwordx4 v132, s[98:99]
	s_add_i32 m0, s20, 0x2000
	s_add_i32 s20, s29, 0x1c000
	global_load_lds_dwordx4 v136, s[98:99]
	s_add_u32 s98, s98, s8
	s_addc_u32 s99, s99, 0
	s_mov_b32 m0, s20
	s_nop 0
	global_load_lds_dwordx4 v132, s[98:99]
	s_add_i32 m0, s20, 0x2000
	s_nop 0
	global_load_lds_dwordx4 v136, s[98:99]
	s_mov_b32 m0, s40
	s_nop 0
	global_load_lds_dwordx4 v130, s[100:101]
	s_mov_b32 m0, s41
	s_nop 0
	global_load_lds_dwordx4 v134, s[100:101]
	s_waitcnt vmcnt(8)
	s_waitcnt lgkmcnt(0)
	s_barrier
	s_waitcnt lgkmcnt(0)
	v_mfma_f32_16x16x32_bf16 v[62:65], v[146:149], v[194:197], v[62:65]
	v_mfma_f32_16x16x32_bf16 v[70:73], v[154:157], v[194:197], v[70:73]
	v_mfma_f32_16x16x32_bf16 v[78:81], v[146:149], v[202:205], v[78:81]
	v_mfma_f32_16x16x32_bf16 v[82:85], v[154:157], v[202:205], v[82:85]
	v_mfma_f32_16x16x32_bf16 v[90:93], v[146:149], v[218:221], v[90:93]
	v_mfma_f32_16x16x32_bf16 v[94:97], v[154:157], v[218:221], v[94:97]
	v_mfma_f32_16x16x32_bf16 v[106:109], v[146:149], v[226:229], v[106:109]
	v_mfma_f32_16x16x32_bf16 v[110:113], v[154:157], v[226:229], v[110:113]
	v_mfma_f32_16x16x32_bf16 v[62:65], v[150:153], v[198:201], v[62:65]
	v_mfma_f32_16x16x32_bf16 v[70:73], v[158:161], v[198:201], v[70:73]
	v_mfma_f32_16x16x32_bf16 v[78:81], v[150:153], v[206:209], v[78:81]
	v_mfma_f32_16x16x32_bf16 v[82:85], v[158:161], v[206:209], v[82:85]
	v_mfma_f32_16x16x32_bf16 v[90:93], v[150:153], v[222:225], v[90:93]
	v_mfma_f32_16x16x32_bf16 v[94:97], v[158:161], v[222:225], v[94:97]
	v_mfma_f32_16x16x32_bf16 v[106:109], v[150:153], v[230:233], v[106:109]
	v_mfma_f32_16x16x32_bf16 v[110:113], v[158:161], v[230:233], v[110:113]
	v_mfma_f32_16x16x32_bf16 v[74:77], v[162:165], v[194:197], v[74:77]
	v_mfma_f32_16x16x32_bf16 v[86:89], v[170:173], v[194:197], v[86:89]
	v_mfma_f32_16x16x32_bf16 v[98:101], v[162:165], v[202:205], v[98:101]
	v_mfma_f32_16x16x32_bf16 v[102:105], v[170:173], v[202:205], v[102:105]
	v_mfma_f32_16x16x32_bf16 v[114:117], v[162:165], v[218:221], v[114:117]
	v_mfma_f32_16x16x32_bf16 v[118:121], v[170:173], v[218:221], v[118:121]
	v_mfma_f32_16x16x32_bf16 v[122:125], v[162:165], v[226:229], v[122:125]
	v_mfma_f32_16x16x32_bf16 v[126:129], v[170:173], v[226:229], v[126:129]
	v_mfma_f32_16x16x32_bf16 v[74:77], v[166:169], v[198:201], v[74:77]
	v_mfma_f32_16x16x32_bf16 v[86:89], v[190:193], v[198:201], v[86:89]
	v_mfma_f32_16x16x32_bf16 v[98:101], v[166:169], v[206:209], v[98:101]
	v_mfma_f32_16x16x32_bf16 v[102:105], v[190:193], v[206:209], v[102:105]
	v_mfma_f32_16x16x32_bf16 v[114:117], v[166:169], v[222:225], v[114:117]
	v_mfma_f32_16x16x32_bf16 v[118:121], v[190:193], v[222:225], v[118:121]
	v_mfma_f32_16x16x32_bf16 v[122:125], v[166:169], v[230:233], v[122:125]
	v_mfma_f32_16x16x32_bf16 v[126:129], v[190:193], v[230:233], v[126:129]
	s_barrier
	s_add_u32 s18, s18, 0x100
	s_addc_u32 s19, s19, 0
	s_add_u32 s82, s82, 0x100
	s_addc_u32 s83, s83, 0
	s_cmp_ge_u32 s87, s42
	s_mov_b32 s20, s87
	s_cbranch_scc0 .LBB0_640
	s_and_b64 vcc, exec, s[70:71]
	s_cbranch_vccz .LBB0_643
	s_barrier
